# GEMM K-loops: removed per-phase s_setprio toggles
# speedup vs baseline: 1.0238x; 1.0124x over previous
.LBB0_297:
	s_add_u32 s22, s20, 0xfffc0080
	s_addc_u32 s23, s21, -1
	s_add_i32 s49, 0, 0x10000
	v_add_u32_e32 v145, s49, v142
	ds_read_b128 v[146:149], v145
	ds_read_b128 v[150:153], v145 offset:1024
	ds_read_b128 v[154:157], v145 offset:2048
	ds_read_b128 v[158:161], v145 offset:3072
	s_cmp_eq_u32 s48, 12
	s_cselect_b32 s25, s9, s23
	s_cselect_b32 s24, s44, s22
	s_cselect_b32 s23, s7, s47
	s_cselect_b32 s22, s45, s46
	s_add_i32 m0, s19, 0xc000
	ds_read_b128 v[162:165], v144
	ds_read_b128 v[166:169], v144 offset:1024
	ds_read_b128 v[170:173], v144 offset:2048
	ds_read_b128 v[174:177], v144 offset:3072
	ds_read_b128 v[190:193], v144 offset:4096
	ds_read_b128 v[194:197], v144 offset:5120
	ds_read_b128 v[198:201], v144 offset:6144
	ds_read_b128 v[202:205], v144 offset:7168
	global_load_lds_dwordx4 v138, s[20:21]
	s_add_i32 m0, s19, 0xe000
	s_nop 0
	global_load_lds_dwordx4 v140, s[20:21]
	s_waitcnt lgkmcnt(8)
	s_barrier
	s_waitcnt lgkmcnt(0)
	s_waitcnt lgkmcnt(0)
	v_mfma_f32_16x16x32_bf16 v[126:129], v[146:149], v[162:165], v[126:129]
	v_mfma_f32_16x16x32_bf16 v[118:121], v[154:157], v[162:165], v[118:121]
	v_mfma_f32_16x16x32_bf16 v[110:113], v[146:149], v[170:173], v[110:113]
	v_mfma_f32_16x16x32_bf16 v[102:105], v[154:157], v[170:173], v[102:105]
	v_mfma_f32_16x16x32_bf16 v[94:97], v[146:149], v[190:193], v[94:97]
	v_mfma_f32_16x16x32_bf16 v[86:89], v[154:157], v[190:193], v[86:89]
	v_mfma_f32_16x16x32_bf16 v[78:81], v[146:149], v[198:201], v[78:81]
	v_mfma_f32_16x16x32_bf16 v[70:73], v[154:157], v[198:201], v[70:73]
	v_mfma_f32_16x16x32_bf16 v[126:129], v[150:153], v[166:169], v[126:129]
	v_mfma_f32_16x16x32_bf16 v[118:121], v[158:161], v[166:169], v[118:121]
	v_mfma_f32_16x16x32_bf16 v[110:113], v[150:153], v[174:177], v[110:113]
	v_mfma_f32_16x16x32_bf16 v[102:105], v[158:161], v[174:177], v[102:105]
	v_mfma_f32_16x16x32_bf16 v[94:97], v[150:153], v[194:197], v[94:97]
	v_mfma_f32_16x16x32_bf16 v[86:89], v[158:161], v[194:197], v[86:89]
	v_mfma_f32_16x16x32_bf16 v[78:81], v[150:153], v[202:205], v[78:81]
	v_mfma_f32_16x16x32_bf16 v[70:73], v[158:161], v[202:205], v[70:73]
	s_barrier
	s_add_i32 s54, 0, 0x14000
	s_add_i32 s49, s49, s35
	v_add_u32_e32 v145, s54, v142
	v_lshl_add_u64 v[186:187], s[22:23], 0, v[134:135]
	s_mov_b32 m0, s49
	ds_read_b128 v[206:209], v145
	ds_read_b128 v[210:213], v145 offset:1024
	ds_read_b128 v[214:217], v145 offset:2048
	ds_read_b128 v[218:221], v145 offset:3072
	global_load_lds_dwordx4 v[186:187], off
	v_lshl_add_u64 v[188:189], s[22:23], 0, v[130:131]
	s_add_i32 m0, s49, 0x2000
	s_nop 0
	global_load_lds_dwordx4 v[188:189], off
	s_barrier
	s_waitcnt lgkmcnt(0)
	s_waitcnt lgkmcnt(0)
	v_mfma_f32_16x16x32_bf16 v[122:125], v[206:209], v[162:165], v[122:125]
	v_mfma_f32_16x16x32_bf16 v[114:117], v[214:217], v[162:165], v[114:117]
	v_mfma_f32_16x16x32_bf16 v[106:109], v[206:209], v[170:173], v[106:109]
	v_mfma_f32_16x16x32_bf16 v[98:101], v[214:217], v[170:173], v[98:101]
	v_mfma_f32_16x16x32_bf16 v[90:93], v[206:209], v[190:193], v[90:93]
	v_mfma_f32_16x16x32_bf16 v[82:85], v[214:217], v[190:193], v[82:85]
	v_mfma_f32_16x16x32_bf16 v[74:77], v[206:209], v[198:201], v[74:77]
	v_mfma_f32_16x16x32_bf16 v[66:69], v[214:217], v[198:201], v[66:69]
	v_mfma_f32_16x16x32_bf16 v[122:125], v[210:213], v[166:169], v[122:125]
	v_mfma_f32_16x16x32_bf16 v[114:117], v[218:221], v[166:169], v[114:117]
	v_mfma_f32_16x16x32_bf16 v[106:109], v[210:213], v[174:177], v[106:109]
	v_mfma_f32_16x16x32_bf16 v[98:101], v[218:221], v[174:177], v[98:101]
	v_mfma_f32_16x16x32_bf16 v[90:93], v[210:213], v[194:197], v[90:93]
	v_mfma_f32_16x16x32_bf16 v[82:85], v[218:221], v[194:197], v[82:85]
	v_mfma_f32_16x16x32_bf16 v[74:77], v[210:213], v[202:205], v[74:77]
	v_mfma_f32_16x16x32_bf16 v[66:69], v[218:221], v[202:205], v[66:69]
	s_mov_b32 m0, s19
	v_lshl_add_u64 v[222:223], s[24:25], 0, v[136:137]
	s_barrier
	ds_read_b128 v[162:165], v144 offset:16384
	ds_read_b128 v[166:169], v144 offset:17408
	ds_read_b128 v[170:173], v144 offset:18432
	ds_read_b128 v[174:177], v144 offset:19456
	ds_read_b128 v[190:193], v144 offset:20480
	ds_read_b128 v[194:197], v144 offset:21504
	ds_read_b128 v[198:201], v144 offset:22528
	ds_read_b128 v[202:205], v144 offset:23552
	global_load_lds_dwordx4 v[222:223], off
	v_lshl_add_u64 v[224:225], s[24:25], 0, v[132:133]
	s_mov_b32 m0, s36
	s_nop 0
	global_load_lds_dwordx4 v[224:225], off
	s_barrier
	s_waitcnt lgkmcnt(0)
	s_waitcnt lgkmcnt(0)
	v_mfma_f32_16x16x32_bf16 v[62:65], v[146:149], v[162:165], v[62:65]
	v_mfma_f32_16x16x32_bf16 v[54:57], v[154:157], v[162:165], v[54:57]
	v_mfma_f32_16x16x32_bf16 v[46:49], v[146:149], v[170:173], v[46:49]
	v_mfma_f32_16x16x32_bf16 v[38:41], v[154:157], v[170:173], v[38:41]
	v_mfma_f32_16x16x32_bf16 v[30:33], v[146:149], v[190:193], v[30:33]
	v_mfma_f32_16x16x32_bf16 v[22:25], v[154:157], v[190:193], v[22:25]
	v_mfma_f32_16x16x32_bf16 v[14:17], v[146:149], v[198:201], v[14:17]
	v_mfma_f32_16x16x32_bf16 v[6:9], v[154:157], v[198:201], v[6:9]
	v_mfma_f32_16x16x32_bf16 v[62:65], v[150:153], v[166:169], v[62:65]
	v_mfma_f32_16x16x32_bf16 v[54:57], v[158:161], v[166:169], v[54:57]
	v_mfma_f32_16x16x32_bf16 v[46:49], v[150:153], v[174:177], v[46:49]
	v_mfma_f32_16x16x32_bf16 v[38:41], v[158:161], v[174:177], v[38:41]
	v_mfma_f32_16x16x32_bf16 v[30:33], v[150:153], v[194:197], v[30:33]
	v_mfma_f32_16x16x32_bf16 v[22:25], v[158:161], v[194:197], v[22:25]
	v_mfma_f32_16x16x32_bf16 v[14:17], v[150:153], v[202:205], v[14:17]
	v_mfma_f32_16x16x32_bf16 v[6:9], v[158:161], v[202:205], v[6:9]
	s_barrier
	s_add_u32 s50, s22, 0x40000
	s_addc_u32 s51, s23, 0
	s_add_i32 s49, s54, s35
	s_mov_b32 m0, s49
	s_nop 0
	global_load_lds_dwordx4 v134, s[50:51]
	s_add_i32 m0, s49, 0x2000
	s_nop 0
	global_load_lds_dwordx4 v130, s[50:51]
	s_waitcnt vmcnt(6)
	s_barrier
	v_mfma_f32_16x16x32_bf16 v[58:61], v[206:209], v[162:165], v[58:61]
	v_mfma_f32_16x16x32_bf16 v[50:53], v[214:217], v[162:165], v[50:53]
	v_mfma_f32_16x16x32_bf16 v[42:45], v[206:209], v[170:173], v[42:45]
	v_mfma_f32_16x16x32_bf16 v[34:37], v[214:217], v[170:173], v[34:37]
	v_mfma_f32_16x16x32_bf16 v[26:29], v[206:209], v[190:193], v[26:29]
	v_mfma_f32_16x16x32_bf16 v[18:21], v[214:217], v[190:193], v[18:21]
	v_mfma_f32_16x16x32_bf16 v[10:13], v[206:209], v[198:201], v[10:13]
	v_mfma_f32_16x16x32_bf16 v[2:5], v[214:217], v[198:201], v[2:5]
	v_mfma_f32_16x16x32_bf16 v[58:61], v[210:213], v[166:169], v[58:61]
	v_mfma_f32_16x16x32_bf16 v[50:53], v[218:221], v[166:169], v[50:53]
	v_mfma_f32_16x16x32_bf16 v[42:45], v[210:213], v[174:177], v[42:45]
	v_mfma_f32_16x16x32_bf16 v[34:37], v[218:221], v[174:177], v[34:37]
	v_mfma_f32_16x16x32_bf16 v[26:29], v[210:213], v[194:197], v[26:29]
	v_mfma_f32_16x16x32_bf16 v[18:21], v[218:221], v[194:197], v[18:21]
	v_mfma_f32_16x16x32_bf16 v[10:13], v[210:213], v[202:205], v[10:13]
	v_mfma_f32_16x16x32_bf16 v[2:5], v[218:221], v[202:205], v[2:5]
	s_add_i32 s49, 0, 0x18000
	v_add_u32_e32 v145, s49, v142
	s_barrier
	ds_read_b128 v[146:149], v145
	ds_read_b128 v[150:153], v145 offset:1024
	ds_read_b128 v[154:157], v145 offset:2048
	ds_read_b128 v[158:161], v145 offset:3072
	s_add_u32 s24, s24, 0x40000
	s_addc_u32 s25, s25, 0
	s_mov_b32 m0, s37
	ds_read_b128 v[162:165], v144 offset:32768
	ds_read_b128 v[166:169], v144 offset:33792
	ds_read_b128 v[170:173], v144 offset:34816
	ds_read_b128 v[174:177], v144 offset:35840
	ds_read_b128 v[190:193], v144 offset:36864
	ds_read_b128 v[194:197], v144 offset:37888
	ds_read_b128 v[198:201], v144 offset:38912
	ds_read_b128 v[202:205], v144 offset:39936
	global_load_lds_dwordx4 v136, s[24:25]
	s_mov_b32 m0, s38
	s_nop 0
	global_load_lds_dwordx4 v132, s[24:25]
	s_waitcnt lgkmcnt(8)
	s_barrier
	s_waitcnt lgkmcnt(0)
	s_waitcnt lgkmcnt(0)
	v_mfma_f32_16x16x32_bf16 v[126:129], v[146:149], v[162:165], v[126:129]
	v_mfma_f32_16x16x32_bf16 v[118:121], v[154:157], v[162:165], v[118:121]
	v_mfma_f32_16x16x32_bf16 v[110:113], v[146:149], v[170:173], v[110:113]
	v_mfma_f32_16x16x32_bf16 v[102:105], v[154:157], v[170:173], v[102:105]
	v_mfma_f32_16x16x32_bf16 v[94:97], v[146:149], v[190:193], v[94:97]
	v_mfma_f32_16x16x32_bf16 v[86:89], v[154:157], v[190:193], v[86:89]
	v_mfma_f32_16x16x32_bf16 v[78:81], v[146:149], v[198:201], v[78:81]
	v_mfma_f32_16x16x32_bf16 v[70:73], v[154:157], v[198:201], v[70:73]
	v_mfma_f32_16x16x32_bf16 v[126:129], v[150:153], v[166:169], v[126:129]
	v_mfma_f32_16x16x32_bf16 v[118:121], v[158:161], v[166:169], v[118:121]
	v_mfma_f32_16x16x32_bf16 v[110:113], v[150:153], v[174:177], v[110:113]
	v_mfma_f32_16x16x32_bf16 v[102:105], v[158:161], v[174:177], v[102:105]
	v_mfma_f32_16x16x32_bf16 v[94:97], v[150:153], v[194:197], v[94:97]
	v_mfma_f32_16x16x32_bf16 v[86:89], v[158:161], v[194:197], v[86:89]
	v_mfma_f32_16x16x32_bf16 v[78:81], v[150:153], v[202:205], v[78:81]
	v_mfma_f32_16x16x32_bf16 v[70:73], v[158:161], v[202:205], v[70:73]
	s_barrier
	s_add_i32 s24, 0, 0x1c000
	s_add_i32 s25, s49, s35
	v_add_u32_e32 v145, s24, v142
	v_lshl_add_u64 v[186:187], v[186:187], 0, s[0:1]
	s_mov_b32 m0, s25
	ds_read_b128 v[206:209], v145
	ds_read_b128 v[210:213], v145 offset:1024
	ds_read_b128 v[214:217], v145 offset:2048
	ds_read_b128 v[218:221], v145 offset:3072
	global_load_lds_dwordx4 v[186:187], off
	v_lshl_add_u64 v[186:187], v[188:189], 0, s[0:1]
	s_add_i32 m0, s25, 0x2000
	s_nop 0
	global_load_lds_dwordx4 v[186:187], off
	s_barrier
	s_waitcnt lgkmcnt(0)
	s_waitcnt lgkmcnt(0)
	v_mfma_f32_16x16x32_bf16 v[122:125], v[206:209], v[162:165], v[122:125]
	v_mfma_f32_16x16x32_bf16 v[114:117], v[214:217], v[162:165], v[114:117]
	v_mfma_f32_16x16x32_bf16 v[106:109], v[206:209], v[170:173], v[106:109]
	v_mfma_f32_16x16x32_bf16 v[98:101], v[214:217], v[170:173], v[98:101]
	v_mfma_f32_16x16x32_bf16 v[90:93], v[206:209], v[190:193], v[90:93]
	v_mfma_f32_16x16x32_bf16 v[82:85], v[214:217], v[190:193], v[82:85]
	v_mfma_f32_16x16x32_bf16 v[74:77], v[206:209], v[198:201], v[74:77]
	v_mfma_f32_16x16x32_bf16 v[66:69], v[214:217], v[198:201], v[66:69]
	v_mfma_f32_16x16x32_bf16 v[122:125], v[210:213], v[166:169], v[122:125]
	v_mfma_f32_16x16x32_bf16 v[114:117], v[218:221], v[166:169], v[114:117]
	v_mfma_f32_16x16x32_bf16 v[106:109], v[210:213], v[174:177], v[106:109]
	v_mfma_f32_16x16x32_bf16 v[98:101], v[218:221], v[174:177], v[98:101]
	v_mfma_f32_16x16x32_bf16 v[90:93], v[210:213], v[194:197], v[90:93]
	v_mfma_f32_16x16x32_bf16 v[82:85], v[218:221], v[194:197], v[82:85]
	v_mfma_f32_16x16x32_bf16 v[74:77], v[210:213], v[202:205], v[74:77]
	v_mfma_f32_16x16x32_bf16 v[66:69], v[218:221], v[202:205], v[66:69]
	s_mov_b32 m0, s39
	v_lshl_add_u64 v[186:187], v[222:223], 0, s[0:1]
	s_barrier
	ds_read_b128 v[162:165], v144 offset:49152
	ds_read_b128 v[166:169], v144 offset:50176
	ds_read_b128 v[170:173], v144 offset:51200
	ds_read_b128 v[174:177], v144 offset:52224
	ds_read_b128 v[190:193], v144 offset:53248
	ds_read_b128 v[194:197], v144 offset:54272
	ds_read_b128 v[198:201], v144 offset:55296
	ds_read_b128 v[202:205], v144 offset:56320
	global_load_lds_dwordx4 v[186:187], off
	v_lshl_add_u64 v[186:187], v[224:225], 0, s[0:1]
	s_mov_b32 m0, s40
	s_nop 0
	global_load_lds_dwordx4 v[186:187], off
	s_barrier
	s_waitcnt lgkmcnt(0)
	s_waitcnt lgkmcnt(0)
	v_mfma_f32_16x16x32_bf16 v[62:65], v[146:149], v[162:165], v[62:65]
	v_mfma_f32_16x16x32_bf16 v[54:57], v[154:157], v[162:165], v[54:57]
	v_mfma_f32_16x16x32_bf16 v[46:49], v[146:149], v[170:173], v[46:49]
	v_mfma_f32_16x16x32_bf16 v[38:41], v[154:157], v[170:173], v[38:41]
	v_mfma_f32_16x16x32_bf16 v[30:33], v[146:149], v[190:193], v[30:33]
	v_mfma_f32_16x16x32_bf16 v[22:25], v[154:157], v[190:193], v[22:25]
	v_mfma_f32_16x16x32_bf16 v[14:17], v[146:149], v[198:201], v[14:17]
	v_mfma_f32_16x16x32_bf16 v[6:9], v[154:157], v[198:201], v[6:9]
	v_mfma_f32_16x16x32_bf16 v[62:65], v[150:153], v[166:169], v[62:65]
	v_mfma_f32_16x16x32_bf16 v[54:57], v[158:161], v[166:169], v[54:57]
	v_mfma_f32_16x16x32_bf16 v[46:49], v[150:153], v[174:177], v[46:49]
	v_mfma_f32_16x16x32_bf16 v[38:41], v[158:161], v[174:177], v[38:41]
	v_mfma_f32_16x16x32_bf16 v[30:33], v[150:153], v[194:197], v[30:33]
	v_mfma_f32_16x16x32_bf16 v[22:25], v[158:161], v[194:197], v[22:25]
	v_mfma_f32_16x16x32_bf16 v[14:17], v[150:153], v[202:205], v[14:17]
	v_mfma_f32_16x16x32_bf16 v[6:9], v[158:161], v[202:205], v[6:9]
	s_barrier
	s_add_u32 s22, s22, 0x40080
	s_addc_u32 s23, s23, 0
	s_add_i32 s24, s24, s35
	s_mov_b32 m0, s24
	s_nop 0
	global_load_lds_dwordx4 v134, s[22:23]
	s_add_i32 m0, s24, 0x2000
	s_nop 0
	global_load_lds_dwordx4 v130, s[22:23]
	s_waitcnt vmcnt(6)
	s_barrier
	v_mfma_f32_16x16x32_bf16 v[58:61], v[206:209], v[162:165], v[58:61]
	v_mfma_f32_16x16x32_bf16 v[50:53], v[214:217], v[162:165], v[50:53]
	v_mfma_f32_16x16x32_bf16 v[42:45], v[206:209], v[170:173], v[42:45]
	v_mfma_f32_16x16x32_bf16 v[34:37], v[214:217], v[170:173], v[34:37]
	v_mfma_f32_16x16x32_bf16 v[26:29], v[206:209], v[190:193], v[26:29]
	v_mfma_f32_16x16x32_bf16 v[18:21], v[214:217], v[190:193], v[18:21]
	v_mfma_f32_16x16x32_bf16 v[10:13], v[206:209], v[198:201], v[10:13]
	v_mfma_f32_16x16x32_bf16 v[2:5], v[214:217], v[198:201], v[2:5]
	v_mfma_f32_16x16x32_bf16 v[58:61], v[210:213], v[166:169], v[58:61]
	v_mfma_f32_16x16x32_bf16 v[50:53], v[218:221], v[166:169], v[50:53]
	v_mfma_f32_16x16x32_bf16 v[42:45], v[210:213], v[174:177], v[42:45]
	v_mfma_f32_16x16x32_bf16 v[34:37], v[218:221], v[174:177], v[34:37]
	v_mfma_f32_16x16x32_bf16 v[26:29], v[210:213], v[194:197], v[26:29]
	v_mfma_f32_16x16x32_bf16 v[18:21], v[218:221], v[194:197], v[18:21]
	v_mfma_f32_16x16x32_bf16 v[10:13], v[210:213], v[202:205], v[10:13]
	v_mfma_f32_16x16x32_bf16 v[2:5], v[218:221], v[202:205], v[2:5]
	s_add_i32 s48, s48, 2
	s_add_u32 s20, s20, 0x100
	s_addc_u32 s21, s21, 0
	s_add_u32 s46, s46, 0x100
	s_addc_u32 s47, s47, 0
	s_cmp_gt_u32 s48, 13
	s_barrier
	s_cbranch_scc0 .LBB0_297
	v_mul_f32_e32 v148, 0xbfb8aa3b, v126
	v_mul_f32_e32 v149, 0xbfb8aa3b, v127
	v_exp_f32_e32 v148, v148
	v_exp_f32_e32 v149, v149
	v_lshl_or_b32 v146, s43, 7, v143
	v_lshl_add_u32 v145, s18, 8, v1
	v_add_f32_e32 v148, 1.0, v148
	v_add_f32_e32 v149, 1.0, v149
	v_rcp_f32_e32 v148, v148
	v_rcp_f32_e32 v149, v149
	v_ashrrev_i32_e32 v147, 31, v146
	s_movk_i32 s7, 0x1700
	s_and_b64 vcc, exec, s[4:5]
	v_pk_mul_f32 v[126:127], v[126:127], v[148:149]
	s_mov_b32 s43, s6
	v_pk_mul_f32 v[122:123], v[126:127], v[122:123]
	v_mul_f32_e32 v126, 0xbfb8aa3b, v128
	v_mul_f32_e32 v127, 0xbfb8aa3b, v129
	v_exp_f32_e32 v126, v126
	v_exp_f32_e32 v127, v127
	s_mov_b32 s18, s8
	s_mov_b64 s[22:23], s[14:15]
	v_add_f32_e32 v126, 1.0, v126
	v_add_f32_e32 v127, 1.0, v127
	v_rcp_f32_e32 v126, v126
	v_rcp_f32_e32 v127, v127
	s_nop 0
	v_pk_mul_f32 v[126:127], v[128:129], v[126:127]
	s_nop 0
	v_pk_mul_f32 v[124:125], v[126:127], v[124:125]
	v_mul_f32_e32 v126, 0xbfb8aa3b, v118
	v_mul_f32_e32 v127, 0xbfb8aa3b, v119
	v_exp_f32_e32 v126, v126
	v_exp_f32_e32 v127, v127
	v_add_f32_e32 v126, 1.0, v126
	v_add_f32_e32 v127, 1.0, v127
	v_rcp_f32_e32 v126, v126
	v_rcp_f32_e32 v127, v127
	s_nop 0
	v_pk_mul_f32 v[118:119], v[118:119], v[126:127]
	s_nop 0
	v_pk_mul_f32 v[114:115], v[118:119], v[114:115]
	v_mul_f32_e32 v118, 0xbfb8aa3b, v120
	v_mul_f32_e32 v119, 0xbfb8aa3b, v121
	v_exp_f32_e32 v118, v118
	v_exp_f32_e32 v119, v119
	v_add_f32_e32 v118, 1.0, v118
	v_add_f32_e32 v119, 1.0, v119
	v_rcp_f32_e32 v118, v118
	v_rcp_f32_e32 v119, v119
	s_nop 0
	v_pk_mul_f32 v[118:119], v[120:121], v[118:119]
	s_nop 0
	v_pk_mul_f32 v[116:117], v[118:119], v[116:117]
	v_cvt_pk_bf16_f32 v120, v114, v115
	v_mov_b64_e32 v[114:115], s[2:3]
	v_cvt_pk_bf16_f32 v118, v122, v123
	v_cvt_pk_bf16_f32 v121, v116, v117
	v_mad_i64_i32 v[122:123], s[20:21], v145, s7, v[114:115]
	v_lshlrev_b64 v[116:117], 1, v[146:147]
	v_cvt_pk_bf16_f32 v119, v124, v125
	v_lshl_add_u64 v[122:123], v[122:123], 0, v[116:117]
	global_store_dwordx4 v[122:123], v[118:121], off
	s_nop 1
	v_mul_f32_e32 v118, 0xbfb8aa3b, v110
	v_mul_f32_e32 v119, 0xbfb8aa3b, v111
	v_exp_f32_e32 v118, v118
	v_exp_f32_e32 v119, v119
	v_add_f32_e32 v118, 1.0, v118
	v_add_f32_e32 v119, 1.0, v119
	v_rcp_f32_e32 v118, v118
	v_rcp_f32_e32 v119, v119
	s_nop 0
	v_pk_mul_f32 v[110:111], v[110:111], v[118:119]
	s_nop 0
	v_pk_mul_f32 v[106:107], v[110:111], v[106:107]
	v_mul_f32_e32 v110, 0xbfb8aa3b, v112
	v_mul_f32_e32 v111, 0xbfb8aa3b, v113
	v_exp_f32_e32 v110, v110
	v_exp_f32_e32 v111, v111
	v_add_f32_e32 v110, 1.0, v110
	v_add_f32_e32 v111, 1.0, v111
	v_rcp_f32_e32 v110, v110
	v_rcp_f32_e32 v111, v111
	s_nop 0
	v_pk_mul_f32 v[110:111], v[112:113], v[110:111]
	s_nop 0
	v_pk_mul_f32 v[108:109], v[110:111], v[108:109]
	v_mul_f32_e32 v110, 0xbfb8aa3b, v102
	v_mul_f32_e32 v111, 0xbfb8aa3b, v103
	v_exp_f32_e32 v110, v110
	v_exp_f32_e32 v111, v111
	v_add_f32_e32 v110, 1.0, v110
	v_add_f32_e32 v111, 1.0, v111
	v_rcp_f32_e32 v110, v110
	v_rcp_f32_e32 v111, v111
	s_nop 0
	v_pk_mul_f32 v[102:103], v[102:103], v[110:111]
	s_nop 0
	v_pk_mul_f32 v[102:103], v[102:103], v[98:99]
	v_mul_f32_e32 v98, 0xbfb8aa3b, v104
	v_mul_f32_e32 v99, 0xbfb8aa3b, v105
	v_exp_f32_e32 v98, v98
	v_exp_f32_e32 v99, v99
	v_add_f32_e32 v98, 1.0, v98
	v_add_f32_e32 v99, 1.0, v99
	v_rcp_f32_e32 v98, v98
	v_rcp_f32_e32 v99, v99
	s_nop 0
	v_pk_mul_f32 v[98:99], v[104:105], v[98:99]
	s_nop 0
	v_pk_mul_f32 v[104:105], v[98:99], v[100:101]
	v_cvt_pk_bf16_f32 v100, v102, v103
	v_or_b32_e32 v102, 16, v145
	v_mad_i64_i32 v[102:103], s[20:21], v102, s7, v[114:115]
	v_cvt_pk_bf16_f32 v98, v106, v107
	v_cvt_pk_bf16_f32 v99, v108, v109
	v_cvt_pk_bf16_f32 v101, v104, v105
	v_lshl_add_u64 v[102:103], v[102:103], 0, v[116:117]
	global_store_dwordx4 v[102:103], v[98:101], off
	s_nop 1
	v_mul_f32_e32 v98, 0xbfb8aa3b, v94
	v_mul_f32_e32 v99, 0xbfb8aa3b, v95
	v_exp_f32_e32 v98, v98
	v_exp_f32_e32 v99, v99
	v_add_f32_e32 v98, 1.0, v98
	v_add_f32_e32 v99, 1.0, v99
	v_rcp_f32_e32 v98, v98
	v_rcp_f32_e32 v99, v99
	s_nop 0
	v_pk_mul_f32 v[94:95], v[94:95], v[98:99]
	s_nop 0
	v_pk_mul_f32 v[90:91], v[94:95], v[90:91]
	v_mul_f32_e32 v94, 0xbfb8aa3b, v96
	v_mul_f32_e32 v95, 0xbfb8aa3b, v97
	v_exp_f32_e32 v94, v94
	v_exp_f32_e32 v95, v95
	v_add_f32_e32 v94, 1.0, v94
	v_add_f32_e32 v95, 1.0, v95
	v_rcp_f32_e32 v94, v94
	v_rcp_f32_e32 v95, v95
	s_nop 0
	v_pk_mul_f32 v[94:95], v[96:97], v[94:95]
	s_nop 0
	v_pk_mul_f32 v[92:93], v[94:95], v[92:93]
	v_mul_f32_e32 v94, 0xbfb8aa3b, v86
	v_mul_f32_e32 v95, 0xbfb8aa3b, v87
	v_exp_f32_e32 v94, v94
	v_exp_f32_e32 v95, v95
	v_add_f32_e32 v94, 1.0, v94
	v_add_f32_e32 v95, 1.0, v95
	v_rcp_f32_e32 v94, v94
	v_rcp_f32_e32 v95, v95
	s_nop 0
	v_pk_mul_f32 v[86:87], v[86:87], v[94:95]
	s_nop 0
	v_pk_mul_f32 v[86:87], v[86:87], v[82:83]
	v_mul_f32_e32 v82, 0xbfb8aa3b, v88
	v_mul_f32_e32 v83, 0xbfb8aa3b, v89
	v_exp_f32_e32 v82, v82
	v_exp_f32_e32 v83, v83
	v_add_f32_e32 v82, 1.0, v82
	v_add_f32_e32 v83, 1.0, v83
	v_rcp_f32_e32 v82, v82
	v_rcp_f32_e32 v83, v83
	s_nop 0
	v_pk_mul_f32 v[82:83], v[88:89], v[82:83]
	s_nop 0
	v_pk_mul_f32 v[88:89], v[82:83], v[84:85]
	v_cvt_pk_bf16_f32 v84, v86, v87
	v_or_b32_e32 v86, 32, v145
	v_mad_i64_i32 v[86:87], s[20:21], v86, s7, v[114:115]
	v_cvt_pk_bf16_f32 v82, v90, v91
	v_cvt_pk_bf16_f32 v83, v92, v93
	v_cvt_pk_bf16_f32 v85, v88, v89
	v_lshl_add_u64 v[86:87], v[86:87], 0, v[116:117]
	global_store_dwordx4 v[86:87], v[82:85], off
	s_nop 1
	v_mul_f32_e32 v82, 0xbfb8aa3b, v78
	v_mul_f32_e32 v83, 0xbfb8aa3b, v79
	v_exp_f32_e32 v82, v82
	v_exp_f32_e32 v83, v83
	v_add_f32_e32 v82, 1.0, v82
	v_add_f32_e32 v83, 1.0, v83
	v_rcp_f32_e32 v82, v82
	v_rcp_f32_e32 v83, v83
	s_nop 0
	v_pk_mul_f32 v[78:79], v[78:79], v[82:83]
	s_nop 0
	v_pk_mul_f32 v[74:75], v[78:79], v[74:75]
	v_mul_f32_e32 v78, 0xbfb8aa3b, v80
	v_mul_f32_e32 v79, 0xbfb8aa3b, v81
	v_exp_f32_e32 v78, v78
	v_exp_f32_e32 v79, v79
	v_add_f32_e32 v78, 1.0, v78
	v_add_f32_e32 v79, 1.0, v79
	v_rcp_f32_e32 v78, v78
	v_rcp_f32_e32 v79, v79
	s_nop 0
	v_pk_mul_f32 v[78:79], v[80:81], v[78:79]
	s_nop 0
	v_pk_mul_f32 v[76:77], v[78:79], v[76:77]
	v_mul_f32_e32 v78, 0xbfb8aa3b, v70
	v_mul_f32_e32 v79, 0xbfb8aa3b, v71
	v_exp_f32_e32 v78, v78
	v_exp_f32_e32 v79, v79
	v_add_f32_e32 v78, 1.0, v78
	v_add_f32_e32 v79, 1.0, v79
	v_rcp_f32_e32 v78, v78
	v_rcp_f32_e32 v79, v79
	s_nop 0
	v_pk_mul_f32 v[70:71], v[70:71], v[78:79]
	s_nop 0
	v_pk_mul_f32 v[70:71], v[70:71], v[66:67]
	v_mul_f32_e32 v66, 0xbfb8aa3b, v72
	v_mul_f32_e32 v67, 0xbfb8aa3b, v73
	v_exp_f32_e32 v66, v66
	v_exp_f32_e32 v67, v67
	v_add_f32_e32 v66, 1.0, v66
	v_add_f32_e32 v67, 1.0, v67
	v_rcp_f32_e32 v66, v66
	v_rcp_f32_e32 v67, v67
	s_nop 0
	v_pk_mul_f32 v[66:67], v[72:73], v[66:67]
	s_nop 0
	v_pk_mul_f32 v[72:73], v[66:67], v[68:69]
	v_cvt_pk_bf16_f32 v68, v70, v71
	v_or_b32_e32 v70, 48, v145
	v_mad_i64_i32 v[70:71], s[20:21], v70, s7, v[114:115]
	v_cvt_pk_bf16_f32 v66, v74, v75
	v_cvt_pk_bf16_f32 v67, v76, v77
	v_cvt_pk_bf16_f32 v69, v72, v73
	v_lshl_add_u64 v[70:71], v[70:71], 0, v[116:117]
	global_store_dwordx4 v[70:71], v[66:69], off
	s_nop 1
	v_mul_f32_e32 v66, 0xbfb8aa3b, v62
	v_mul_f32_e32 v67, 0xbfb8aa3b, v63
	v_exp_f32_e32 v66, v66
	v_exp_f32_e32 v67, v67
	v_add_u32_e32 v68, 0x80, v145
	v_add_f32_e32 v66, 1.0, v66
	v_add_f32_e32 v67, 1.0, v67
	v_rcp_f32_e32 v66, v66
	v_rcp_f32_e32 v67, v67
	s_nop 0
	v_pk_mul_f32 v[62:63], v[62:63], v[66:67]
	s_nop 0
	v_pk_mul_f32 v[58:59], v[62:63], v[58:59]
	v_mul_f32_e32 v62, 0xbfb8aa3b, v64
	v_mul_f32_e32 v63, 0xbfb8aa3b, v65
	v_exp_f32_e32 v62, v62
	v_exp_f32_e32 v63, v63
	v_add_f32_e32 v62, 1.0, v62
	v_add_f32_e32 v63, 1.0, v63
	v_rcp_f32_e32 v62, v62
	v_rcp_f32_e32 v63, v63
	s_nop 0
	v_pk_mul_f32 v[62:63], v[64:65], v[62:63]
	s_nop 0
	v_pk_mul_f32 v[60:61], v[62:63], v[60:61]
	v_mul_f32_e32 v62, 0xbfb8aa3b, v54
	v_mul_f32_e32 v63, 0xbfb8aa3b, v55
	v_exp_f32_e32 v62, v62
	v_exp_f32_e32 v63, v63
	v_add_f32_e32 v62, 1.0, v62
	v_add_f32_e32 v63, 1.0, v63
	v_rcp_f32_e32 v62, v62
	v_rcp_f32_e32 v63, v63
	s_nop 0
	v_pk_mul_f32 v[54:55], v[54:55], v[62:63]
	s_nop 0
	v_pk_mul_f32 v[54:55], v[54:55], v[50:51]
	v_mul_f32_e32 v50, 0xbfb8aa3b, v56
	v_mul_f32_e32 v51, 0xbfb8aa3b, v57
	v_exp_f32_e32 v50, v50
	v_exp_f32_e32 v51, v51
	v_add_f32_e32 v50, 1.0, v50
	v_add_f32_e32 v51, 1.0, v51
	v_rcp_f32_e32 v50, v50
	v_rcp_f32_e32 v51, v51
	s_nop 0
	v_pk_mul_f32 v[50:51], v[56:57], v[50:51]
	s_nop 0
	v_pk_mul_f32 v[56:57], v[50:51], v[52:53]
	v_cvt_pk_bf16_f32 v52, v54, v55
	v_mad_i64_i32 v[54:55], s[20:21], v68, s7, v[114:115]
	v_cvt_pk_bf16_f32 v50, v58, v59
	v_cvt_pk_bf16_f32 v51, v60, v61
	v_cvt_pk_bf16_f32 v53, v56, v57
	v_lshl_add_u64 v[54:55], v[54:55], 0, v[116:117]
	global_store_dwordx4 v[54:55], v[50:53], off
	s_nop 1
	v_mul_f32_e32 v50, 0xbfb8aa3b, v46
	v_mul_f32_e32 v51, 0xbfb8aa3b, v47
	v_exp_f32_e32 v50, v50
	v_exp_f32_e32 v51, v51
	v_add_f32_e32 v50, 1.0, v50
	v_add_f32_e32 v51, 1.0, v51
	v_rcp_f32_e32 v50, v50
	v_rcp_f32_e32 v51, v51
	s_nop 0
	v_pk_mul_f32 v[46:47], v[46:47], v[50:51]
	s_nop 0
	v_pk_mul_f32 v[42:43], v[46:47], v[42:43]
	v_mul_f32_e32 v46, 0xbfb8aa3b, v48
	v_mul_f32_e32 v47, 0xbfb8aa3b, v49
	v_exp_f32_e32 v46, v46
	v_exp_f32_e32 v47, v47
	v_add_f32_e32 v46, 1.0, v46
	v_add_f32_e32 v47, 1.0, v47
	v_rcp_f32_e32 v46, v46
	v_rcp_f32_e32 v47, v47
	s_nop 0
	v_pk_mul_f32 v[46:47], v[48:49], v[46:47]
	s_nop 0
	v_pk_mul_f32 v[44:45], v[46:47], v[44:45]
	v_mul_f32_e32 v46, 0xbfb8aa3b, v38
	v_mul_f32_e32 v47, 0xbfb8aa3b, v39
	v_exp_f32_e32 v46, v46
	v_exp_f32_e32 v47, v47
	v_add_f32_e32 v46, 1.0, v46
	v_add_f32_e32 v47, 1.0, v47
	v_rcp_f32_e32 v46, v46
	v_rcp_f32_e32 v47, v47
	s_nop 0
	v_pk_mul_f32 v[38:39], v[38:39], v[46:47]
	s_nop 0
	v_pk_mul_f32 v[38:39], v[38:39], v[34:35]
	v_mul_f32_e32 v34, 0xbfb8aa3b, v40
	v_mul_f32_e32 v35, 0xbfb8aa3b, v41
	v_exp_f32_e32 v34, v34
	v_exp_f32_e32 v35, v35
	v_add_f32_e32 v34, 1.0, v34
	v_add_f32_e32 v35, 1.0, v35
	v_rcp_f32_e32 v34, v34
	v_rcp_f32_e32 v35, v35
	s_nop 0
	v_pk_mul_f32 v[34:35], v[40:41], v[34:35]
	s_nop 0
	v_pk_mul_f32 v[40:41], v[34:35], v[36:37]
	v_cvt_pk_bf16_f32 v36, v38, v39
	v_add_u32_e32 v38, 0x90, v145
	v_mad_i64_i32 v[38:39], s[20:21], v38, s7, v[114:115]
	v_cvt_pk_bf16_f32 v34, v42, v43
	v_cvt_pk_bf16_f32 v35, v44, v45
	v_cvt_pk_bf16_f32 v37, v40, v41
	v_lshl_add_u64 v[38:39], v[38:39], 0, v[116:117]
	global_store_dwordx4 v[38:39], v[34:37], off
	s_nop 1
	v_mul_f32_e32 v34, 0xbfb8aa3b, v30
	v_mul_f32_e32 v35, 0xbfb8aa3b, v31
	v_exp_f32_e32 v34, v34
	v_exp_f32_e32 v35, v35
	v_add_f32_e32 v34, 1.0, v34
	v_add_f32_e32 v35, 1.0, v35
	v_rcp_f32_e32 v34, v34
	v_rcp_f32_e32 v35, v35
	s_nop 0
	v_pk_mul_f32 v[30:31], v[30:31], v[34:35]
	s_nop 0
	v_pk_mul_f32 v[26:27], v[30:31], v[26:27]
	v_mul_f32_e32 v30, 0xbfb8aa3b, v32
	v_mul_f32_e32 v31, 0xbfb8aa3b, v33
	v_exp_f32_e32 v30, v30
	v_exp_f32_e32 v31, v31
	v_add_f32_e32 v30, 1.0, v30
	v_add_f32_e32 v31, 1.0, v31
	v_rcp_f32_e32 v30, v30
	v_rcp_f32_e32 v31, v31
	s_nop 0
	v_pk_mul_f32 v[30:31], v[32:33], v[30:31]
	s_nop 0
	v_pk_mul_f32 v[28:29], v[30:31], v[28:29]
	v_mul_f32_e32 v30, 0xbfb8aa3b, v22
	v_mul_f32_e32 v31, 0xbfb8aa3b, v23
	v_exp_f32_e32 v30, v30
	v_exp_f32_e32 v31, v31
	v_add_f32_e32 v30, 1.0, v30
	v_add_f32_e32 v31, 1.0, v31
	v_rcp_f32_e32 v30, v30
	v_rcp_f32_e32 v31, v31
	s_nop 0
	v_pk_mul_f32 v[22:23], v[22:23], v[30:31]
	s_nop 0
	v_pk_mul_f32 v[22:23], v[22:23], v[18:19]
	v_mul_f32_e32 v18, 0xbfb8aa3b, v24
	v_mul_f32_e32 v19, 0xbfb8aa3b, v25
	v_exp_f32_e32 v18, v18
	v_exp_f32_e32 v19, v19
	v_add_f32_e32 v18, 1.0, v18
	v_add_f32_e32 v19, 1.0, v19
	v_rcp_f32_e32 v18, v18
	v_rcp_f32_e32 v19, v19
	s_nop 0
	v_pk_mul_f32 v[18:19], v[24:25], v[18:19]
	s_nop 0
	v_pk_mul_f32 v[24:25], v[18:19], v[20:21]
	v_cvt_pk_bf16_f32 v20, v22, v23
	v_add_u32_e32 v22, 0xa0, v145
	v_mad_i64_i32 v[22:23], s[20:21], v22, s7, v[114:115]
	v_cvt_pk_bf16_f32 v18, v26, v27
	v_cvt_pk_bf16_f32 v19, v28, v29
	v_cvt_pk_bf16_f32 v21, v24, v25
	v_lshl_add_u64 v[22:23], v[22:23], 0, v[116:117]
	global_store_dwordx4 v[22:23], v[18:21], off
	s_nop 1
	v_mul_f32_e32 v18, 0xbfb8aa3b, v14
	v_mul_f32_e32 v19, 0xbfb8aa3b, v15
	v_exp_f32_e32 v18, v18
	v_exp_f32_e32 v19, v19
	v_add_f32_e32 v18, 1.0, v18
	v_add_f32_e32 v19, 1.0, v19
	v_rcp_f32_e32 v18, v18
	v_rcp_f32_e32 v19, v19
	s_nop 0
	v_pk_mul_f32 v[14:15], v[14:15], v[18:19]
	s_nop 0
	v_pk_mul_f32 v[10:11], v[14:15], v[10:11]
	v_mul_f32_e32 v14, 0xbfb8aa3b, v16
	v_mul_f32_e32 v15, 0xbfb8aa3b, v17
	v_exp_f32_e32 v14, v14
	v_exp_f32_e32 v15, v15
	v_add_f32_e32 v14, 1.0, v14
	v_add_f32_e32 v15, 1.0, v15
	v_rcp_f32_e32 v14, v14
	v_rcp_f32_e32 v15, v15
	s_nop 0
	v_pk_mul_f32 v[14:15], v[16:17], v[14:15]
	s_nop 0
	v_pk_mul_f32 v[12:13], v[14:15], v[12:13]
	v_mul_f32_e32 v14, 0xbfb8aa3b, v6
	v_mul_f32_e32 v15, 0xbfb8aa3b, v7
	v_exp_f32_e32 v14, v14
	v_exp_f32_e32 v15, v15
	v_add_f32_e32 v14, 1.0, v14
	v_add_f32_e32 v15, 1.0, v15
	v_rcp_f32_e32 v14, v14
	v_rcp_f32_e32 v15, v15
	s_nop 0
	v_pk_mul_f32 v[6:7], v[6:7], v[14:15]
	s_nop 0
	v_pk_mul_f32 v[6:7], v[6:7], v[2:3]
	v_mul_f32_e32 v2, 0xbfb8aa3b, v8
	v_mul_f32_e32 v3, 0xbfb8aa3b, v9
	v_exp_f32_e32 v2, v2
	v_exp_f32_e32 v3, v3
	v_add_f32_e32 v2, 1.0, v2
	v_add_f32_e32 v3, 1.0, v3
	v_rcp_f32_e32 v2, v2
	v_rcp_f32_e32 v3, v3
	s_nop 0
	v_pk_mul_f32 v[2:3], v[8:9], v[2:3]
	s_nop 0
	v_pk_mul_f32 v[8:9], v[2:3], v[4:5]
	v_cvt_pk_bf16_f32 v4, v6, v7
	v_add_u32_e32 v6, 0xb0, v145
	v_mad_i64_i32 v[6:7], s[20:21], v6, s7, v[114:115]
	v_cvt_pk_bf16_f32 v2, v10, v11
	v_cvt_pk_bf16_f32 v3, v12, v13
	v_cvt_pk_bf16_f32 v5, v8, v9
	v_lshl_add_u64 v[6:7], v[6:7], 0, v[116:117]
	s_mov_b64 s[20:21], s[12:13]
	global_store_dwordx4 v[6:7], v[2:5], off
	s_cbranch_vccz .LBB0_294
	s_waitcnt vmcnt(0)
	s_cmpk_gt_u32 s28, 0xff
	s_cbranch_scc1 .LBB0_301
	s_barrier

.LBB0_374:
	s_add_u32 s16, s14, 0x100
	s_addc_u32 s17, s15, 0
	s_add_i32 s49, 0, 0x10000
	v_add_u32_e32 v154, s49, v164
	ds_read_b128 v[142:145], v154
	ds_read_b128 v[146:149], v154 offset:1024
	ds_read_b128 v[150:153], v154 offset:2048
	ds_read_b128 v[154:157], v154 offset:3072
	s_cmp_eq_u32 s48, 40
	s_cselect_b32 s21, s7, s17
	s_cselect_b32 s20, s6, s16
	s_cselect_b32 s19, s9, s47
	s_cselect_b32 s18, s8, s46
	v_lshl_add_u64 v[162:163], s[14:15], 0, v[138:139]
	s_add_i32 m0, s35, 0xc000
	ds_read_b128 v[158:161], v166
	ds_read_b128 v[168:171], v166 offset:1024
	ds_read_b128 v[172:175], v166 offset:2048
	ds_read_b128 v[190:193], v166 offset:3072
	ds_read_b128 v[194:197], v166 offset:4096
	ds_read_b128 v[198:201], v166 offset:5120
	ds_read_b128 v[202:205], v166 offset:6144
	ds_read_b128 v[206:209], v166 offset:7168
	global_load_lds_dwordx4 v[162:163], off
	v_lshl_add_u64 v[162:163], s[14:15], 0, v[140:141]
	s_add_i32 m0, s35, 0xe000
	s_nop 0
	global_load_lds_dwordx4 v[162:163], off
	s_waitcnt lgkmcnt(8)
	s_barrier
	s_waitcnt lgkmcnt(0)
	s_waitcnt lgkmcnt(0)
	v_mfma_f32_16x16x32_bf16 v[126:129], v[142:145], v[158:161], v[126:129]
	v_mfma_f32_16x16x32_bf16 v[122:125], v[150:153], v[158:161], v[122:125]
	v_mfma_f32_16x16x32_bf16 v[110:113], v[142:145], v[172:175], v[110:113]
	v_mfma_f32_16x16x32_bf16 v[106:109], v[150:153], v[172:175], v[106:109]
	v_mfma_f32_16x16x32_bf16 v[94:97], v[142:145], v[194:197], v[94:97]
	v_mfma_f32_16x16x32_bf16 v[90:93], v[150:153], v[194:197], v[90:93]
	v_mfma_f32_16x16x32_bf16 v[78:81], v[142:145], v[202:205], v[78:81]
	v_mfma_f32_16x16x32_bf16 v[74:77], v[150:153], v[202:205], v[74:77]
	v_mfma_f32_16x16x32_bf16 v[126:129], v[146:149], v[168:171], v[126:129]
	v_mfma_f32_16x16x32_bf16 v[122:125], v[154:157], v[168:171], v[122:125]
	v_mfma_f32_16x16x32_bf16 v[110:113], v[146:149], v[190:193], v[110:113]
	v_mfma_f32_16x16x32_bf16 v[106:109], v[154:157], v[190:193], v[106:109]
	v_mfma_f32_16x16x32_bf16 v[94:97], v[146:149], v[198:201], v[94:97]
	v_mfma_f32_16x16x32_bf16 v[90:93], v[154:157], v[198:201], v[90:93]
	v_mfma_f32_16x16x32_bf16 v[78:81], v[146:149], v[206:209], v[78:81]
	v_mfma_f32_16x16x32_bf16 v[74:77], v[154:157], v[206:209], v[74:77]
	s_barrier
	s_add_i32 s50, 0, 0x14000
	v_add_u32_e32 v162, s50, v164
	s_add_i32 s14, s49, s34
	ds_read_b128 v[210:213], v162
	ds_read_b128 v[214:217], v162 offset:1024
	ds_read_b128 v[218:221], v162 offset:2048
	ds_read_b128 v[222:225], v162 offset:3072
	v_lshl_add_u64 v[162:163], s[18:19], 0, v[132:133]
	s_mov_b32 m0, s14
	v_lshl_add_u64 v[176:177], s[18:19], 0, v[136:137]
	global_load_lds_dwordx4 v[162:163], off
	s_add_i32 m0, s14, 0x2000
	s_nop 0
	global_load_lds_dwordx4 v[176:177], off
	s_barrier
	s_waitcnt lgkmcnt(0)
	s_waitcnt lgkmcnt(0)
	v_mfma_f32_16x16x32_bf16 v[118:121], v[210:213], v[158:161], v[118:121]
	v_mfma_f32_16x16x32_bf16 v[114:117], v[218:221], v[158:161], v[114:117]
	v_mfma_f32_16x16x32_bf16 v[102:105], v[210:213], v[172:175], v[102:105]
	v_mfma_f32_16x16x32_bf16 v[98:101], v[218:221], v[172:175], v[98:101]
	v_mfma_f32_16x16x32_bf16 v[86:89], v[210:213], v[194:197], v[86:89]
	v_mfma_f32_16x16x32_bf16 v[82:85], v[218:221], v[194:197], v[82:85]
	v_mfma_f32_16x16x32_bf16 v[70:73], v[210:213], v[202:205], v[70:73]
	v_mfma_f32_16x16x32_bf16 v[66:69], v[218:221], v[202:205], v[66:69]
	v_mfma_f32_16x16x32_bf16 v[118:121], v[214:217], v[168:171], v[118:121]
	v_mfma_f32_16x16x32_bf16 v[114:117], v[222:225], v[168:171], v[114:117]
	v_mfma_f32_16x16x32_bf16 v[102:105], v[214:217], v[190:193], v[102:105]
	v_mfma_f32_16x16x32_bf16 v[98:101], v[222:225], v[190:193], v[98:101]
	v_mfma_f32_16x16x32_bf16 v[86:89], v[214:217], v[198:201], v[86:89]
	v_mfma_f32_16x16x32_bf16 v[82:85], v[222:225], v[198:201], v[82:85]
	v_mfma_f32_16x16x32_bf16 v[70:73], v[214:217], v[206:209], v[70:73]
	v_mfma_f32_16x16x32_bf16 v[66:69], v[222:225], v[206:209], v[66:69]
	s_mov_b32 m0, s35
	v_lshl_add_u64 v[186:187], s[20:21], 0, v[130:131]
	s_barrier
	ds_read_b128 v[158:161], v166 offset:16384
	ds_read_b128 v[168:171], v166 offset:17408
	ds_read_b128 v[172:175], v166 offset:18432
	ds_read_b128 v[190:193], v166 offset:19456
	ds_read_b128 v[194:197], v166 offset:20480
	ds_read_b128 v[198:201], v166 offset:21504
	ds_read_b128 v[202:205], v166 offset:22528
	ds_read_b128 v[206:209], v166 offset:23552
	global_load_lds_dwordx4 v[186:187], off
	v_lshl_add_u64 v[188:189], s[20:21], 0, v[134:135]
	s_mov_b32 m0, s36
	s_nop 0
	global_load_lds_dwordx4 v[188:189], off
	s_barrier
	s_waitcnt lgkmcnt(0)
	s_waitcnt lgkmcnt(0)
	v_mfma_f32_16x16x32_bf16 v[62:65], v[142:145], v[158:161], v[62:65]
	v_mfma_f32_16x16x32_bf16 v[58:61], v[150:153], v[158:161], v[58:61]
	v_mfma_f32_16x16x32_bf16 v[46:49], v[142:145], v[172:175], v[46:49]
	v_mfma_f32_16x16x32_bf16 v[42:45], v[150:153], v[172:175], v[42:45]
	v_mfma_f32_16x16x32_bf16 v[30:33], v[142:145], v[194:197], v[30:33]
	v_mfma_f32_16x16x32_bf16 v[26:29], v[150:153], v[194:197], v[26:29]
	v_mfma_f32_16x16x32_bf16 v[14:17], v[142:145], v[202:205], v[14:17]
	v_mfma_f32_16x16x32_bf16 v[10:13], v[150:153], v[202:205], v[10:13]
	v_mfma_f32_16x16x32_bf16 v[62:65], v[146:149], v[168:171], v[62:65]
	v_mfma_f32_16x16x32_bf16 v[58:61], v[154:157], v[168:171], v[58:61]
	v_mfma_f32_16x16x32_bf16 v[46:49], v[146:149], v[190:193], v[46:49]
	v_mfma_f32_16x16x32_bf16 v[42:45], v[154:157], v[190:193], v[42:45]
	v_mfma_f32_16x16x32_bf16 v[30:33], v[146:149], v[198:201], v[30:33]
	v_mfma_f32_16x16x32_bf16 v[26:29], v[154:157], v[198:201], v[26:29]
	v_mfma_f32_16x16x32_bf16 v[14:17], v[146:149], v[206:209], v[14:17]
	v_mfma_f32_16x16x32_bf16 v[10:13], v[154:157], v[206:209], v[10:13]
	s_barrier
	s_add_u32 s14, s18, 0xb0000
	s_addc_u32 s15, s19, 0
	s_add_i32 s49, s50, s34
	s_mov_b32 m0, s49
	s_nop 0
	global_load_lds_dwordx4 v132, s[14:15]
	s_add_i32 m0, s49, 0x2000
	s_nop 0
	global_load_lds_dwordx4 v136, s[14:15]
	s_waitcnt vmcnt(6)
	s_barrier
	v_mfma_f32_16x16x32_bf16 v[54:57], v[210:213], v[158:161], v[54:57]
	v_mfma_f32_16x16x32_bf16 v[50:53], v[218:221], v[158:161], v[50:53]
	v_mfma_f32_16x16x32_bf16 v[38:41], v[210:213], v[172:175], v[38:41]
	v_mfma_f32_16x16x32_bf16 v[34:37], v[218:221], v[172:175], v[34:37]
	v_mfma_f32_16x16x32_bf16 v[22:25], v[210:213], v[194:197], v[22:25]
	v_mfma_f32_16x16x32_bf16 v[18:21], v[218:221], v[194:197], v[18:21]
	v_mfma_f32_16x16x32_bf16 v[6:9], v[210:213], v[202:205], v[6:9]
	v_mfma_f32_16x16x32_bf16 v[2:5], v[218:221], v[202:205], v[2:5]
	v_mfma_f32_16x16x32_bf16 v[54:57], v[214:217], v[168:171], v[54:57]
	v_mfma_f32_16x16x32_bf16 v[50:53], v[222:225], v[168:171], v[50:53]
	v_mfma_f32_16x16x32_bf16 v[38:41], v[214:217], v[190:193], v[38:41]
	v_mfma_f32_16x16x32_bf16 v[34:37], v[222:225], v[190:193], v[34:37]
	v_mfma_f32_16x16x32_bf16 v[22:25], v[214:217], v[198:201], v[22:25]
	v_mfma_f32_16x16x32_bf16 v[18:21], v[222:225], v[198:201], v[18:21]
	v_mfma_f32_16x16x32_bf16 v[6:9], v[214:217], v[206:209], v[6:9]
	v_mfma_f32_16x16x32_bf16 v[2:5], v[222:225], v[206:209], v[2:5]
	s_add_i32 s49, 0, 0x18000
	v_add_u32_e32 v154, s49, v164
	s_barrier
	ds_read_b128 v[142:145], v154
	ds_read_b128 v[146:149], v154 offset:1024
	ds_read_b128 v[150:153], v154 offset:2048
	ds_read_b128 v[154:157], v154 offset:3072
	s_add_u32 s14, s20, 0xb8000
	s_addc_u32 s15, s21, 0
	s_mov_b32 m0, s37
	ds_read_b128 v[158:161], v166 offset:32768
	ds_read_b128 v[168:171], v166 offset:33792
	ds_read_b128 v[172:175], v166 offset:34816
	ds_read_b128 v[190:193], v166 offset:35840
	ds_read_b128 v[194:197], v166 offset:36864
	ds_read_b128 v[198:201], v166 offset:37888
	ds_read_b128 v[202:205], v166 offset:38912
	ds_read_b128 v[206:209], v166 offset:39936
	global_load_lds_dwordx4 v130, s[14:15]
	s_mov_b32 m0, s38
	s_nop 0
	global_load_lds_dwordx4 v134, s[14:15]
	s_waitcnt lgkmcnt(8)
	s_barrier
	s_waitcnt lgkmcnt(0)
	s_waitcnt lgkmcnt(0)
	v_mfma_f32_16x16x32_bf16 v[126:129], v[142:145], v[158:161], v[126:129]
	v_mfma_f32_16x16x32_bf16 v[122:125], v[150:153], v[158:161], v[122:125]
	v_mfma_f32_16x16x32_bf16 v[110:113], v[142:145], v[172:175], v[110:113]
	v_mfma_f32_16x16x32_bf16 v[106:109], v[150:153], v[172:175], v[106:109]
	v_mfma_f32_16x16x32_bf16 v[94:97], v[142:145], v[194:197], v[94:97]
	v_mfma_f32_16x16x32_bf16 v[90:93], v[150:153], v[194:197], v[90:93]
	v_mfma_f32_16x16x32_bf16 v[78:81], v[142:145], v[202:205], v[78:81]
	v_mfma_f32_16x16x32_bf16 v[74:77], v[150:153], v[202:205], v[74:77]
	v_mfma_f32_16x16x32_bf16 v[126:129], v[146:149], v[168:171], v[126:129]
	v_mfma_f32_16x16x32_bf16 v[122:125], v[154:157], v[168:171], v[122:125]
	v_mfma_f32_16x16x32_bf16 v[110:113], v[146:149], v[190:193], v[110:113]
	v_mfma_f32_16x16x32_bf16 v[106:109], v[154:157], v[190:193], v[106:109]
	v_mfma_f32_16x16x32_bf16 v[94:97], v[146:149], v[198:201], v[94:97]
	v_mfma_f32_16x16x32_bf16 v[90:93], v[154:157], v[198:201], v[90:93]
	v_mfma_f32_16x16x32_bf16 v[78:81], v[146:149], v[206:209], v[78:81]
	v_mfma_f32_16x16x32_bf16 v[74:77], v[154:157], v[206:209], v[74:77]
	s_barrier
	s_add_i32 s20, 0, 0x1c000
	s_add_i32 s14, s49, s34
	v_add_u32_e32 v167, s20, v164
	v_lshl_add_u64 v[162:163], v[162:163], 0, s[0:1]
	s_mov_b32 m0, s14
	ds_read_b128 v[210:213], v167
	ds_read_b128 v[214:217], v167 offset:1024
	ds_read_b128 v[218:221], v167 offset:2048
	ds_read_b128 v[222:225], v167 offset:3072
	global_load_lds_dwordx4 v[162:163], off
	v_lshl_add_u64 v[162:163], v[176:177], 0, s[0:1]
	s_add_i32 m0, s14, 0x2000
	s_nop 0
	global_load_lds_dwordx4 v[162:163], off
	s_barrier
	s_waitcnt lgkmcnt(0)
	s_waitcnt lgkmcnt(0)
	v_mfma_f32_16x16x32_bf16 v[118:121], v[210:213], v[158:161], v[118:121]
	v_mfma_f32_16x16x32_bf16 v[114:117], v[218:221], v[158:161], v[114:117]
	v_mfma_f32_16x16x32_bf16 v[102:105], v[210:213], v[172:175], v[102:105]
	v_mfma_f32_16x16x32_bf16 v[98:101], v[218:221], v[172:175], v[98:101]
	v_mfma_f32_16x16x32_bf16 v[86:89], v[210:213], v[194:197], v[86:89]
	v_mfma_f32_16x16x32_bf16 v[82:85], v[218:221], v[194:197], v[82:85]
	v_mfma_f32_16x16x32_bf16 v[70:73], v[210:213], v[202:205], v[70:73]
	v_mfma_f32_16x16x32_bf16 v[66:69], v[218:221], v[202:205], v[66:69]
	v_mfma_f32_16x16x32_bf16 v[118:121], v[214:217], v[168:171], v[118:121]
	v_mfma_f32_16x16x32_bf16 v[114:117], v[222:225], v[168:171], v[114:117]
	v_mfma_f32_16x16x32_bf16 v[102:105], v[214:217], v[190:193], v[102:105]
	v_mfma_f32_16x16x32_bf16 v[98:101], v[222:225], v[190:193], v[98:101]
	v_mfma_f32_16x16x32_bf16 v[86:89], v[214:217], v[198:201], v[86:89]
	v_mfma_f32_16x16x32_bf16 v[82:85], v[222:225], v[198:201], v[82:85]
	v_mfma_f32_16x16x32_bf16 v[70:73], v[214:217], v[206:209], v[70:73]
	v_mfma_f32_16x16x32_bf16 v[66:69], v[222:225], v[206:209], v[66:69]
	s_mov_b32 m0, s39
	v_lshl_add_u64 v[162:163], v[186:187], 0, s[0:1]
	s_barrier
	ds_read_b128 v[158:161], v166 offset:49152
	ds_read_b128 v[168:171], v166 offset:50176
	ds_read_b128 v[172:175], v166 offset:51200
	ds_read_b128 v[190:193], v166 offset:52224
	ds_read_b128 v[194:197], v166 offset:53248
	ds_read_b128 v[198:201], v166 offset:54272
	ds_read_b128 v[202:205], v166 offset:55296
	ds_read_b128 v[206:209], v166 offset:56320
	global_load_lds_dwordx4 v[162:163], off
	v_lshl_add_u64 v[162:163], v[188:189], 0, s[0:1]
	s_mov_b32 m0, s40
	s_nop 0
	global_load_lds_dwordx4 v[162:163], off
	s_barrier
	s_waitcnt lgkmcnt(0)
	s_waitcnt lgkmcnt(0)
	v_mfma_f32_16x16x32_bf16 v[62:65], v[142:145], v[158:161], v[62:65]
	v_mfma_f32_16x16x32_bf16 v[58:61], v[150:153], v[158:161], v[58:61]
	v_mfma_f32_16x16x32_bf16 v[46:49], v[142:145], v[172:175], v[46:49]
	v_mfma_f32_16x16x32_bf16 v[42:45], v[150:153], v[172:175], v[42:45]
	v_mfma_f32_16x16x32_bf16 v[30:33], v[142:145], v[194:197], v[30:33]
	v_mfma_f32_16x16x32_bf16 v[26:29], v[150:153], v[194:197], v[26:29]
	v_mfma_f32_16x16x32_bf16 v[14:17], v[142:145], v[202:205], v[14:17]
	v_mfma_f32_16x16x32_bf16 v[10:13], v[150:153], v[202:205], v[10:13]
	v_mfma_f32_16x16x32_bf16 v[62:65], v[146:149], v[168:171], v[62:65]
	v_mfma_f32_16x16x32_bf16 v[58:61], v[154:157], v[168:171], v[58:61]
	v_mfma_f32_16x16x32_bf16 v[46:49], v[146:149], v[190:193], v[46:49]
	v_mfma_f32_16x16x32_bf16 v[42:45], v[154:157], v[190:193], v[42:45]
	v_mfma_f32_16x16x32_bf16 v[30:33], v[146:149], v[198:201], v[30:33]
	v_mfma_f32_16x16x32_bf16 v[26:29], v[154:157], v[198:201], v[26:29]
	v_mfma_f32_16x16x32_bf16 v[14:17], v[146:149], v[206:209], v[14:17]
	v_mfma_f32_16x16x32_bf16 v[10:13], v[154:157], v[206:209], v[10:13]
	s_barrier
	s_add_u32 s14, s18, 0xb0080
	s_addc_u32 s15, s19, 0
	s_add_i32 s18, s20, s34
	s_mov_b32 m0, s18
	s_nop 0
	global_load_lds_dwordx4 v132, s[14:15]
	s_add_i32 m0, s18, 0x2000
	s_nop 0
	global_load_lds_dwordx4 v136, s[14:15]
	s_waitcnt vmcnt(6)
	s_barrier
	v_mfma_f32_16x16x32_bf16 v[54:57], v[210:213], v[158:161], v[54:57]
	v_mfma_f32_16x16x32_bf16 v[50:53], v[218:221], v[158:161], v[50:53]
	v_mfma_f32_16x16x32_bf16 v[38:41], v[210:213], v[172:175], v[38:41]
	v_mfma_f32_16x16x32_bf16 v[34:37], v[218:221], v[172:175], v[34:37]
	v_mfma_f32_16x16x32_bf16 v[22:25], v[210:213], v[194:197], v[22:25]
	v_mfma_f32_16x16x32_bf16 v[18:21], v[218:221], v[194:197], v[18:21]
	v_mfma_f32_16x16x32_bf16 v[6:9], v[210:213], v[202:205], v[6:9]
	v_mfma_f32_16x16x32_bf16 v[2:5], v[218:221], v[202:205], v[2:5]
	v_mfma_f32_16x16x32_bf16 v[54:57], v[214:217], v[168:171], v[54:57]
	v_mfma_f32_16x16x32_bf16 v[50:53], v[222:225], v[168:171], v[50:53]
	v_mfma_f32_16x16x32_bf16 v[38:41], v[214:217], v[190:193], v[38:41]
	v_mfma_f32_16x16x32_bf16 v[34:37], v[222:225], v[190:193], v[34:37]
	v_mfma_f32_16x16x32_bf16 v[22:25], v[214:217], v[198:201], v[22:25]
	v_mfma_f32_16x16x32_bf16 v[18:21], v[222:225], v[198:201], v[18:21]
	v_mfma_f32_16x16x32_bf16 v[6:9], v[214:217], v[206:209], v[6:9]
	v_mfma_f32_16x16x32_bf16 v[2:5], v[222:225], v[206:209], v[2:5]
	s_add_i32 s48, s48, 2
	s_add_u32 s46, s46, 0x100
	s_addc_u32 s47, s47, 0
	s_cmp_gt_u32 s48, 41
	s_mov_b64 s[14:15], s[16:17]
	s_barrier
	s_cbranch_scc0 .LBB0_374
	s_ashr_i32 s14, s33, 5
	s_mul_hi_i32 s15, s14, 0x9000
	s_mul_i32 s14, s14, 0x9000
	v_lshl_or_b32 v158, s45, 8, v165
	s_add_u32 s14, s26, s14
	s_addc_u32 s15, s27, s15
	v_ashrrev_i32_e32 v159, 31, v158
	v_lshl_add_u64 v[160:161], v[158:159], 2, s[14:15]
	global_load_dwordx4 v[142:145], v[160:161], off offset:16
	global_load_dwordx4 v[146:149], v[160:161], off
	v_lshl_add_u32 v162, s33, 8, v1
	v_ashrrev_i32_e32 v163, 31, v162
	s_mov_b64 s[14:15], 0x80000
	s_and_b64 vcc, exec, s[4:5]
	s_mov_b32 s45, s43
	s_mov_b32 s33, s44
	s_mov_b64 s[16:17], s[8:9]
	s_waitcnt vmcnt(0)
	v_pk_add_f32 v[144:145], v[144:145], 1.0 op_sel_hi:[1,0]
	v_pk_add_f32 v[148:149], v[148:149], 1.0 op_sel_hi:[1,0]
	v_pk_add_f32 v[146:147], v[146:147], 1.0 op_sel_hi:[1,0]
	v_pk_add_f32 v[142:143], v[142:143], 1.0 op_sel_hi:[1,0]
	v_pk_mul_f32 v[152:153], v[148:149], 0.5 op_sel_hi:[1,0]
	v_pk_mul_f32 v[156:157], v[146:147], 0.5 op_sel_hi:[1,0]
	v_pk_mul_f32 v[150:151], v[144:145], 0.5 op_sel_hi:[1,0]
	v_pk_mul_f32 v[154:155], v[142:143], 0.5 op_sel_hi:[1,0]
	global_load_dwordx4 v[142:145], v[160:161], off offset:528
	global_load_dwordx4 v[146:149], v[160:161], off offset:512
	s_waitcnt vmcnt(0)
	v_pk_add_f32 v[144:145], v[144:145], 1.0 op_sel_hi:[1,0]
	v_pk_add_f32 v[148:149], v[148:149], 1.0 op_sel_hi:[1,0]
	v_pk_add_f32 v[160:161], v[146:147], 1.0 op_sel_hi:[1,0]
	v_pk_mul_f32 v[146:147], v[148:149], 0.5 op_sel_hi:[1,0]
	v_pk_mul_f32 v[148:149], v[160:161], 0.5 op_sel_hi:[1,0]
	v_pk_add_f32 v[160:161], v[142:143], 1.0 op_sel_hi:[1,0]
	v_pk_mul_f32 v[142:143], v[144:145], 0.5 op_sel_hi:[1,0]
	v_pk_mul_f32 v[144:145], v[160:161], 0.5 op_sel_hi:[1,0]
	v_lshlrev_b64 v[160:161], 12, v[162:163]
	v_lshl_add_u64 v[168:169], s[12:13], 0, v[160:161]
	v_lshlrev_b64 v[160:161], 1, v[158:159]
	v_lshl_add_u64 v[158:159], v[168:169], 0, v[160:161]
	global_load_dwordx4 v[168:171], v[158:159], off offset:2048
	s_waitcnt vmcnt(0)
	v_lshlrev_b32_e32 v172, 16, v168
	v_and_b32_e32 v173, 0xffff0000, v168
	v_lshlrev_b32_e32 v168, 16, v169
	v_and_b32_e32 v169, 0xffff0000, v169
	v_pk_fma_f32 v[128:129], v[128:129], v[152:153], v[168:169]
	v_lshlrev_b32_e32 v168, 16, v170
	v_and_b32_e32 v169, 0xffff0000, v170
	v_pk_fma_f32 v[168:169], v[122:123], v[154:155], v[168:169]
	v_lshlrev_b32_e32 v122, 16, v171
	v_and_b32_e32 v123, 0xffff0000, v171
	v_pk_fma_f32 v[126:127], v[126:127], v[156:157], v[172:173]
	v_pk_fma_f32 v[170:171], v[124:125], v[150:151], v[122:123]
	v_cvt_pk_bf16_f32 v122, v126, v127
	v_cvt_pk_bf16_f32 v123, v128, v129
	v_cvt_pk_bf16_f32 v124, v168, v169
	v_cvt_pk_bf16_f32 v125, v170, v171
	global_store_dwordx4 v[158:159], v[122:125], off offset:2048
	global_load_dwordx4 v[122:125], v[158:159], off offset:2304
	s_waitcnt vmcnt(0)
	v_lshlrev_b32_e32 v126, 16, v122
	v_and_b32_e32 v127, 0xffff0000, v122
	v_lshlrev_b32_e32 v122, 16, v123
	v_and_b32_e32 v123, 0xffff0000, v123
	v_pk_fma_f32 v[120:121], v[120:121], v[146:147], v[122:123]
	v_lshlrev_b32_e32 v122, 16, v124
	v_and_b32_e32 v123, 0xffff0000, v124
	v_pk_fma_f32 v[122:123], v[114:115], v[144:145], v[122:123]
	v_lshlrev_b32_e32 v114, 16, v125
	v_and_b32_e32 v115, 0xffff0000, v125
	v_pk_fma_f32 v[118:119], v[118:119], v[148:149], v[126:127]
	v_pk_fma_f32 v[124:125], v[116:117], v[142:143], v[114:115]
	v_cvt_pk_bf16_f32 v114, v118, v119
	v_cvt_pk_bf16_f32 v115, v120, v121
	v_cvt_pk_bf16_f32 v116, v122, v123
	v_cvt_pk_bf16_f32 v117, v124, v125
	global_store_dwordx4 v[158:159], v[114:117], off offset:2304
	s_nop 1
	v_or_b32_e32 v114, 16, v162
	v_ashrrev_i32_e32 v115, 31, v114
	v_lshlrev_b64 v[114:115], 12, v[114:115]
	v_lshl_add_u64 v[114:115], s[12:13], 0, v[114:115]
	v_lshl_add_u64 v[118:119], v[114:115], 0, v[160:161]
	global_load_dwordx4 v[114:117], v[118:119], off offset:2048
	s_waitcnt vmcnt(0)
	v_lshlrev_b32_e32 v120, 16, v114
	v_and_b32_e32 v121, 0xffff0000, v114
	v_lshlrev_b32_e32 v114, 16, v115
	v_and_b32_e32 v115, 0xffff0000, v115
	v_pk_fma_f32 v[112:113], v[112:113], v[152:153], v[114:115]
	v_lshlrev_b32_e32 v114, 16, v116
	v_and_b32_e32 v115, 0xffff0000, v116
	v_pk_fma_f32 v[114:115], v[106:107], v[154:155], v[114:115]
	v_lshlrev_b32_e32 v106, 16, v117
	v_and_b32_e32 v107, 0xffff0000, v117
	v_pk_fma_f32 v[110:111], v[110:111], v[156:157], v[120:121]
	v_pk_fma_f32 v[116:117], v[108:109], v[150:151], v[106:107]
	v_cvt_pk_bf16_f32 v106, v110, v111
	v_cvt_pk_bf16_f32 v107, v112, v113
	v_cvt_pk_bf16_f32 v108, v114, v115
	v_cvt_pk_bf16_f32 v109, v116, v117
	global_store_dwordx4 v[118:119], v[106:109], off offset:2048
	global_load_dwordx4 v[106:109], v[118:119], off offset:2304
	s_waitcnt vmcnt(0)
	v_lshlrev_b32_e32 v110, 16, v106
	v_and_b32_e32 v111, 0xffff0000, v106
	v_lshlrev_b32_e32 v106, 16, v107
	v_and_b32_e32 v107, 0xffff0000, v107
	v_pk_fma_f32 v[104:105], v[104:105], v[146:147], v[106:107]
	v_lshlrev_b32_e32 v106, 16, v108
	v_and_b32_e32 v107, 0xffff0000, v108
	v_pk_fma_f32 v[106:107], v[98:99], v[144:145], v[106:107]
	v_lshlrev_b32_e32 v98, 16, v109
	v_and_b32_e32 v99, 0xffff0000, v109
	v_pk_fma_f32 v[102:103], v[102:103], v[148:149], v[110:111]
	v_pk_fma_f32 v[108:109], v[100:101], v[142:143], v[98:99]
	v_cvt_pk_bf16_f32 v98, v102, v103
	v_cvt_pk_bf16_f32 v99, v104, v105
	v_cvt_pk_bf16_f32 v100, v106, v107
	v_cvt_pk_bf16_f32 v101, v108, v109
	global_store_dwordx4 v[118:119], v[98:101], off offset:2304
	s_nop 1
	v_or_b32_e32 v98, 32, v162
	v_ashrrev_i32_e32 v99, 31, v98
	v_lshlrev_b64 v[98:99], 12, v[98:99]
	v_lshl_add_u64 v[98:99], s[12:13], 0, v[98:99]
	v_lshl_add_u64 v[102:103], v[98:99], 0, v[160:161]
	global_load_dwordx4 v[98:101], v[102:103], off offset:2048
	s_waitcnt vmcnt(0)
	v_lshlrev_b32_e32 v104, 16, v98
	v_and_b32_e32 v105, 0xffff0000, v98
	v_lshlrev_b32_e32 v98, 16, v99
	v_and_b32_e32 v99, 0xffff0000, v99
	v_pk_fma_f32 v[96:97], v[96:97], v[152:153], v[98:99]
	v_lshlrev_b32_e32 v98, 16, v100
	v_and_b32_e32 v99, 0xffff0000, v100
	v_pk_fma_f32 v[98:99], v[90:91], v[154:155], v[98:99]
	v_lshlrev_b32_e32 v90, 16, v101
	v_and_b32_e32 v91, 0xffff0000, v101
	v_pk_fma_f32 v[94:95], v[94:95], v[156:157], v[104:105]
	v_pk_fma_f32 v[100:101], v[92:93], v[150:151], v[90:91]
	v_cvt_pk_bf16_f32 v90, v94, v95
	v_cvt_pk_bf16_f32 v91, v96, v97
	v_cvt_pk_bf16_f32 v92, v98, v99
	v_cvt_pk_bf16_f32 v93, v100, v101
	global_store_dwordx4 v[102:103], v[90:93], off offset:2048
	global_load_dwordx4 v[90:93], v[102:103], off offset:2304
	s_waitcnt vmcnt(0)
	v_lshlrev_b32_e32 v94, 16, v90
	v_and_b32_e32 v95, 0xffff0000, v90
	v_lshlrev_b32_e32 v90, 16, v91
	v_and_b32_e32 v91, 0xffff0000, v91
	v_pk_fma_f32 v[88:89], v[88:89], v[146:147], v[90:91]
	v_lshlrev_b32_e32 v90, 16, v92
	v_and_b32_e32 v91, 0xffff0000, v92
	v_pk_fma_f32 v[90:91], v[82:83], v[144:145], v[90:91]
	v_lshlrev_b32_e32 v82, 16, v93
	v_and_b32_e32 v83, 0xffff0000, v93
	v_pk_fma_f32 v[86:87], v[86:87], v[148:149], v[94:95]
	v_pk_fma_f32 v[92:93], v[84:85], v[142:143], v[82:83]
	v_cvt_pk_bf16_f32 v82, v86, v87
	v_cvt_pk_bf16_f32 v83, v88, v89
	v_cvt_pk_bf16_f32 v84, v90, v91
	v_cvt_pk_bf16_f32 v85, v92, v93
	global_store_dwordx4 v[102:103], v[82:85], off offset:2304
	s_nop 1
	v_or_b32_e32 v82, 48, v162
	v_ashrrev_i32_e32 v83, 31, v82
	v_lshlrev_b64 v[82:83], 12, v[82:83]
	v_lshl_add_u64 v[82:83], s[12:13], 0, v[82:83]
	v_lshl_add_u64 v[82:83], v[82:83], 0, v[160:161]
	global_load_dwordx4 v[84:87], v[82:83], off offset:2048
	s_waitcnt vmcnt(0)
	v_lshlrev_b32_e32 v88, 16, v84
	v_and_b32_e32 v89, 0xffff0000, v84
	v_lshlrev_b32_e32 v84, 16, v85
	v_and_b32_e32 v85, 0xffff0000, v85
	v_pk_fma_f32 v[80:81], v[80:81], v[152:153], v[84:85]
	v_lshlrev_b32_e32 v84, 16, v86
	v_and_b32_e32 v85, 0xffff0000, v86
	v_pk_fma_f32 v[84:85], v[74:75], v[154:155], v[84:85]
	v_lshlrev_b32_e32 v74, 16, v87
	v_and_b32_e32 v75, 0xffff0000, v87
	v_pk_fma_f32 v[78:79], v[78:79], v[156:157], v[88:89]
	v_pk_fma_f32 v[86:87], v[76:77], v[150:151], v[74:75]
	v_cvt_pk_bf16_f32 v74, v78, v79
	v_cvt_pk_bf16_f32 v75, v80, v81
	v_cvt_pk_bf16_f32 v76, v84, v85
	v_cvt_pk_bf16_f32 v77, v86, v87
	global_store_dwordx4 v[82:83], v[74:77], off offset:2048
	global_load_dwordx4 v[74:77], v[82:83], off offset:2304
	s_waitcnt vmcnt(0)
	v_lshlrev_b32_e32 v78, 16, v74
	v_and_b32_e32 v79, 0xffff0000, v74
	v_lshlrev_b32_e32 v74, 16, v75
	v_and_b32_e32 v75, 0xffff0000, v75
	v_pk_fma_f32 v[72:73], v[72:73], v[146:147], v[74:75]
	v_lshlrev_b32_e32 v74, 16, v76
	v_and_b32_e32 v75, 0xffff0000, v76
	v_pk_fma_f32 v[74:75], v[66:67], v[144:145], v[74:75]
	v_lshlrev_b32_e32 v66, 16, v77
	v_and_b32_e32 v67, 0xffff0000, v77
	v_pk_fma_f32 v[70:71], v[70:71], v[148:149], v[78:79]
	v_pk_fma_f32 v[76:77], v[68:69], v[142:143], v[66:67]
	v_cvt_pk_bf16_f32 v66, v70, v71
	v_cvt_pk_bf16_f32 v67, v72, v73
	v_cvt_pk_bf16_f32 v68, v74, v75
	v_cvt_pk_bf16_f32 v69, v76, v77
	v_lshl_add_u64 v[70:71], v[158:159], 0, s[14:15]
	global_store_dwordx4 v[82:83], v[66:69], off offset:2304
	global_load_dwordx4 v[66:69], v[70:71], off offset:2048
	s_mov_b64 s[14:15], 0x90000
	s_waitcnt vmcnt(0)
	v_lshlrev_b32_e32 v72, 16, v66
	v_and_b32_e32 v73, 0xffff0000, v66
	v_lshlrev_b32_e32 v66, 16, v67
	v_and_b32_e32 v67, 0xffff0000, v67
	v_pk_fma_f32 v[64:65], v[64:65], v[152:153], v[66:67]
	v_lshlrev_b32_e32 v66, 16, v68
	v_and_b32_e32 v67, 0xffff0000, v68
	v_pk_fma_f32 v[66:67], v[58:59], v[154:155], v[66:67]
	v_lshlrev_b32_e32 v58, 16, v69
	v_and_b32_e32 v59, 0xffff0000, v69
	v_pk_fma_f32 v[62:63], v[62:63], v[156:157], v[72:73]
	v_pk_fma_f32 v[68:69], v[60:61], v[150:151], v[58:59]
	v_cvt_pk_bf16_f32 v58, v62, v63
	v_cvt_pk_bf16_f32 v59, v64, v65
	v_cvt_pk_bf16_f32 v60, v66, v67
	v_cvt_pk_bf16_f32 v61, v68, v69
	global_store_dwordx4 v[70:71], v[58:61], off offset:2048
	global_load_dwordx4 v[58:61], v[70:71], off offset:2304
	s_waitcnt vmcnt(0)
	v_lshlrev_b32_e32 v62, 16, v58
	v_and_b32_e32 v63, 0xffff0000, v58
	v_lshlrev_b32_e32 v58, 16, v59
	v_and_b32_e32 v59, 0xffff0000, v59
	v_pk_fma_f32 v[56:57], v[56:57], v[146:147], v[58:59]
	v_lshlrev_b32_e32 v58, 16, v60
	v_and_b32_e32 v59, 0xffff0000, v60
	v_pk_fma_f32 v[58:59], v[50:51], v[144:145], v[58:59]
	v_lshlrev_b32_e32 v50, 16, v61
	v_and_b32_e32 v51, 0xffff0000, v61
	v_pk_fma_f32 v[54:55], v[54:55], v[148:149], v[62:63]
	v_pk_fma_f32 v[60:61], v[52:53], v[142:143], v[50:51]
	v_cvt_pk_bf16_f32 v50, v54, v55
	v_cvt_pk_bf16_f32 v51, v56, v57
	v_cvt_pk_bf16_f32 v52, v58, v59
	v_cvt_pk_bf16_f32 v53, v60, v61
	v_lshl_add_u64 v[54:55], v[158:159], 0, s[14:15]
	global_store_dwordx4 v[70:71], v[50:53], off offset:2304
	global_load_dwordx4 v[50:53], v[54:55], off offset:2048
	s_mov_b64 s[14:15], 0xa0000
	s_waitcnt vmcnt(0)
	v_lshlrev_b32_e32 v56, 16, v50
	v_and_b32_e32 v57, 0xffff0000, v50
	v_lshlrev_b32_e32 v50, 16, v51
	v_and_b32_e32 v51, 0xffff0000, v51
	v_pk_fma_f32 v[48:49], v[48:49], v[152:153], v[50:51]
	v_lshlrev_b32_e32 v50, 16, v52
	v_and_b32_e32 v51, 0xffff0000, v52
	v_pk_fma_f32 v[50:51], v[42:43], v[154:155], v[50:51]
	v_lshlrev_b32_e32 v42, 16, v53
	v_and_b32_e32 v43, 0xffff0000, v53
	v_pk_fma_f32 v[46:47], v[46:47], v[156:157], v[56:57]
	v_pk_fma_f32 v[52:53], v[44:45], v[150:151], v[42:43]
	v_cvt_pk_bf16_f32 v42, v46, v47
	v_cvt_pk_bf16_f32 v43, v48, v49
	v_cvt_pk_bf16_f32 v44, v50, v51
	v_cvt_pk_bf16_f32 v45, v52, v53
	global_store_dwordx4 v[54:55], v[42:45], off offset:2048
	global_load_dwordx4 v[42:45], v[54:55], off offset:2304
	s_waitcnt vmcnt(0)
	v_lshlrev_b32_e32 v46, 16, v42
	v_and_b32_e32 v47, 0xffff0000, v42
	v_lshlrev_b32_e32 v42, 16, v43
	v_and_b32_e32 v43, 0xffff0000, v43
	v_pk_fma_f32 v[40:41], v[40:41], v[146:147], v[42:43]
	v_lshlrev_b32_e32 v42, 16, v44
	v_and_b32_e32 v43, 0xffff0000, v44
	v_pk_fma_f32 v[42:43], v[34:35], v[144:145], v[42:43]
	v_lshlrev_b32_e32 v34, 16, v45
	v_and_b32_e32 v35, 0xffff0000, v45
	v_pk_fma_f32 v[38:39], v[38:39], v[148:149], v[46:47]
	v_pk_fma_f32 v[44:45], v[36:37], v[142:143], v[34:35]
	v_cvt_pk_bf16_f32 v34, v38, v39
	v_cvt_pk_bf16_f32 v35, v40, v41
	v_cvt_pk_bf16_f32 v36, v42, v43
	v_cvt_pk_bf16_f32 v37, v44, v45
	v_lshl_add_u64 v[38:39], v[158:159], 0, s[14:15]
	global_store_dwordx4 v[54:55], v[34:37], off offset:2304
	global_load_dwordx4 v[34:37], v[38:39], off offset:2048
	s_mov_b64 s[14:15], 0xb0000
	s_waitcnt vmcnt(0)
	v_lshlrev_b32_e32 v40, 16, v34
	v_and_b32_e32 v41, 0xffff0000, v34
	v_lshlrev_b32_e32 v34, 16, v35
	v_and_b32_e32 v35, 0xffff0000, v35
	v_pk_fma_f32 v[32:33], v[32:33], v[152:153], v[34:35]
	v_lshlrev_b32_e32 v34, 16, v36
	v_and_b32_e32 v35, 0xffff0000, v36
	v_pk_fma_f32 v[34:35], v[26:27], v[154:155], v[34:35]
	v_lshlrev_b32_e32 v26, 16, v37
	v_and_b32_e32 v27, 0xffff0000, v37
	v_pk_fma_f32 v[30:31], v[30:31], v[156:157], v[40:41]
	v_pk_fma_f32 v[36:37], v[28:29], v[150:151], v[26:27]
	v_cvt_pk_bf16_f32 v26, v30, v31
	v_cvt_pk_bf16_f32 v27, v32, v33
	v_cvt_pk_bf16_f32 v28, v34, v35
	v_cvt_pk_bf16_f32 v29, v36, v37
	global_store_dwordx4 v[38:39], v[26:29], off offset:2048
	global_load_dwordx4 v[26:29], v[38:39], off offset:2304
	s_waitcnt vmcnt(0)
	v_lshlrev_b32_e32 v30, 16, v26
	v_and_b32_e32 v31, 0xffff0000, v26
	v_lshlrev_b32_e32 v26, 16, v27
	v_and_b32_e32 v27, 0xffff0000, v27
	v_pk_fma_f32 v[24:25], v[24:25], v[146:147], v[26:27]
	v_lshlrev_b32_e32 v26, 16, v28
	v_and_b32_e32 v27, 0xffff0000, v28
	v_pk_fma_f32 v[26:27], v[18:19], v[144:145], v[26:27]
	v_lshlrev_b32_e32 v18, 16, v29
	v_and_b32_e32 v19, 0xffff0000, v29
	v_pk_fma_f32 v[22:23], v[22:23], v[148:149], v[30:31]
	v_pk_fma_f32 v[28:29], v[20:21], v[142:143], v[18:19]
	v_cvt_pk_bf16_f32 v18, v22, v23
	v_cvt_pk_bf16_f32 v19, v24, v25
	v_cvt_pk_bf16_f32 v20, v26, v27
	v_cvt_pk_bf16_f32 v21, v28, v29
	global_store_dwordx4 v[38:39], v[18:21], off offset:2304
	s_nop 1
	v_lshl_add_u64 v[18:19], v[158:159], 0, s[14:15]
	global_load_dwordx4 v[20:23], v[18:19], off offset:2048
	s_mov_b64 s[14:15], s[6:7]
	s_waitcnt vmcnt(0)
	v_lshlrev_b32_e32 v24, 16, v20
	v_and_b32_e32 v25, 0xffff0000, v20
	v_lshlrev_b32_e32 v20, 16, v21
	v_and_b32_e32 v21, 0xffff0000, v21
	v_pk_fma_f32 v[16:17], v[16:17], v[152:153], v[20:21]
	v_lshlrev_b32_e32 v20, 16, v22
	v_and_b32_e32 v21, 0xffff0000, v22
	v_pk_fma_f32 v[20:21], v[10:11], v[154:155], v[20:21]
	v_lshlrev_b32_e32 v10, 16, v23
	v_and_b32_e32 v11, 0xffff0000, v23
	v_pk_fma_f32 v[14:15], v[14:15], v[156:157], v[24:25]
	v_pk_fma_f32 v[22:23], v[12:13], v[150:151], v[10:11]
	v_cvt_pk_bf16_f32 v10, v14, v15
	v_cvt_pk_bf16_f32 v11, v16, v17
	v_cvt_pk_bf16_f32 v12, v20, v21
	v_cvt_pk_bf16_f32 v13, v22, v23
	global_store_dwordx4 v[18:19], v[10:13], off offset:2048
	global_load_dwordx4 v[10:13], v[18:19], off offset:2304
	s_waitcnt vmcnt(0)
	v_lshlrev_b32_e32 v14, 16, v10
	v_and_b32_e32 v15, 0xffff0000, v10
	v_lshlrev_b32_e32 v10, 16, v11
	v_and_b32_e32 v11, 0xffff0000, v11
	v_pk_fma_f32 v[8:9], v[8:9], v[146:147], v[10:11]
	v_lshlrev_b32_e32 v10, 16, v12
	v_and_b32_e32 v11, 0xffff0000, v12
	v_pk_fma_f32 v[10:11], v[2:3], v[144:145], v[10:11]
	v_lshlrev_b32_e32 v2, 16, v13
	v_and_b32_e32 v3, 0xffff0000, v13
	v_pk_fma_f32 v[6:7], v[6:7], v[148:149], v[14:15]
	v_pk_fma_f32 v[12:13], v[4:5], v[142:143], v[2:3]
	v_cvt_pk_bf16_f32 v2, v6, v7
	v_cvt_pk_bf16_f32 v3, v8, v9
	v_cvt_pk_bf16_f32 v4, v10, v11
	v_cvt_pk_bf16_f32 v5, v12, v13
	global_store_dwordx4 v[18:19], v[2:5], off offset:2304
	s_cbranch_vccz .LBB0_363
	s_waitcnt vmcnt(0)
	s_cmpk_gt_u32 s30, 0xff
	s_cbranch_scc1 .LBB0_378
	s_barrier

.LBB0_400:
	s_add_u32 s16, s14, 0x100
	s_addc_u32 s17, s15, 0
	s_add_i32 s49, 0, 0x10000
	v_add_u32_e32 v154, s49, v164
	ds_read_b128 v[142:145], v154
	ds_read_b128 v[146:149], v154 offset:1024
	ds_read_b128 v[150:153], v154 offset:2048
	ds_read_b128 v[154:157], v154 offset:3072
	s_cmp_eq_u32 s48, 40
	s_cselect_b32 s21, s7, s17
	s_cselect_b32 s20, s6, s16
	s_cselect_b32 s19, s9, s47
	s_cselect_b32 s18, s8, s46
	v_lshl_add_u64 v[162:163], s[14:15], 0, v[138:139]
	s_add_i32 m0, s34, 0xc000
	ds_read_b128 v[158:161], v166
	ds_read_b128 v[168:171], v166 offset:1024
	ds_read_b128 v[172:175], v166 offset:2048
	ds_read_b128 v[190:193], v166 offset:3072
	ds_read_b128 v[194:197], v166 offset:4096
	ds_read_b128 v[198:201], v166 offset:5120
	ds_read_b128 v[202:205], v166 offset:6144
	ds_read_b128 v[206:209], v166 offset:7168
	global_load_lds_dwordx4 v[162:163], off
	v_lshl_add_u64 v[162:163], s[14:15], 0, v[140:141]
	s_add_i32 m0, s34, 0xe000
	s_nop 0
	global_load_lds_dwordx4 v[162:163], off
	s_waitcnt lgkmcnt(8)
	s_barrier
	s_waitcnt lgkmcnt(0)
	s_waitcnt lgkmcnt(0)
	v_mfma_f32_16x16x32_bf16 v[126:129], v[142:145], v[158:161], v[126:129]
	v_mfma_f32_16x16x32_bf16 v[122:125], v[150:153], v[158:161], v[122:125]
	v_mfma_f32_16x16x32_bf16 v[110:113], v[142:145], v[172:175], v[110:113]
	v_mfma_f32_16x16x32_bf16 v[106:109], v[150:153], v[172:175], v[106:109]
	v_mfma_f32_16x16x32_bf16 v[94:97], v[142:145], v[194:197], v[94:97]
	v_mfma_f32_16x16x32_bf16 v[90:93], v[150:153], v[194:197], v[90:93]
	v_mfma_f32_16x16x32_bf16 v[78:81], v[142:145], v[202:205], v[78:81]
	v_mfma_f32_16x16x32_bf16 v[74:77], v[150:153], v[202:205], v[74:77]
	v_mfma_f32_16x16x32_bf16 v[126:129], v[146:149], v[168:171], v[126:129]
	v_mfma_f32_16x16x32_bf16 v[122:125], v[154:157], v[168:171], v[122:125]
	v_mfma_f32_16x16x32_bf16 v[110:113], v[146:149], v[190:193], v[110:113]
	v_mfma_f32_16x16x32_bf16 v[106:109], v[154:157], v[190:193], v[106:109]
	v_mfma_f32_16x16x32_bf16 v[94:97], v[146:149], v[198:201], v[94:97]
	v_mfma_f32_16x16x32_bf16 v[90:93], v[154:157], v[198:201], v[90:93]
	v_mfma_f32_16x16x32_bf16 v[78:81], v[146:149], v[206:209], v[78:81]
	v_mfma_f32_16x16x32_bf16 v[74:77], v[154:157], v[206:209], v[74:77]
	s_barrier
	s_add_i32 s50, 0, 0x14000
	v_add_u32_e32 v162, s50, v164
	s_add_i32 s14, s49, s33
	ds_read_b128 v[210:213], v162
	ds_read_b128 v[214:217], v162 offset:1024
	ds_read_b128 v[218:221], v162 offset:2048
	ds_read_b128 v[222:225], v162 offset:3072
	v_lshl_add_u64 v[162:163], s[18:19], 0, v[132:133]
	s_mov_b32 m0, s14
	v_lshl_add_u64 v[176:177], s[18:19], 0, v[136:137]
	global_load_lds_dwordx4 v[162:163], off
	s_add_i32 m0, s14, 0x2000
	s_nop 0
	global_load_lds_dwordx4 v[176:177], off
	s_barrier
	s_waitcnt lgkmcnt(0)
	s_waitcnt lgkmcnt(0)
	v_mfma_f32_16x16x32_bf16 v[118:121], v[210:213], v[158:161], v[118:121]
	v_mfma_f32_16x16x32_bf16 v[114:117], v[218:221], v[158:161], v[114:117]
	v_mfma_f32_16x16x32_bf16 v[102:105], v[210:213], v[172:175], v[102:105]
	v_mfma_f32_16x16x32_bf16 v[98:101], v[218:221], v[172:175], v[98:101]
	v_mfma_f32_16x16x32_bf16 v[86:89], v[210:213], v[194:197], v[86:89]
	v_mfma_f32_16x16x32_bf16 v[82:85], v[218:221], v[194:197], v[82:85]
	v_mfma_f32_16x16x32_bf16 v[70:73], v[210:213], v[202:205], v[70:73]
	v_mfma_f32_16x16x32_bf16 v[66:69], v[218:221], v[202:205], v[66:69]
	v_mfma_f32_16x16x32_bf16 v[118:121], v[214:217], v[168:171], v[118:121]
	v_mfma_f32_16x16x32_bf16 v[114:117], v[222:225], v[168:171], v[114:117]
	v_mfma_f32_16x16x32_bf16 v[102:105], v[214:217], v[190:193], v[102:105]
	v_mfma_f32_16x16x32_bf16 v[98:101], v[222:225], v[190:193], v[98:101]
	v_mfma_f32_16x16x32_bf16 v[86:89], v[214:217], v[198:201], v[86:89]
	v_mfma_f32_16x16x32_bf16 v[82:85], v[222:225], v[198:201], v[82:85]
	v_mfma_f32_16x16x32_bf16 v[70:73], v[214:217], v[206:209], v[70:73]
	v_mfma_f32_16x16x32_bf16 v[66:69], v[222:225], v[206:209], v[66:69]
	s_mov_b32 m0, s34
	v_lshl_add_u64 v[186:187], s[20:21], 0, v[130:131]
	s_barrier
	ds_read_b128 v[158:161], v166 offset:16384
	ds_read_b128 v[168:171], v166 offset:17408
	ds_read_b128 v[172:175], v166 offset:18432
	ds_read_b128 v[190:193], v166 offset:19456
	ds_read_b128 v[194:197], v166 offset:20480
	ds_read_b128 v[198:201], v166 offset:21504
	ds_read_b128 v[202:205], v166 offset:22528
	ds_read_b128 v[206:209], v166 offset:23552
	global_load_lds_dwordx4 v[186:187], off
	v_lshl_add_u64 v[188:189], s[20:21], 0, v[134:135]
	s_mov_b32 m0, s35
	s_nop 0
	global_load_lds_dwordx4 v[188:189], off
	s_barrier
	s_waitcnt lgkmcnt(0)
	s_waitcnt lgkmcnt(0)
	v_mfma_f32_16x16x32_bf16 v[62:65], v[142:145], v[158:161], v[62:65]
	v_mfma_f32_16x16x32_bf16 v[58:61], v[150:153], v[158:161], v[58:61]
	v_mfma_f32_16x16x32_bf16 v[46:49], v[142:145], v[172:175], v[46:49]
	v_mfma_f32_16x16x32_bf16 v[42:45], v[150:153], v[172:175], v[42:45]
	v_mfma_f32_16x16x32_bf16 v[30:33], v[142:145], v[194:197], v[30:33]
	v_mfma_f32_16x16x32_bf16 v[26:29], v[150:153], v[194:197], v[26:29]
	v_mfma_f32_16x16x32_bf16 v[14:17], v[142:145], v[202:205], v[14:17]
	v_mfma_f32_16x16x32_bf16 v[10:13], v[150:153], v[202:205], v[10:13]
	v_mfma_f32_16x16x32_bf16 v[62:65], v[146:149], v[168:171], v[62:65]
	v_mfma_f32_16x16x32_bf16 v[58:61], v[154:157], v[168:171], v[58:61]
	v_mfma_f32_16x16x32_bf16 v[46:49], v[146:149], v[190:193], v[46:49]
	v_mfma_f32_16x16x32_bf16 v[42:45], v[154:157], v[190:193], v[42:45]
	v_mfma_f32_16x16x32_bf16 v[30:33], v[146:149], v[198:201], v[30:33]
	v_mfma_f32_16x16x32_bf16 v[26:29], v[154:157], v[198:201], v[26:29]
	v_mfma_f32_16x16x32_bf16 v[14:17], v[146:149], v[206:209], v[14:17]
	v_mfma_f32_16x16x32_bf16 v[10:13], v[154:157], v[206:209], v[10:13]
	s_barrier
	s_add_u32 s14, s18, 0xb0000
	s_addc_u32 s15, s19, 0
	s_add_i32 s49, s50, s33
	s_mov_b32 m0, s49
	s_nop 0
	global_load_lds_dwordx4 v132, s[14:15]
	s_add_i32 m0, s49, 0x2000
	s_nop 0
	global_load_lds_dwordx4 v136, s[14:15]
	s_waitcnt vmcnt(6)
	s_barrier
	v_mfma_f32_16x16x32_bf16 v[54:57], v[210:213], v[158:161], v[54:57]
	v_mfma_f32_16x16x32_bf16 v[50:53], v[218:221], v[158:161], v[50:53]
	v_mfma_f32_16x16x32_bf16 v[38:41], v[210:213], v[172:175], v[38:41]
	v_mfma_f32_16x16x32_bf16 v[34:37], v[218:221], v[172:175], v[34:37]
	v_mfma_f32_16x16x32_bf16 v[22:25], v[210:213], v[194:197], v[22:25]
	v_mfma_f32_16x16x32_bf16 v[18:21], v[218:221], v[194:197], v[18:21]
	v_mfma_f32_16x16x32_bf16 v[6:9], v[210:213], v[202:205], v[6:9]
	v_mfma_f32_16x16x32_bf16 v[2:5], v[218:221], v[202:205], v[2:5]
	v_mfma_f32_16x16x32_bf16 v[54:57], v[214:217], v[168:171], v[54:57]
	v_mfma_f32_16x16x32_bf16 v[50:53], v[222:225], v[168:171], v[50:53]
	v_mfma_f32_16x16x32_bf16 v[38:41], v[214:217], v[190:193], v[38:41]
	v_mfma_f32_16x16x32_bf16 v[34:37], v[222:225], v[190:193], v[34:37]
	v_mfma_f32_16x16x32_bf16 v[22:25], v[214:217], v[198:201], v[22:25]
	v_mfma_f32_16x16x32_bf16 v[18:21], v[222:225], v[198:201], v[18:21]
	v_mfma_f32_16x16x32_bf16 v[6:9], v[214:217], v[206:209], v[6:9]
	v_mfma_f32_16x16x32_bf16 v[2:5], v[222:225], v[206:209], v[2:5]
	s_add_i32 s49, 0, 0x18000
	v_add_u32_e32 v154, s49, v164
	s_barrier
	ds_read_b128 v[142:145], v154
	ds_read_b128 v[146:149], v154 offset:1024
	ds_read_b128 v[150:153], v154 offset:2048
	ds_read_b128 v[154:157], v154 offset:3072
	s_add_u32 s14, s20, 0xb8000
	s_addc_u32 s15, s21, 0
	s_mov_b32 m0, s36
	ds_read_b128 v[158:161], v166 offset:32768
	ds_read_b128 v[168:171], v166 offset:33792
	ds_read_b128 v[172:175], v166 offset:34816
	ds_read_b128 v[190:193], v166 offset:35840
	ds_read_b128 v[194:197], v166 offset:36864
	ds_read_b128 v[198:201], v166 offset:37888
	ds_read_b128 v[202:205], v166 offset:38912
	ds_read_b128 v[206:209], v166 offset:39936
	global_load_lds_dwordx4 v130, s[14:15]
	s_mov_b32 m0, s37
	s_nop 0
	global_load_lds_dwordx4 v134, s[14:15]
	s_waitcnt lgkmcnt(8)
	s_barrier
	s_waitcnt lgkmcnt(0)
	s_waitcnt lgkmcnt(0)
	v_mfma_f32_16x16x32_bf16 v[126:129], v[142:145], v[158:161], v[126:129]
	v_mfma_f32_16x16x32_bf16 v[122:125], v[150:153], v[158:161], v[122:125]
	v_mfma_f32_16x16x32_bf16 v[110:113], v[142:145], v[172:175], v[110:113]
	v_mfma_f32_16x16x32_bf16 v[106:109], v[150:153], v[172:175], v[106:109]
	v_mfma_f32_16x16x32_bf16 v[94:97], v[142:145], v[194:197], v[94:97]
	v_mfma_f32_16x16x32_bf16 v[90:93], v[150:153], v[194:197], v[90:93]
	v_mfma_f32_16x16x32_bf16 v[78:81], v[142:145], v[202:205], v[78:81]
	v_mfma_f32_16x16x32_bf16 v[74:77], v[150:153], v[202:205], v[74:77]
	v_mfma_f32_16x16x32_bf16 v[126:129], v[146:149], v[168:171], v[126:129]
	v_mfma_f32_16x16x32_bf16 v[122:125], v[154:157], v[168:171], v[122:125]
	v_mfma_f32_16x16x32_bf16 v[110:113], v[146:149], v[190:193], v[110:113]
	v_mfma_f32_16x16x32_bf16 v[106:109], v[154:157], v[190:193], v[106:109]
	v_mfma_f32_16x16x32_bf16 v[94:97], v[146:149], v[198:201], v[94:97]
	v_mfma_f32_16x16x32_bf16 v[90:93], v[154:157], v[198:201], v[90:93]
	v_mfma_f32_16x16x32_bf16 v[78:81], v[146:149], v[206:209], v[78:81]
	v_mfma_f32_16x16x32_bf16 v[74:77], v[154:157], v[206:209], v[74:77]
	s_barrier
	s_add_i32 s20, 0, 0x1c000
	s_add_i32 s14, s49, s33
	v_add_u32_e32 v167, s20, v164
	v_lshl_add_u64 v[162:163], v[162:163], 0, s[0:1]
	s_mov_b32 m0, s14
	ds_read_b128 v[210:213], v167
	ds_read_b128 v[214:217], v167 offset:1024
	ds_read_b128 v[218:221], v167 offset:2048
	ds_read_b128 v[222:225], v167 offset:3072
	global_load_lds_dwordx4 v[162:163], off
	v_lshl_add_u64 v[162:163], v[176:177], 0, s[0:1]
	s_add_i32 m0, s14, 0x2000
	s_nop 0
	global_load_lds_dwordx4 v[162:163], off
	s_barrier
	s_waitcnt lgkmcnt(0)
	s_waitcnt lgkmcnt(0)
	v_mfma_f32_16x16x32_bf16 v[118:121], v[210:213], v[158:161], v[118:121]
	v_mfma_f32_16x16x32_bf16 v[114:117], v[218:221], v[158:161], v[114:117]
	v_mfma_f32_16x16x32_bf16 v[102:105], v[210:213], v[172:175], v[102:105]
	v_mfma_f32_16x16x32_bf16 v[98:101], v[218:221], v[172:175], v[98:101]
	v_mfma_f32_16x16x32_bf16 v[86:89], v[210:213], v[194:197], v[86:89]
	v_mfma_f32_16x16x32_bf16 v[82:85], v[218:221], v[194:197], v[82:85]
	v_mfma_f32_16x16x32_bf16 v[70:73], v[210:213], v[202:205], v[70:73]
	v_mfma_f32_16x16x32_bf16 v[66:69], v[218:221], v[202:205], v[66:69]
	v_mfma_f32_16x16x32_bf16 v[118:121], v[214:217], v[168:171], v[118:121]
	v_mfma_f32_16x16x32_bf16 v[114:117], v[222:225], v[168:171], v[114:117]
	v_mfma_f32_16x16x32_bf16 v[102:105], v[214:217], v[190:193], v[102:105]
	v_mfma_f32_16x16x32_bf16 v[98:101], v[222:225], v[190:193], v[98:101]
	v_mfma_f32_16x16x32_bf16 v[86:89], v[214:217], v[198:201], v[86:89]
	v_mfma_f32_16x16x32_bf16 v[82:85], v[222:225], v[198:201], v[82:85]
	v_mfma_f32_16x16x32_bf16 v[70:73], v[214:217], v[206:209], v[70:73]
	v_mfma_f32_16x16x32_bf16 v[66:69], v[222:225], v[206:209], v[66:69]
	s_mov_b32 m0, s38
	v_lshl_add_u64 v[162:163], v[186:187], 0, s[0:1]
	s_barrier
	ds_read_b128 v[158:161], v166 offset:49152
	ds_read_b128 v[168:171], v166 offset:50176
	ds_read_b128 v[172:175], v166 offset:51200
	ds_read_b128 v[190:193], v166 offset:52224
	ds_read_b128 v[194:197], v166 offset:53248
	ds_read_b128 v[198:201], v166 offset:54272
	ds_read_b128 v[202:205], v166 offset:55296
	ds_read_b128 v[206:209], v166 offset:56320
	global_load_lds_dwordx4 v[162:163], off
	v_lshl_add_u64 v[162:163], v[188:189], 0, s[0:1]
	s_mov_b32 m0, s39
	s_nop 0
	global_load_lds_dwordx4 v[162:163], off
	s_barrier
	s_waitcnt lgkmcnt(0)
	s_waitcnt lgkmcnt(0)
	v_mfma_f32_16x16x32_bf16 v[62:65], v[142:145], v[158:161], v[62:65]
	v_mfma_f32_16x16x32_bf16 v[58:61], v[150:153], v[158:161], v[58:61]
	v_mfma_f32_16x16x32_bf16 v[46:49], v[142:145], v[172:175], v[46:49]
	v_mfma_f32_16x16x32_bf16 v[42:45], v[150:153], v[172:175], v[42:45]
	v_mfma_f32_16x16x32_bf16 v[30:33], v[142:145], v[194:197], v[30:33]
	v_mfma_f32_16x16x32_bf16 v[26:29], v[150:153], v[194:197], v[26:29]
	v_mfma_f32_16x16x32_bf16 v[14:17], v[142:145], v[202:205], v[14:17]
	v_mfma_f32_16x16x32_bf16 v[10:13], v[150:153], v[202:205], v[10:13]
	v_mfma_f32_16x16x32_bf16 v[62:65], v[146:149], v[168:171], v[62:65]
	v_mfma_f32_16x16x32_bf16 v[58:61], v[154:157], v[168:171], v[58:61]
	v_mfma_f32_16x16x32_bf16 v[46:49], v[146:149], v[190:193], v[46:49]
	v_mfma_f32_16x16x32_bf16 v[42:45], v[154:157], v[190:193], v[42:45]
	v_mfma_f32_16x16x32_bf16 v[30:33], v[146:149], v[198:201], v[30:33]
	v_mfma_f32_16x16x32_bf16 v[26:29], v[154:157], v[198:201], v[26:29]
	v_mfma_f32_16x16x32_bf16 v[14:17], v[146:149], v[206:209], v[14:17]
	v_mfma_f32_16x16x32_bf16 v[10:13], v[154:157], v[206:209], v[10:13]
	s_barrier
	s_add_u32 s14, s18, 0xb0080
	s_addc_u32 s15, s19, 0
	s_add_i32 s18, s20, s33
	s_mov_b32 m0, s18
	s_nop 0
	global_load_lds_dwordx4 v132, s[14:15]
	s_add_i32 m0, s18, 0x2000
	s_nop 0
	global_load_lds_dwordx4 v136, s[14:15]
	s_waitcnt vmcnt(6)
	s_barrier
	v_mfma_f32_16x16x32_bf16 v[54:57], v[210:213], v[158:161], v[54:57]
	v_mfma_f32_16x16x32_bf16 v[50:53], v[218:221], v[158:161], v[50:53]
	v_mfma_f32_16x16x32_bf16 v[38:41], v[210:213], v[172:175], v[38:41]
	v_mfma_f32_16x16x32_bf16 v[34:37], v[218:221], v[172:175], v[34:37]
	v_mfma_f32_16x16x32_bf16 v[22:25], v[210:213], v[194:197], v[22:25]
	v_mfma_f32_16x16x32_bf16 v[18:21], v[218:221], v[194:197], v[18:21]
	v_mfma_f32_16x16x32_bf16 v[6:9], v[210:213], v[202:205], v[6:9]
	v_mfma_f32_16x16x32_bf16 v[2:5], v[218:221], v[202:205], v[2:5]
	v_mfma_f32_16x16x32_bf16 v[54:57], v[214:217], v[168:171], v[54:57]
	v_mfma_f32_16x16x32_bf16 v[50:53], v[222:225], v[168:171], v[50:53]
	v_mfma_f32_16x16x32_bf16 v[38:41], v[214:217], v[190:193], v[38:41]
	v_mfma_f32_16x16x32_bf16 v[34:37], v[222:225], v[190:193], v[34:37]
	v_mfma_f32_16x16x32_bf16 v[22:25], v[214:217], v[198:201], v[22:25]
	v_mfma_f32_16x16x32_bf16 v[18:21], v[222:225], v[198:201], v[18:21]
	v_mfma_f32_16x16x32_bf16 v[6:9], v[214:217], v[206:209], v[6:9]
	v_mfma_f32_16x16x32_bf16 v[2:5], v[222:225], v[206:209], v[2:5]
	s_add_i32 s48, s48, 2
	s_add_u32 s46, s46, 0x100
	s_addc_u32 s47, s47, 0
	s_cmp_gt_u32 s48, 41
	s_mov_b64 s[14:15], s[16:17]
	s_barrier
	s_cbranch_scc0 .LBB0_400
	s_ashr_i32 s14, s44, 5
	v_lshl_or_b32 v176, s45, 8, v165
	s_mul_hi_i32 s15, s14, 0x9000
	s_mul_i32 s14, s14, 0x9000
	s_add_u32 s14, s26, s14
	v_ashrrev_i32_e32 v177, 31, v176
	s_addc_u32 s15, s27, s15
	v_lshlrev_b64 v[158:159], 2, v[176:177]
	v_lshl_add_u64 v[160:161], s[14:15], 0, v[158:159]
	global_load_dwordx4 v[142:145], v[160:161], off offset:16
	global_load_dwordx4 v[146:149], v[160:161], off
	v_lshl_add_u32 v162, s44, 8, v1
	v_ashrrev_i32_e32 v163, 31, v162
	s_mov_b64 s[14:15], 0x80000
	s_and_b64 vcc, exec, s[4:5]
	s_mov_b32 s45, s42
	s_mov_b32 s44, s43
	s_mov_b64 s[16:17], s[8:9]
	s_waitcnt vmcnt(0)
	v_pk_add_f32 v[144:145], v[144:145], 1.0 op_sel_hi:[1,0]
	v_pk_add_f32 v[148:149], v[148:149], 1.0 op_sel_hi:[1,0]
	v_pk_add_f32 v[146:147], v[146:147], 1.0 op_sel_hi:[1,0]
	v_pk_add_f32 v[142:143], v[142:143], 1.0 op_sel_hi:[1,0]
	v_pk_mul_f32 v[150:151], v[148:149], 0.5 op_sel_hi:[1,0]
	v_pk_mul_f32 v[152:153], v[146:147], 0.5 op_sel_hi:[1,0]
	v_pk_mul_f32 v[154:155], v[144:145], 0.5 op_sel_hi:[1,0]
	v_pk_mul_f32 v[156:157], v[142:143], 0.5 op_sel_hi:[1,0]
	global_load_dwordx4 v[146:149], v[160:161], off offset:528
	global_load_dwordx4 v[142:145], v[160:161], off offset:512
	s_waitcnt vmcnt(0)
	v_pk_add_f32 v[148:149], v[148:149], 1.0 op_sel_hi:[1,0]
	v_pk_add_f32 v[144:145], v[144:145], 1.0 op_sel_hi:[1,0]
	v_pk_add_f32 v[160:161], v[142:143], 1.0 op_sel_hi:[1,0]
	v_pk_mul_f32 v[142:143], v[144:145], 0.5 op_sel_hi:[1,0]
	v_pk_mul_f32 v[144:145], v[160:161], 0.5 op_sel_hi:[1,0]
	v_pk_add_f32 v[160:161], v[146:147], 1.0 op_sel_hi:[1,0]
	v_pk_mul_f32 v[146:147], v[148:149], 0.5 op_sel_hi:[1,0]
	v_pk_mul_f32 v[148:149], v[160:161], 0.5 op_sel_hi:[1,0]
	v_lshlrev_b64 v[160:161], 12, v[162:163]
	v_lshl_add_u64 v[168:169], s[2:3], 0, v[160:161]
	v_lshl_add_u64 v[186:187], v[168:169], 0, v[158:159]
	global_load_dwordx4 v[168:171], v[186:187], off offset:16
	global_load_dwordx4 v[172:175], v[186:187], off
	s_waitcnt vmcnt(0)
	v_pk_fma_f32 v[122:123], v[122:123], v[156:157], v[168:169]
	v_pk_fma_f32 v[128:129], v[128:129], v[150:151], v[174:175]
	v_pk_fma_f32 v[126:127], v[126:127], v[152:153], v[172:173]
	v_pk_fma_f32 v[170:171], v[124:125], v[154:155], v[170:171]
	v_cvt_pk_bf16_f32 v124, v126, v127
	v_cvt_pk_bf16_f32 v125, v128, v129
	v_cvt_pk_bf16_f32 v126, v122, v123
	v_lshl_add_u64 v[128:129], s[12:13], 0, v[160:161]
	v_lshlrev_b64 v[122:123], 1, v[176:177]
	v_cvt_pk_bf16_f32 v127, v170, v171
	v_lshl_add_u64 v[128:129], v[128:129], 0, v[122:123]
	global_store_dwordx4 v[128:129], v[124:127], off offset:2048
	global_load_dwordx4 v[124:127], v[186:187], off offset:528
	s_nop 0
	global_load_dwordx4 v[168:171], v[186:187], off offset:512
	s_waitcnt vmcnt(0)
	v_pk_fma_f32 v[126:127], v[116:117], v[146:147], v[126:127]
	v_pk_fma_f32 v[120:121], v[120:121], v[142:143], v[170:171]
	v_pk_fma_f32 v[118:119], v[118:119], v[144:145], v[168:169]
	v_pk_fma_f32 v[116:117], v[114:115], v[148:149], v[124:125]
	v_cvt_pk_bf16_f32 v114, v118, v119
	v_cvt_pk_bf16_f32 v115, v120, v121
	v_cvt_pk_bf16_f32 v116, v116, v117
	v_cvt_pk_bf16_f32 v117, v126, v127
	global_store_dwordx4 v[128:129], v[114:117], off offset:2304
	s_nop 1
	v_or_b32_e32 v114, 16, v162
	v_ashrrev_i32_e32 v115, 31, v114
	v_lshlrev_b64 v[124:125], 12, v[114:115]
	v_lshl_add_u64 v[114:115], s[2:3], 0, v[124:125]
	v_lshl_add_u64 v[126:127], v[114:115], 0, v[158:159]
	global_load_dwordx4 v[114:117], v[126:127], off offset:16
	global_load_dwordx4 v[118:121], v[126:127], off
	s_waitcnt vmcnt(0)
	v_pk_fma_f32 v[116:117], v[108:109], v[154:155], v[116:117]
	v_pk_fma_f32 v[110:111], v[110:111], v[152:153], v[118:119]
	v_pk_fma_f32 v[112:113], v[112:113], v[150:151], v[120:121]
	v_pk_fma_f32 v[108:109], v[106:107], v[156:157], v[114:115]
	v_cvt_pk_bf16_f32 v106, v110, v111
	v_lshl_add_u64 v[110:111], s[12:13], 0, v[124:125]
	v_cvt_pk_bf16_f32 v107, v112, v113
	v_cvt_pk_bf16_f32 v108, v108, v109
	v_cvt_pk_bf16_f32 v109, v116, v117
	v_lshl_add_u64 v[114:115], v[110:111], 0, v[122:123]
	global_store_dwordx4 v[114:115], v[106:109], off offset:2048
	global_load_dwordx4 v[106:109], v[126:127], off offset:528
	s_nop 0
	global_load_dwordx4 v[110:113], v[126:127], off offset:512
	s_waitcnt vmcnt(0)
	v_pk_fma_f32 v[108:109], v[100:101], v[146:147], v[108:109]
	v_pk_fma_f32 v[104:105], v[104:105], v[142:143], v[112:113]
	v_pk_fma_f32 v[102:103], v[102:103], v[144:145], v[110:111]
	v_pk_fma_f32 v[100:101], v[98:99], v[148:149], v[106:107]
	v_cvt_pk_bf16_f32 v98, v102, v103
	v_cvt_pk_bf16_f32 v99, v104, v105
	v_cvt_pk_bf16_f32 v100, v100, v101
	v_cvt_pk_bf16_f32 v101, v108, v109
	global_store_dwordx4 v[114:115], v[98:101], off offset:2304
	s_nop 1
	v_or_b32_e32 v98, 32, v162
	v_ashrrev_i32_e32 v99, 31, v98
	v_lshlrev_b64 v[106:107], 12, v[98:99]
	v_lshl_add_u64 v[98:99], s[2:3], 0, v[106:107]
	v_lshl_add_u64 v[108:109], v[98:99], 0, v[158:159]
	global_load_dwordx4 v[98:101], v[108:109], off offset:16
	global_load_dwordx4 v[102:105], v[108:109], off
	s_waitcnt vmcnt(0)
	v_pk_fma_f32 v[100:101], v[92:93], v[154:155], v[100:101]
	v_pk_fma_f32 v[94:95], v[94:95], v[152:153], v[102:103]
	v_pk_fma_f32 v[96:97], v[96:97], v[150:151], v[104:105]
	v_pk_fma_f32 v[92:93], v[90:91], v[156:157], v[98:99]
	v_cvt_pk_bf16_f32 v90, v94, v95
	v_lshl_add_u64 v[94:95], s[12:13], 0, v[106:107]
	v_cvt_pk_bf16_f32 v91, v96, v97
	v_cvt_pk_bf16_f32 v92, v92, v93
	v_cvt_pk_bf16_f32 v93, v100, v101
	v_lshl_add_u64 v[98:99], v[94:95], 0, v[122:123]
	global_store_dwordx4 v[98:99], v[90:93], off offset:2048
	global_load_dwordx4 v[90:93], v[108:109], off offset:528
	s_nop 0
	global_load_dwordx4 v[94:97], v[108:109], off offset:512
	s_waitcnt vmcnt(0)
	v_pk_fma_f32 v[92:93], v[84:85], v[146:147], v[92:93]
	v_pk_fma_f32 v[88:89], v[88:89], v[142:143], v[96:97]
	v_pk_fma_f32 v[86:87], v[86:87], v[144:145], v[94:95]
	v_pk_fma_f32 v[84:85], v[82:83], v[148:149], v[90:91]
	v_cvt_pk_bf16_f32 v82, v86, v87
	v_cvt_pk_bf16_f32 v83, v88, v89
	v_cvt_pk_bf16_f32 v84, v84, v85
	v_cvt_pk_bf16_f32 v85, v92, v93
	global_store_dwordx4 v[98:99], v[82:85], off offset:2304
	s_nop 1
	v_or_b32_e32 v82, 48, v162
	v_ashrrev_i32_e32 v83, 31, v82
	v_lshlrev_b64 v[90:91], 12, v[82:83]
	v_lshl_add_u64 v[82:83], s[2:3], 0, v[90:91]
	v_lshl_add_u64 v[92:93], v[82:83], 0, v[158:159]
	global_load_dwordx4 v[82:85], v[92:93], off offset:16
	global_load_dwordx4 v[86:89], v[92:93], off
	s_waitcnt vmcnt(0)
	v_pk_fma_f32 v[84:85], v[76:77], v[154:155], v[84:85]
	v_pk_fma_f32 v[78:79], v[78:79], v[152:153], v[86:87]
	v_pk_fma_f32 v[80:81], v[80:81], v[150:151], v[88:89]
	v_pk_fma_f32 v[76:77], v[74:75], v[156:157], v[82:83]
	v_cvt_pk_bf16_f32 v74, v78, v79
	v_lshl_add_u64 v[78:79], s[12:13], 0, v[90:91]
	v_cvt_pk_bf16_f32 v75, v80, v81
	v_cvt_pk_bf16_f32 v76, v76, v77
	v_cvt_pk_bf16_f32 v77, v84, v85
	v_lshl_add_u64 v[82:83], v[78:79], 0, v[122:123]
	global_store_dwordx4 v[82:83], v[74:77], off offset:2048
	global_load_dwordx4 v[74:77], v[92:93], off offset:528
	s_nop 0
	global_load_dwordx4 v[78:81], v[92:93], off offset:512
	s_waitcnt vmcnt(0)
	v_pk_fma_f32 v[76:77], v[68:69], v[146:147], v[76:77]
	v_pk_fma_f32 v[72:73], v[72:73], v[142:143], v[80:81]
	v_pk_fma_f32 v[70:71], v[70:71], v[144:145], v[78:79]
	v_pk_fma_f32 v[68:69], v[66:67], v[148:149], v[74:75]
	v_cvt_pk_bf16_f32 v66, v70, v71
	v_cvt_pk_bf16_f32 v67, v72, v73
	v_cvt_pk_bf16_f32 v68, v68, v69
	v_cvt_pk_bf16_f32 v69, v76, v77
	v_lshl_add_u64 v[74:75], v[160:161], 0, s[14:15]
	global_store_dwordx4 v[82:83], v[66:69], off offset:2304
	s_mov_b64 s[14:15], 0x90000
	s_nop 0
	v_lshl_add_u64 v[66:67], s[2:3], 0, v[74:75]
	v_lshl_add_u64 v[76:77], v[66:67], 0, v[158:159]
	global_load_dwordx4 v[66:69], v[76:77], off offset:16
	global_load_dwordx4 v[70:73], v[76:77], off
	s_waitcnt vmcnt(0)
	v_pk_fma_f32 v[68:69], v[60:61], v[154:155], v[68:69]
	v_pk_fma_f32 v[62:63], v[62:63], v[152:153], v[70:71]
	v_pk_fma_f32 v[64:65], v[64:65], v[150:151], v[72:73]
	v_pk_fma_f32 v[60:61], v[58:59], v[156:157], v[66:67]
	v_cvt_pk_bf16_f32 v58, v62, v63
	v_lshl_add_u64 v[62:63], s[12:13], 0, v[74:75]
	v_cvt_pk_bf16_f32 v59, v64, v65
	v_cvt_pk_bf16_f32 v60, v60, v61
	v_cvt_pk_bf16_f32 v61, v68, v69
	v_lshl_add_u64 v[66:67], v[62:63], 0, v[122:123]
	global_store_dwordx4 v[66:67], v[58:61], off offset:2048
	global_load_dwordx4 v[58:61], v[76:77], off offset:528
	s_nop 0
	global_load_dwordx4 v[62:65], v[76:77], off offset:512
	s_waitcnt vmcnt(0)
	v_pk_fma_f32 v[60:61], v[52:53], v[146:147], v[60:61]
	v_pk_fma_f32 v[56:57], v[56:57], v[142:143], v[64:65]
	v_pk_fma_f32 v[54:55], v[54:55], v[144:145], v[62:63]
	v_pk_fma_f32 v[52:53], v[50:51], v[148:149], v[58:59]
	v_cvt_pk_bf16_f32 v50, v54, v55
	v_cvt_pk_bf16_f32 v51, v56, v57
	v_cvt_pk_bf16_f32 v52, v52, v53
	v_cvt_pk_bf16_f32 v53, v60, v61
	v_lshl_add_u64 v[58:59], v[160:161], 0, s[14:15]
	global_store_dwordx4 v[66:67], v[50:53], off offset:2304
	s_mov_b64 s[14:15], 0xa0000
	s_nop 0
	v_lshl_add_u64 v[50:51], s[2:3], 0, v[58:59]
	v_lshl_add_u64 v[60:61], v[50:51], 0, v[158:159]
	global_load_dwordx4 v[50:53], v[60:61], off offset:16
	global_load_dwordx4 v[54:57], v[60:61], off
	s_waitcnt vmcnt(0)
	v_pk_fma_f32 v[52:53], v[44:45], v[154:155], v[52:53]
	v_pk_fma_f32 v[46:47], v[46:47], v[152:153], v[54:55]
	v_pk_fma_f32 v[48:49], v[48:49], v[150:151], v[56:57]
	v_pk_fma_f32 v[44:45], v[42:43], v[156:157], v[50:51]
	v_cvt_pk_bf16_f32 v42, v46, v47
	v_lshl_add_u64 v[46:47], s[12:13], 0, v[58:59]
	v_cvt_pk_bf16_f32 v43, v48, v49
	v_cvt_pk_bf16_f32 v44, v44, v45
	v_cvt_pk_bf16_f32 v45, v52, v53
	v_lshl_add_u64 v[50:51], v[46:47], 0, v[122:123]
	global_store_dwordx4 v[50:51], v[42:45], off offset:2048
	global_load_dwordx4 v[42:45], v[60:61], off offset:528
	s_nop 0
	global_load_dwordx4 v[46:49], v[60:61], off offset:512
	s_waitcnt vmcnt(0)
	v_pk_fma_f32 v[44:45], v[36:37], v[146:147], v[44:45]
	v_pk_fma_f32 v[40:41], v[40:41], v[142:143], v[48:49]
	v_pk_fma_f32 v[38:39], v[38:39], v[144:145], v[46:47]
	v_pk_fma_f32 v[36:37], v[34:35], v[148:149], v[42:43]
	v_cvt_pk_bf16_f32 v34, v38, v39
	v_cvt_pk_bf16_f32 v35, v40, v41
	v_cvt_pk_bf16_f32 v36, v36, v37
	v_cvt_pk_bf16_f32 v37, v44, v45
	v_lshl_add_u64 v[42:43], v[160:161], 0, s[14:15]
	global_store_dwordx4 v[50:51], v[34:37], off offset:2304
	s_mov_b64 s[14:15], 0xb0000
	s_nop 0
	v_lshl_add_u64 v[34:35], s[2:3], 0, v[42:43]
	v_lshl_add_u64 v[44:45], v[34:35], 0, v[158:159]
	global_load_dwordx4 v[34:37], v[44:45], off offset:16
	global_load_dwordx4 v[38:41], v[44:45], off
	s_waitcnt vmcnt(0)
	v_pk_fma_f32 v[36:37], v[28:29], v[154:155], v[36:37]
	v_pk_fma_f32 v[30:31], v[30:31], v[152:153], v[38:39]
	v_pk_fma_f32 v[32:33], v[32:33], v[150:151], v[40:41]
	v_pk_fma_f32 v[28:29], v[26:27], v[156:157], v[34:35]
	v_cvt_pk_bf16_f32 v26, v30, v31
	v_lshl_add_u64 v[30:31], s[12:13], 0, v[42:43]
	v_cvt_pk_bf16_f32 v27, v32, v33
	v_cvt_pk_bf16_f32 v28, v28, v29
	v_cvt_pk_bf16_f32 v29, v36, v37
	v_lshl_add_u64 v[34:35], v[30:31], 0, v[122:123]
	global_store_dwordx4 v[34:35], v[26:29], off offset:2048
	global_load_dwordx4 v[26:29], v[44:45], off offset:528
	s_nop 0
	global_load_dwordx4 v[30:33], v[44:45], off offset:512
	s_waitcnt vmcnt(0)
	v_pk_fma_f32 v[28:29], v[20:21], v[146:147], v[28:29]
	v_pk_fma_f32 v[24:25], v[24:25], v[142:143], v[32:33]
	v_pk_fma_f32 v[22:23], v[22:23], v[144:145], v[30:31]
	v_pk_fma_f32 v[20:21], v[18:19], v[148:149], v[26:27]
	v_cvt_pk_bf16_f32 v18, v22, v23
	v_cvt_pk_bf16_f32 v19, v24, v25
	v_cvt_pk_bf16_f32 v20, v20, v21
	v_cvt_pk_bf16_f32 v21, v28, v29
	v_lshl_add_u64 v[26:27], v[160:161], 0, s[14:15]
	global_store_dwordx4 v[34:35], v[18:21], off offset:2304
	s_mov_b64 s[14:15], s[6:7]
	s_nop 0
	v_lshl_add_u64 v[18:19], s[2:3], 0, v[26:27]
	v_lshl_add_u64 v[28:29], v[18:19], 0, v[158:159]
	global_load_dwordx4 v[18:21], v[28:29], off offset:16
	global_load_dwordx4 v[22:25], v[28:29], off
	s_waitcnt vmcnt(0)
	v_pk_fma_f32 v[20:21], v[12:13], v[154:155], v[20:21]
	v_pk_fma_f32 v[14:15], v[14:15], v[152:153], v[22:23]
	v_pk_fma_f32 v[16:17], v[16:17], v[150:151], v[24:25]
	v_pk_fma_f32 v[12:13], v[10:11], v[156:157], v[18:19]
	v_cvt_pk_bf16_f32 v10, v14, v15
	v_lshl_add_u64 v[14:15], s[12:13], 0, v[26:27]
	v_cvt_pk_bf16_f32 v11, v16, v17
	v_cvt_pk_bf16_f32 v12, v12, v13
	v_cvt_pk_bf16_f32 v13, v20, v21
	v_lshl_add_u64 v[18:19], v[14:15], 0, v[122:123]
	global_store_dwordx4 v[18:19], v[10:13], off offset:2048
	global_load_dwordx4 v[10:13], v[28:29], off offset:528
	s_nop 0
	global_load_dwordx4 v[14:17], v[28:29], off offset:512
	s_waitcnt vmcnt(0)
	v_pk_fma_f32 v[12:13], v[4:5], v[146:147], v[12:13]
	v_pk_fma_f32 v[8:9], v[8:9], v[142:143], v[16:17]
	v_pk_fma_f32 v[6:7], v[6:7], v[144:145], v[14:15]
	v_pk_fma_f32 v[4:5], v[2:3], v[148:149], v[10:11]
	v_cvt_pk_bf16_f32 v2, v6, v7
	v_cvt_pk_bf16_f32 v3, v8, v9
	v_cvt_pk_bf16_f32 v4, v4, v5
	v_cvt_pk_bf16_f32 v5, v12, v13
	global_store_dwordx4 v[18:19], v[2:5], off offset:2304
	s_cbranch_vccz .LBB0_389
	s_waitcnt vmcnt(0)
	s_cmpk_gt_u32 s30, 0xff
	s_cbranch_scc1 .LBB0_404
	s_barrier

.LBB0_528:
	s_add_u32 s22, s20, 0xfffc0080
	s_addc_u32 s23, s21, -1
	s_add_i32 s55, 0, 0x10000
	v_add_u32_e32 v144, s55, v146
	ds_read_b128 v[150:153], v144
	ds_read_b128 v[154:157], v144 offset:1024
	ds_read_b128 v[158:161], v144 offset:2048
	ds_read_b128 v[162:165], v144 offset:3072
	s_cmp_eq_u32 s54, 12
	s_cselect_b32 s25, s11, s23
	s_cselect_b32 s24, s15, s22
	s_cselect_b32 s23, s13, s53
	s_cselect_b32 s22, s51, s52
	s_add_i32 m0, s41, 0xc000
	ds_read_b128 v[166:169], v148
	ds_read_b128 v[170:173], v148 offset:1024
	ds_read_b128 v[174:177], v148 offset:2048
	ds_read_b128 v[190:193], v148 offset:3072
	ds_read_b128 v[194:197], v148 offset:4096
	ds_read_b128 v[198:201], v148 offset:5120
	ds_read_b128 v[202:205], v148 offset:6144
	ds_read_b128 v[206:209], v148 offset:7168
	global_load_lds_dwordx4 v140, s[20:21]
	v_lshl_add_u64 v[144:145], s[20:21], 0, v[142:143]
	s_add_i32 m0, s41, 0xe000
	s_nop 0
	global_load_lds_dwordx4 v[144:145], off
	s_waitcnt lgkmcnt(8)
	s_barrier
	s_waitcnt lgkmcnt(0)
	s_waitcnt lgkmcnt(0)
	v_mfma_f32_16x16x32_bf16 v[86:89], v[150:153], v[166:169], v[86:89]
	v_mfma_f32_16x16x32_bf16 v[82:85], v[158:161], v[166:169], v[82:85]
	v_mfma_f32_16x16x32_bf16 v[78:81], v[150:153], v[174:177], v[78:81]
	v_mfma_f32_16x16x32_bf16 v[74:77], v[158:161], v[174:177], v[74:77]
	v_mfma_f32_16x16x32_bf16 v[62:65], v[150:153], v[194:197], v[62:65]
	v_mfma_f32_16x16x32_bf16 v[58:61], v[158:161], v[194:197], v[58:61]
	v_mfma_f32_16x16x32_bf16 v[54:57], v[150:153], v[202:205], v[54:57]
	v_mfma_f32_16x16x32_bf16 v[50:53], v[158:161], v[202:205], v[50:53]
	v_mfma_f32_16x16x32_bf16 v[86:89], v[154:157], v[170:173], v[86:89]
	v_mfma_f32_16x16x32_bf16 v[82:85], v[162:165], v[170:173], v[82:85]
	v_mfma_f32_16x16x32_bf16 v[78:81], v[154:157], v[190:193], v[78:81]
	v_mfma_f32_16x16x32_bf16 v[74:77], v[162:165], v[190:193], v[74:77]
	v_mfma_f32_16x16x32_bf16 v[62:65], v[154:157], v[198:201], v[62:65]
	v_mfma_f32_16x16x32_bf16 v[58:61], v[162:165], v[198:201], v[58:61]
	v_mfma_f32_16x16x32_bf16 v[54:57], v[154:157], v[206:209], v[54:57]
	v_mfma_f32_16x16x32_bf16 v[50:53], v[162:165], v[206:209], v[50:53]
	s_barrier
	s_add_i32 s58, 0, 0x14000
	v_add_u32_e32 v144, s58, v146
	s_add_i32 s55, s55, s35
	ds_read_b128 v[210:213], v144
	ds_read_b128 v[214:217], v144 offset:1024
	ds_read_b128 v[218:221], v144 offset:2048
	ds_read_b128 v[222:225], v144 offset:3072
	v_lshl_add_u64 v[144:145], s[22:23], 0, v[134:135]
	s_mov_b32 m0, s55
	v_lshl_add_u64 v[186:187], s[22:23], 0, v[130:131]
	global_load_lds_dwordx4 v[144:145], off
	s_add_i32 m0, s55, 0x2000
	s_nop 0
	global_load_lds_dwordx4 v[186:187], off
	s_barrier
	s_waitcnt lgkmcnt(0)
	s_waitcnt lgkmcnt(0)
	v_mfma_f32_16x16x32_bf16 v[126:129], v[210:213], v[166:169], v[126:129]
	v_mfma_f32_16x16x32_bf16 v[122:125], v[218:221], v[166:169], v[122:125]
	v_mfma_f32_16x16x32_bf16 v[118:121], v[210:213], v[174:177], v[118:121]
	v_mfma_f32_16x16x32_bf16 v[114:117], v[218:221], v[174:177], v[114:117]
	v_mfma_f32_16x16x32_bf16 v[110:113], v[210:213], v[194:197], v[110:113]
	v_mfma_f32_16x16x32_bf16 v[106:109], v[218:221], v[194:197], v[106:109]
	v_mfma_f32_16x16x32_bf16 v[102:105], v[210:213], v[202:205], v[102:105]
	v_mfma_f32_16x16x32_bf16 v[98:101], v[218:221], v[202:205], v[98:101]
	v_mfma_f32_16x16x32_bf16 v[126:129], v[214:217], v[170:173], v[126:129]
	v_mfma_f32_16x16x32_bf16 v[122:125], v[222:225], v[170:173], v[122:125]
	v_mfma_f32_16x16x32_bf16 v[118:121], v[214:217], v[190:193], v[118:121]
	v_mfma_f32_16x16x32_bf16 v[114:117], v[222:225], v[190:193], v[114:117]
	v_mfma_f32_16x16x32_bf16 v[110:113], v[214:217], v[198:201], v[110:113]
	v_mfma_f32_16x16x32_bf16 v[106:109], v[222:225], v[198:201], v[106:109]
	v_mfma_f32_16x16x32_bf16 v[102:105], v[214:217], v[206:209], v[102:105]
	v_mfma_f32_16x16x32_bf16 v[98:101], v[222:225], v[206:209], v[98:101]
	s_mov_b32 m0, s41
	v_lshl_add_u64 v[188:189], s[24:25], 0, v[136:137]
	s_barrier
	ds_read_b128 v[166:169], v148 offset:16384
	ds_read_b128 v[170:173], v148 offset:17408
	ds_read_b128 v[174:177], v148 offset:18432
	ds_read_b128 v[190:193], v148 offset:19456
	ds_read_b128 v[194:197], v148 offset:20480
	ds_read_b128 v[198:201], v148 offset:21504
	ds_read_b128 v[202:205], v148 offset:22528
	ds_read_b128 v[206:209], v148 offset:23552
	global_load_lds_dwordx4 v[188:189], off
	v_lshl_add_u64 v[226:227], s[24:25], 0, v[132:133]
	s_mov_b32 m0, s42
	s_nop 0
	global_load_lds_dwordx4 v[226:227], off
	s_barrier
	s_waitcnt lgkmcnt(0)
	s_waitcnt lgkmcnt(0)
	v_mfma_f32_16x16x32_bf16 v[34:37], v[150:153], v[166:169], v[34:37]
	v_mfma_f32_16x16x32_bf16 v[26:29], v[158:161], v[166:169], v[26:29]
	v_mfma_f32_16x16x32_bf16 v[22:25], v[150:153], v[174:177], v[22:25]
	v_mfma_f32_16x16x32_bf16 v[18:21], v[158:161], v[174:177], v[18:21]
	v_mfma_f32_16x16x32_bf16 v[14:17], v[150:153], v[194:197], v[14:17]
	v_mfma_f32_16x16x32_bf16 v[10:13], v[158:161], v[194:197], v[10:13]
	v_mfma_f32_16x16x32_bf16 v[6:9], v[150:153], v[202:205], v[6:9]
	v_mfma_f32_16x16x32_bf16 v[2:5], v[158:161], v[202:205], v[2:5]
	v_mfma_f32_16x16x32_bf16 v[34:37], v[154:157], v[170:173], v[34:37]
	v_mfma_f32_16x16x32_bf16 v[26:29], v[162:165], v[170:173], v[26:29]
	v_mfma_f32_16x16x32_bf16 v[22:25], v[154:157], v[190:193], v[22:25]
	v_mfma_f32_16x16x32_bf16 v[18:21], v[162:165], v[190:193], v[18:21]
	v_mfma_f32_16x16x32_bf16 v[14:17], v[154:157], v[198:201], v[14:17]
	v_mfma_f32_16x16x32_bf16 v[10:13], v[162:165], v[198:201], v[10:13]
	v_mfma_f32_16x16x32_bf16 v[6:9], v[154:157], v[206:209], v[6:9]
	v_mfma_f32_16x16x32_bf16 v[2:5], v[162:165], v[206:209], v[2:5]
	s_barrier
	s_add_u32 s56, s22, 0x40000
	s_addc_u32 s57, s23, 0
	s_add_i32 s55, s58, s35
	s_mov_b32 m0, s55
	s_nop 0
	global_load_lds_dwordx4 v134, s[56:57]
	s_add_i32 m0, s55, 0x2000
	s_nop 0
	global_load_lds_dwordx4 v130, s[56:57]
	s_waitcnt vmcnt(6)
	s_barrier
	v_mfma_f32_16x16x32_bf16 v[94:97], v[210:213], v[166:169], v[94:97]
	v_mfma_f32_16x16x32_bf16 v[90:93], v[218:221], v[166:169], v[90:93]
	v_mfma_f32_16x16x32_bf16 v[70:73], v[210:213], v[174:177], v[70:73]
	v_mfma_f32_16x16x32_bf16 v[66:69], v[218:221], v[174:177], v[66:69]
	v_mfma_f32_16x16x32_bf16 v[46:49], v[210:213], v[194:197], v[46:49]
	v_mfma_f32_16x16x32_bf16 v[42:45], v[218:221], v[194:197], v[42:45]
	v_mfma_f32_16x16x32_bf16 v[38:41], v[210:213], v[202:205], v[38:41]
	v_mfma_f32_16x16x32_bf16 v[30:33], v[218:221], v[202:205], v[30:33]
	v_mfma_f32_16x16x32_bf16 v[94:97], v[214:217], v[170:173], v[94:97]
	v_mfma_f32_16x16x32_bf16 v[90:93], v[222:225], v[170:173], v[90:93]
	v_mfma_f32_16x16x32_bf16 v[70:73], v[214:217], v[190:193], v[70:73]
	v_mfma_f32_16x16x32_bf16 v[66:69], v[222:225], v[190:193], v[66:69]
	v_mfma_f32_16x16x32_bf16 v[46:49], v[214:217], v[198:201], v[46:49]
	v_mfma_f32_16x16x32_bf16 v[42:45], v[222:225], v[198:201], v[42:45]
	v_mfma_f32_16x16x32_bf16 v[38:41], v[214:217], v[206:209], v[38:41]
	v_mfma_f32_16x16x32_bf16 v[30:33], v[222:225], v[206:209], v[30:33]
	s_add_i32 s55, 0, 0x18000
	v_add_u32_e32 v149, s55, v146
	s_barrier
	ds_read_b128 v[150:153], v149
	ds_read_b128 v[154:157], v149 offset:1024
	ds_read_b128 v[158:161], v149 offset:2048
	ds_read_b128 v[162:165], v149 offset:3072
	s_add_u32 s24, s24, 0x40000
	s_addc_u32 s25, s25, 0
	s_mov_b32 m0, s43
	ds_read_b128 v[166:169], v148 offset:32768
	ds_read_b128 v[170:173], v148 offset:33792
	ds_read_b128 v[174:177], v148 offset:34816
	ds_read_b128 v[190:193], v148 offset:35840
	ds_read_b128 v[194:197], v148 offset:36864
	ds_read_b128 v[198:201], v148 offset:37888
	ds_read_b128 v[202:205], v148 offset:38912
	ds_read_b128 v[206:209], v148 offset:39936
	global_load_lds_dwordx4 v136, s[24:25]
	s_mov_b32 m0, s44
	s_nop 0
	global_load_lds_dwordx4 v132, s[24:25]
	s_waitcnt lgkmcnt(8)
	s_barrier
	s_waitcnt lgkmcnt(0)
	s_waitcnt lgkmcnt(0)
	v_mfma_f32_16x16x32_bf16 v[86:89], v[150:153], v[166:169], v[86:89]
	v_mfma_f32_16x16x32_bf16 v[82:85], v[158:161], v[166:169], v[82:85]
	v_mfma_f32_16x16x32_bf16 v[78:81], v[150:153], v[174:177], v[78:81]
	v_mfma_f32_16x16x32_bf16 v[74:77], v[158:161], v[174:177], v[74:77]
	v_mfma_f32_16x16x32_bf16 v[62:65], v[150:153], v[194:197], v[62:65]
	v_mfma_f32_16x16x32_bf16 v[58:61], v[158:161], v[194:197], v[58:61]
	v_mfma_f32_16x16x32_bf16 v[54:57], v[150:153], v[202:205], v[54:57]
	v_mfma_f32_16x16x32_bf16 v[50:53], v[158:161], v[202:205], v[50:53]
	v_mfma_f32_16x16x32_bf16 v[86:89], v[154:157], v[170:173], v[86:89]
	v_mfma_f32_16x16x32_bf16 v[82:85], v[162:165], v[170:173], v[82:85]
	v_mfma_f32_16x16x32_bf16 v[78:81], v[154:157], v[190:193], v[78:81]
	v_mfma_f32_16x16x32_bf16 v[74:77], v[162:165], v[190:193], v[74:77]
	v_mfma_f32_16x16x32_bf16 v[62:65], v[154:157], v[198:201], v[62:65]
	v_mfma_f32_16x16x32_bf16 v[58:61], v[162:165], v[198:201], v[58:61]
	v_mfma_f32_16x16x32_bf16 v[54:57], v[154:157], v[206:209], v[54:57]
	v_mfma_f32_16x16x32_bf16 v[50:53], v[162:165], v[206:209], v[50:53]
	s_barrier
	s_add_i32 s24, 0, 0x1c000
	s_add_i32 s25, s55, s35
	v_add_u32_e32 v149, s24, v146
	v_lshl_add_u64 v[144:145], v[144:145], 0, s[0:1]
	s_mov_b32 m0, s25
	ds_read_b128 v[210:213], v149
	ds_read_b128 v[214:217], v149 offset:1024
	ds_read_b128 v[218:221], v149 offset:2048
	ds_read_b128 v[222:225], v149 offset:3072
	global_load_lds_dwordx4 v[144:145], off
	v_lshl_add_u64 v[144:145], v[186:187], 0, s[0:1]
	s_add_i32 m0, s25, 0x2000
	s_nop 0
	global_load_lds_dwordx4 v[144:145], off
	s_barrier
	s_waitcnt lgkmcnt(0)
	s_waitcnt lgkmcnt(0)
	v_mfma_f32_16x16x32_bf16 v[126:129], v[210:213], v[166:169], v[126:129]
	v_mfma_f32_16x16x32_bf16 v[122:125], v[218:221], v[166:169], v[122:125]
	v_mfma_f32_16x16x32_bf16 v[118:121], v[210:213], v[174:177], v[118:121]
	v_mfma_f32_16x16x32_bf16 v[114:117], v[218:221], v[174:177], v[114:117]
	v_mfma_f32_16x16x32_bf16 v[110:113], v[210:213], v[194:197], v[110:113]
	v_mfma_f32_16x16x32_bf16 v[106:109], v[218:221], v[194:197], v[106:109]
	v_mfma_f32_16x16x32_bf16 v[102:105], v[210:213], v[202:205], v[102:105]
	v_mfma_f32_16x16x32_bf16 v[98:101], v[218:221], v[202:205], v[98:101]
	v_mfma_f32_16x16x32_bf16 v[126:129], v[214:217], v[170:173], v[126:129]
	v_mfma_f32_16x16x32_bf16 v[122:125], v[222:225], v[170:173], v[122:125]
	v_mfma_f32_16x16x32_bf16 v[118:121], v[214:217], v[190:193], v[118:121]
	v_mfma_f32_16x16x32_bf16 v[114:117], v[222:225], v[190:193], v[114:117]
	v_mfma_f32_16x16x32_bf16 v[110:113], v[214:217], v[198:201], v[110:113]
	v_mfma_f32_16x16x32_bf16 v[106:109], v[222:225], v[198:201], v[106:109]
	v_mfma_f32_16x16x32_bf16 v[102:105], v[214:217], v[206:209], v[102:105]
	v_mfma_f32_16x16x32_bf16 v[98:101], v[222:225], v[206:209], v[98:101]
	s_mov_b32 m0, s46
	v_lshl_add_u64 v[144:145], v[188:189], 0, s[0:1]
	s_barrier
	ds_read_b128 v[166:169], v148 offset:49152
	ds_read_b128 v[170:173], v148 offset:50176
	ds_read_b128 v[174:177], v148 offset:51200
	ds_read_b128 v[190:193], v148 offset:52224
	ds_read_b128 v[194:197], v148 offset:53248
	ds_read_b128 v[198:201], v148 offset:54272
	ds_read_b128 v[202:205], v148 offset:55296
	ds_read_b128 v[206:209], v148 offset:56320
	global_load_lds_dwordx4 v[144:145], off
	v_lshl_add_u64 v[144:145], v[226:227], 0, s[0:1]
	s_mov_b32 m0, s47
	s_nop 0
	global_load_lds_dwordx4 v[144:145], off
	s_barrier
	s_waitcnt lgkmcnt(0)
	s_waitcnt lgkmcnt(0)
	v_mfma_f32_16x16x32_bf16 v[34:37], v[150:153], v[166:169], v[34:37]
	v_mfma_f32_16x16x32_bf16 v[26:29], v[158:161], v[166:169], v[26:29]
	v_mfma_f32_16x16x32_bf16 v[22:25], v[150:153], v[174:177], v[22:25]
	v_mfma_f32_16x16x32_bf16 v[18:21], v[158:161], v[174:177], v[18:21]
	v_mfma_f32_16x16x32_bf16 v[14:17], v[150:153], v[194:197], v[14:17]
	v_mfma_f32_16x16x32_bf16 v[10:13], v[158:161], v[194:197], v[10:13]
	v_mfma_f32_16x16x32_bf16 v[6:9], v[150:153], v[202:205], v[6:9]
	v_mfma_f32_16x16x32_bf16 v[2:5], v[158:161], v[202:205], v[2:5]
	v_mfma_f32_16x16x32_bf16 v[34:37], v[154:157], v[170:173], v[34:37]
	v_mfma_f32_16x16x32_bf16 v[26:29], v[162:165], v[170:173], v[26:29]
	v_mfma_f32_16x16x32_bf16 v[22:25], v[154:157], v[190:193], v[22:25]
	v_mfma_f32_16x16x32_bf16 v[18:21], v[162:165], v[190:193], v[18:21]
	v_mfma_f32_16x16x32_bf16 v[14:17], v[154:157], v[198:201], v[14:17]
	v_mfma_f32_16x16x32_bf16 v[10:13], v[162:165], v[198:201], v[10:13]
	v_mfma_f32_16x16x32_bf16 v[6:9], v[154:157], v[206:209], v[6:9]
	v_mfma_f32_16x16x32_bf16 v[2:5], v[162:165], v[206:209], v[2:5]
	s_barrier
	s_add_u32 s22, s22, 0x40080
	s_addc_u32 s23, s23, 0
	s_add_i32 s24, s24, s35
	s_mov_b32 m0, s24
	s_nop 0
	global_load_lds_dwordx4 v134, s[22:23]
	v_lshl_add_u64 v[144:145], s[22:23], 0, v[130:131]
	s_add_i32 m0, s24, 0x2000
	s_nop 0
	global_load_lds_dwordx4 v[144:145], off
	s_waitcnt vmcnt(6)
	s_barrier
	v_mfma_f32_16x16x32_bf16 v[94:97], v[210:213], v[166:169], v[94:97]
	v_mfma_f32_16x16x32_bf16 v[90:93], v[218:221], v[166:169], v[90:93]
	v_mfma_f32_16x16x32_bf16 v[70:73], v[210:213], v[174:177], v[70:73]
	v_mfma_f32_16x16x32_bf16 v[66:69], v[218:221], v[174:177], v[66:69]
	v_mfma_f32_16x16x32_bf16 v[46:49], v[210:213], v[194:197], v[46:49]
	v_mfma_f32_16x16x32_bf16 v[42:45], v[218:221], v[194:197], v[42:45]
	v_mfma_f32_16x16x32_bf16 v[38:41], v[210:213], v[202:205], v[38:41]
	v_mfma_f32_16x16x32_bf16 v[30:33], v[218:221], v[202:205], v[30:33]
	v_mfma_f32_16x16x32_bf16 v[94:97], v[214:217], v[170:173], v[94:97]
	v_mfma_f32_16x16x32_bf16 v[90:93], v[222:225], v[170:173], v[90:93]
	v_mfma_f32_16x16x32_bf16 v[70:73], v[214:217], v[190:193], v[70:73]
	v_mfma_f32_16x16x32_bf16 v[66:69], v[222:225], v[190:193], v[66:69]
	v_mfma_f32_16x16x32_bf16 v[46:49], v[214:217], v[198:201], v[46:49]
	v_mfma_f32_16x16x32_bf16 v[42:45], v[222:225], v[198:201], v[42:45]
	v_mfma_f32_16x16x32_bf16 v[38:41], v[214:217], v[206:209], v[38:41]
	v_mfma_f32_16x16x32_bf16 v[30:33], v[222:225], v[206:209], v[30:33]
	s_add_i32 s54, s54, 2
	s_add_u32 s20, s20, 0x100
	s_addc_u32 s21, s21, 0
	s_add_u32 s52, s52, 0x100
	s_addc_u32 s53, s53, 0
	s_cmp_gt_u32 s54, 13
	s_barrier
	s_cbranch_scc0 .LBB0_528
	v_lshl_add_u32 v144, s10, 8, v1
	s_cmp_lg_u32 s50, s45
	s_mov_b64 s[10:11], -1
	s_cbranch_scc0 .LBB0_531
	v_lshl_or_b32 v154, s50, 8, v147
	v_readlane_b32 s13, v255, 32
	v_ashrrev_i32_e32 v155, 31, v154
	v_lshlrev_b64 v[154:155], 1, v[154:155]
	v_mad_i64_i32 v[156:157], s[10:11], v144, s13, 0
	v_lshl_add_u64 v[156:157], v[156:157], 1, s[6:7]
	v_lshl_add_u64 v[156:157], v[156:157], 0, v[154:155]
	v_cvt_pk_bf16_f32 v126, v126, v127
	v_cvt_pk_bf16_f32 v127, v128, v129
	v_cvt_pk_bf16_f32 v128, v122, v123
	v_cvt_pk_bf16_f32 v129, v124, v125
	global_store_dwordx4 v[156:157], v[126:129], off offset:256
	v_cvt_pk_bf16_f32 v150, v86, v87
	v_cvt_pk_bf16_f32 v151, v88, v89
	v_or_b32_e32 v126, 16, v144
	v_mad_i64_i32 v[126:127], s[10:11], v126, s13, 0
	v_lshl_add_u64 v[126:127], v[126:127], 1, s[6:7]
	v_cvt_pk_bf16_f32 v152, v82, v83
	v_cvt_pk_bf16_f32 v153, v84, v85
	v_lshl_add_u64 v[126:127], v[126:127], 0, v[154:155]
	v_cvt_pk_bf16_f32 v118, v118, v119
	v_cvt_pk_bf16_f32 v119, v120, v121
	v_cvt_pk_bf16_f32 v120, v114, v115
	v_cvt_pk_bf16_f32 v121, v116, v117
	global_store_dwordx4 v[156:157], v[150:153], off
	global_store_dwordx4 v[126:127], v[118:121], off offset:256
	v_cvt_pk_bf16_f32 v122, v78, v79
	v_cvt_pk_bf16_f32 v123, v80, v81
	v_or_b32_e32 v118, 32, v144
	v_mad_i64_i32 v[118:119], s[10:11], v118, s13, 0
	v_lshl_add_u64 v[118:119], v[118:119], 1, s[6:7]
	v_cvt_pk_bf16_f32 v124, v74, v75
	v_cvt_pk_bf16_f32 v125, v76, v77
	v_lshl_add_u64 v[118:119], v[118:119], 0, v[154:155]
	v_cvt_pk_bf16_f32 v110, v110, v111
	v_cvt_pk_bf16_f32 v111, v112, v113
	v_cvt_pk_bf16_f32 v112, v106, v107
	v_cvt_pk_bf16_f32 v113, v108, v109
	global_store_dwordx4 v[126:127], v[122:125], off
	global_store_dwordx4 v[118:119], v[110:113], off offset:256
	v_cvt_pk_bf16_f32 v114, v62, v63
	v_cvt_pk_bf16_f32 v115, v64, v65
	v_or_b32_e32 v110, 48, v144
	v_mad_i64_i32 v[110:111], s[10:11], v110, s13, 0
	v_lshl_add_u64 v[110:111], v[110:111], 1, s[6:7]
	v_cvt_pk_bf16_f32 v116, v58, v59
	v_cvt_pk_bf16_f32 v117, v60, v61
	v_lshl_add_u64 v[110:111], v[110:111], 0, v[154:155]
	v_cvt_pk_bf16_f32 v102, v102, v103
	v_cvt_pk_bf16_f32 v103, v104, v105
	v_cvt_pk_bf16_f32 v104, v98, v99
	v_cvt_pk_bf16_f32 v105, v100, v101
	global_store_dwordx4 v[118:119], v[114:117], off
	global_store_dwordx4 v[110:111], v[102:105], off offset:256
	v_cvt_pk_bf16_f32 v106, v54, v55
	v_cvt_pk_bf16_f32 v107, v56, v57
	v_add_u32_e32 v102, 0x80, v144
	v_mad_i64_i32 v[102:103], s[10:11], v102, s13, 0
	v_lshl_add_u64 v[102:103], v[102:103], 1, s[6:7]
	v_cvt_pk_bf16_f32 v108, v50, v51
	v_cvt_pk_bf16_f32 v109, v52, v53
	v_lshl_add_u64 v[102:103], v[102:103], 0, v[154:155]
	v_cvt_pk_bf16_f32 v94, v94, v95
	v_cvt_pk_bf16_f32 v95, v96, v97
	v_cvt_pk_bf16_f32 v96, v90, v91
	v_cvt_pk_bf16_f32 v97, v92, v93
	global_store_dwordx4 v[110:111], v[106:109], off
	global_store_dwordx4 v[102:103], v[94:97], off offset:256
	v_cvt_pk_bf16_f32 v98, v34, v35
	v_cvt_pk_bf16_f32 v99, v36, v37
	v_add_u32_e32 v94, 0x90, v144
	v_mad_i64_i32 v[94:95], s[10:11], v94, s13, 0
	v_lshl_add_u64 v[94:95], v[94:95], 1, s[6:7]
	v_cvt_pk_bf16_f32 v100, v26, v27
	v_cvt_pk_bf16_f32 v101, v28, v29
	v_lshl_add_u64 v[94:95], v[94:95], 0, v[154:155]
	v_cvt_pk_bf16_f32 v70, v70, v71
	v_cvt_pk_bf16_f32 v71, v72, v73
	v_cvt_pk_bf16_f32 v72, v66, v67
	v_cvt_pk_bf16_f32 v73, v68, v69
	global_store_dwordx4 v[102:103], v[98:101], off
	global_store_dwordx4 v[94:95], v[70:73], off offset:256
	v_cvt_pk_bf16_f32 v90, v22, v23
	v_cvt_pk_bf16_f32 v91, v24, v25
	v_add_u32_e32 v70, 0xa0, v144
	v_mad_i64_i32 v[70:71], s[10:11], v70, s13, 0
	v_lshl_add_u64 v[70:71], v[70:71], 1, s[6:7]
	v_cvt_pk_bf16_f32 v92, v18, v19
	v_cvt_pk_bf16_f32 v93, v20, v21
	v_lshl_add_u64 v[70:71], v[70:71], 0, v[154:155]
	v_cvt_pk_bf16_f32 v46, v46, v47
	v_cvt_pk_bf16_f32 v47, v48, v49
	v_cvt_pk_bf16_f32 v48, v42, v43
	v_cvt_pk_bf16_f32 v49, v44, v45
	global_store_dwordx4 v[94:95], v[90:93], off
	global_store_dwordx4 v[70:71], v[46:49], off offset:256
	v_cvt_pk_bf16_f32 v66, v14, v15
	v_cvt_pk_bf16_f32 v67, v16, v17
	v_add_u32_e32 v46, 0xb0, v144
	v_mad_i64_i32 v[46:47], s[10:11], v46, s13, 0
	v_lshl_add_u64 v[46:47], v[46:47], 1, s[6:7]
	v_cvt_pk_bf16_f32 v68, v10, v11
	v_cvt_pk_bf16_f32 v69, v12, v13
	v_cvt_pk_bf16_f32 v42, v6, v7
	v_cvt_pk_bf16_f32 v43, v8, v9
	v_cvt_pk_bf16_f32 v44, v2, v3
	v_cvt_pk_bf16_f32 v45, v4, v5
	v_lshl_add_u64 v[46:47], v[46:47], 0, v[154:155]
	v_cvt_pk_bf16_f32 v38, v38, v39
	v_cvt_pk_bf16_f32 v39, v40, v41
	v_cvt_pk_bf16_f32 v40, v30, v31
	v_cvt_pk_bf16_f32 v41, v32, v33
	global_store_dwordx4 v[70:71], v[66:69], off
	global_store_dwordx4 v[46:47], v[42:45], off
	global_store_dwordx4 v[46:47], v[38:41], off offset:256
	s_mov_b64 s[10:11], 0

.LBB0_1408:
	s_add_u32 s16, s14, s6
	s_addc_u32 s17, s15, s7
	s_add_u32 s16, s16, 0x100
	s_addc_u32 s17, s17, 0
	s_add_u32 s48, s45, s6
	s_addc_u32 s49, s46, s7
	s_add_i32 s50, 0, 0x10000
	v_add_u32_e32 v158, s50, v164
	ds_read_b128 v[146:149], v158
	ds_read_b128 v[150:153], v158 offset:1024
	ds_read_b128 v[154:157], v158 offset:2048
	ds_read_b128 v[158:161], v158 offset:3072
	s_cmpk_eq_i32 s6, 0xf00
	s_cselect_b32 s19, s11, s17
	s_cselect_b32 s18, s10, s16
	s_cselect_b32 s17, s3, s49
	s_cselect_b32 s16, s44, s48
	v_lshl_add_u64 v[162:163], v[142:143], 0, s[6:7]
	s_add_i32 m0, s30, 0xc000
	ds_read_b128 v[168:171], v166
	ds_read_b128 v[172:175], v166 offset:1024
	ds_read_b128 v[186:189], v166 offset:2048
	ds_read_b128 v[190:193], v166 offset:3072
	ds_read_b128 v[194:197], v166 offset:4096
	ds_read_b128 v[198:201], v166 offset:5120
	ds_read_b128 v[202:205], v166 offset:6144
	ds_read_b128 v[206:209], v166 offset:7168
	global_load_lds_dwordx4 v[162:163], off
	v_lshl_add_u64 v[162:163], v[144:145], 0, s[6:7]
	s_add_i32 m0, s30, 0xe000
	s_nop 0
	global_load_lds_dwordx4 v[162:163], off
	s_waitcnt lgkmcnt(8)
	s_barrier
	s_waitcnt lgkmcnt(0)
	s_waitcnt lgkmcnt(0)
	v_mfma_f32_16x16x32_bf16 v[126:129], v[146:149], v[168:171], v[126:129]
	v_mfma_f32_16x16x32_bf16 v[122:125], v[154:157], v[168:171], v[122:125]
	v_mfma_f32_16x16x32_bf16 v[110:113], v[146:149], v[186:189], v[110:113]
	v_mfma_f32_16x16x32_bf16 v[106:109], v[154:157], v[186:189], v[106:109]
	v_mfma_f32_16x16x32_bf16 v[94:97], v[146:149], v[194:197], v[94:97]
	v_mfma_f32_16x16x32_bf16 v[90:93], v[154:157], v[194:197], v[90:93]
	v_mfma_f32_16x16x32_bf16 v[78:81], v[146:149], v[202:205], v[78:81]
	v_mfma_f32_16x16x32_bf16 v[74:77], v[154:157], v[202:205], v[74:77]
	v_mfma_f32_16x16x32_bf16 v[126:129], v[150:153], v[172:175], v[126:129]
	v_mfma_f32_16x16x32_bf16 v[122:125], v[158:161], v[172:175], v[122:125]
	v_mfma_f32_16x16x32_bf16 v[110:113], v[150:153], v[190:193], v[110:113]
	v_mfma_f32_16x16x32_bf16 v[106:109], v[158:161], v[190:193], v[106:109]
	v_mfma_f32_16x16x32_bf16 v[94:97], v[150:153], v[198:201], v[94:97]
	v_mfma_f32_16x16x32_bf16 v[90:93], v[158:161], v[198:201], v[90:93]
	v_mfma_f32_16x16x32_bf16 v[78:81], v[150:153], v[206:209], v[78:81]
	v_mfma_f32_16x16x32_bf16 v[74:77], v[158:161], v[206:209], v[74:77]
	s_barrier
	s_add_i32 s51, 0, 0x14000
	v_add_u32_e32 v162, s51, v164
	s_add_i32 s48, s50, s29
	ds_read_b128 v[210:213], v162
	ds_read_b128 v[214:217], v162 offset:1024
	ds_read_b128 v[218:221], v162 offset:2048
	ds_read_b128 v[222:225], v162 offset:3072
	v_lshl_add_u64 v[162:163], s[16:17], 0, v[132:133]
	s_mov_b32 m0, s48
	v_lshl_add_u64 v[176:177], s[16:17], 0, v[136:137]
	global_load_lds_dwordx4 v[162:163], off
	s_add_i32 m0, s48, 0x2000
	s_nop 0
	global_load_lds_dwordx4 v[176:177], off
	s_barrier
	s_waitcnt lgkmcnt(0)
	s_waitcnt lgkmcnt(0)
	v_mfma_f32_16x16x32_bf16 v[118:121], v[210:213], v[168:171], v[118:121]
	v_mfma_f32_16x16x32_bf16 v[114:117], v[218:221], v[168:171], v[114:117]
	v_mfma_f32_16x16x32_bf16 v[102:105], v[210:213], v[186:189], v[102:105]
	v_mfma_f32_16x16x32_bf16 v[98:101], v[218:221], v[186:189], v[98:101]
	v_mfma_f32_16x16x32_bf16 v[86:89], v[210:213], v[194:197], v[86:89]
	v_mfma_f32_16x16x32_bf16 v[82:85], v[218:221], v[194:197], v[82:85]
	v_mfma_f32_16x16x32_bf16 v[70:73], v[210:213], v[202:205], v[70:73]
	v_mfma_f32_16x16x32_bf16 v[66:69], v[218:221], v[202:205], v[66:69]
	v_mfma_f32_16x16x32_bf16 v[118:121], v[214:217], v[172:175], v[118:121]
	v_mfma_f32_16x16x32_bf16 v[114:117], v[222:225], v[172:175], v[114:117]
	v_mfma_f32_16x16x32_bf16 v[102:105], v[214:217], v[190:193], v[102:105]
	v_mfma_f32_16x16x32_bf16 v[98:101], v[222:225], v[190:193], v[98:101]
	v_mfma_f32_16x16x32_bf16 v[86:89], v[214:217], v[198:201], v[86:89]
	v_mfma_f32_16x16x32_bf16 v[82:85], v[222:225], v[198:201], v[82:85]
	v_mfma_f32_16x16x32_bf16 v[70:73], v[214:217], v[206:209], v[70:73]
	v_mfma_f32_16x16x32_bf16 v[66:69], v[222:225], v[206:209], v[66:69]
	s_mov_b32 m0, s30
	v_lshl_add_u64 v[226:227], s[18:19], 0, v[130:131]
	s_barrier
	ds_read_b128 v[168:171], v166 offset:16384
	ds_read_b128 v[172:175], v166 offset:17408
	ds_read_b128 v[186:189], v166 offset:18432
	ds_read_b128 v[190:193], v166 offset:19456
	ds_read_b128 v[194:197], v166 offset:20480
	ds_read_b128 v[198:201], v166 offset:21504
	ds_read_b128 v[202:205], v166 offset:22528
	ds_read_b128 v[206:209], v166 offset:23552
	global_load_lds_dwordx4 v[226:227], off
	v_lshl_add_u64 v[228:229], s[18:19], 0, v[134:135]
	s_mov_b32 m0, s31
	s_nop 0
	global_load_lds_dwordx4 v[228:229], off
	s_barrier
	s_waitcnt lgkmcnt(0)
	s_waitcnt lgkmcnt(0)
	v_mfma_f32_16x16x32_bf16 v[62:65], v[146:149], v[168:171], v[62:65]
	v_mfma_f32_16x16x32_bf16 v[58:61], v[154:157], v[168:171], v[58:61]
	v_mfma_f32_16x16x32_bf16 v[46:49], v[146:149], v[186:189], v[46:49]
	v_mfma_f32_16x16x32_bf16 v[42:45], v[154:157], v[186:189], v[42:45]
	v_mfma_f32_16x16x32_bf16 v[30:33], v[146:149], v[194:197], v[30:33]
	v_mfma_f32_16x16x32_bf16 v[26:29], v[154:157], v[194:197], v[26:29]
	v_mfma_f32_16x16x32_bf16 v[14:17], v[146:149], v[202:205], v[14:17]
	v_mfma_f32_16x16x32_bf16 v[10:13], v[154:157], v[202:205], v[10:13]
	v_mfma_f32_16x16x32_bf16 v[62:65], v[150:153], v[172:175], v[62:65]
	v_mfma_f32_16x16x32_bf16 v[58:61], v[158:161], v[172:175], v[58:61]
	v_mfma_f32_16x16x32_bf16 v[46:49], v[150:153], v[190:193], v[46:49]
	v_mfma_f32_16x16x32_bf16 v[42:45], v[158:161], v[190:193], v[42:45]
	v_mfma_f32_16x16x32_bf16 v[30:33], v[150:153], v[198:201], v[30:33]
	v_mfma_f32_16x16x32_bf16 v[26:29], v[158:161], v[198:201], v[26:29]
	v_mfma_f32_16x16x32_bf16 v[14:17], v[150:153], v[206:209], v[14:17]
	v_mfma_f32_16x16x32_bf16 v[10:13], v[158:161], v[206:209], v[10:13]
	s_barrier
	s_add_u32 s48, s16, 0x80000
	s_addc_u32 s49, s17, 0
	s_add_i32 s50, s51, s29
	s_mov_b32 m0, s50
	s_nop 0
	global_load_lds_dwordx4 v132, s[48:49]
	s_add_i32 m0, s50, 0x2000
	s_nop 0
	global_load_lds_dwordx4 v136, s[48:49]
	s_waitcnt vmcnt(6)
	s_barrier
	v_mfma_f32_16x16x32_bf16 v[54:57], v[210:213], v[168:171], v[54:57]
	v_mfma_f32_16x16x32_bf16 v[50:53], v[218:221], v[168:171], v[50:53]
	v_mfma_f32_16x16x32_bf16 v[38:41], v[210:213], v[186:189], v[38:41]
	v_mfma_f32_16x16x32_bf16 v[34:37], v[218:221], v[186:189], v[34:37]
	v_mfma_f32_16x16x32_bf16 v[22:25], v[210:213], v[194:197], v[22:25]
	v_mfma_f32_16x16x32_bf16 v[18:21], v[218:221], v[194:197], v[18:21]
	v_mfma_f32_16x16x32_bf16 v[6:9], v[210:213], v[202:205], v[6:9]
	v_mfma_f32_16x16x32_bf16 v[2:5], v[218:221], v[202:205], v[2:5]
	v_mfma_f32_16x16x32_bf16 v[54:57], v[214:217], v[172:175], v[54:57]
	v_mfma_f32_16x16x32_bf16 v[50:53], v[222:225], v[172:175], v[50:53]
	v_mfma_f32_16x16x32_bf16 v[38:41], v[214:217], v[190:193], v[38:41]
	v_mfma_f32_16x16x32_bf16 v[34:37], v[222:225], v[190:193], v[34:37]
	v_mfma_f32_16x16x32_bf16 v[22:25], v[214:217], v[198:201], v[22:25]
	v_mfma_f32_16x16x32_bf16 v[18:21], v[222:225], v[198:201], v[18:21]
	v_mfma_f32_16x16x32_bf16 v[6:9], v[214:217], v[206:209], v[6:9]
	v_mfma_f32_16x16x32_bf16 v[2:5], v[222:225], v[206:209], v[2:5]
	s_add_i32 s48, 0, 0x18000
	v_add_u32_e32 v158, s48, v164
	s_barrier
	ds_read_b128 v[146:149], v158
	ds_read_b128 v[150:153], v158 offset:1024
	ds_read_b128 v[154:157], v158 offset:2048
	ds_read_b128 v[158:161], v158 offset:3072
	s_add_u32 s18, s18, s80
	s_addc_u32 s19, s19, 0
	s_mov_b32 m0, s34
	ds_read_b128 v[168:171], v166 offset:32768
	ds_read_b128 v[172:175], v166 offset:33792
	ds_read_b128 v[186:189], v166 offset:34816
	ds_read_b128 v[190:193], v166 offset:35840
	ds_read_b128 v[194:197], v166 offset:36864
	ds_read_b128 v[198:201], v166 offset:37888
	ds_read_b128 v[202:205], v166 offset:38912
	ds_read_b128 v[206:209], v166 offset:39936
	global_load_lds_dwordx4 v130, s[18:19]
	s_mov_b32 m0, s35
	s_nop 0
	global_load_lds_dwordx4 v134, s[18:19]
	s_waitcnt lgkmcnt(8)
	s_barrier
	s_waitcnt lgkmcnt(0)
	s_waitcnt lgkmcnt(0)
	v_mfma_f32_16x16x32_bf16 v[126:129], v[146:149], v[168:171], v[126:129]
	v_mfma_f32_16x16x32_bf16 v[122:125], v[154:157], v[168:171], v[122:125]
	v_mfma_f32_16x16x32_bf16 v[110:113], v[146:149], v[186:189], v[110:113]
	v_mfma_f32_16x16x32_bf16 v[106:109], v[154:157], v[186:189], v[106:109]
	v_mfma_f32_16x16x32_bf16 v[94:97], v[146:149], v[194:197], v[94:97]
	v_mfma_f32_16x16x32_bf16 v[90:93], v[154:157], v[194:197], v[90:93]
	v_mfma_f32_16x16x32_bf16 v[78:81], v[146:149], v[202:205], v[78:81]
	v_mfma_f32_16x16x32_bf16 v[74:77], v[154:157], v[202:205], v[74:77]
	v_mfma_f32_16x16x32_bf16 v[126:129], v[150:153], v[172:175], v[126:129]
	v_mfma_f32_16x16x32_bf16 v[122:125], v[158:161], v[172:175], v[122:125]
	v_mfma_f32_16x16x32_bf16 v[110:113], v[150:153], v[190:193], v[110:113]
	v_mfma_f32_16x16x32_bf16 v[106:109], v[158:161], v[190:193], v[106:109]
	v_mfma_f32_16x16x32_bf16 v[94:97], v[150:153], v[198:201], v[94:97]
	v_mfma_f32_16x16x32_bf16 v[90:93], v[158:161], v[198:201], v[90:93]
	v_mfma_f32_16x16x32_bf16 v[78:81], v[150:153], v[206:209], v[78:81]
	v_mfma_f32_16x16x32_bf16 v[74:77], v[158:161], v[206:209], v[74:77]
	s_barrier
	s_add_i32 s18, 0, 0x1c000
	s_add_i32 s19, s48, s29
	v_add_u32_e32 v167, s18, v164
	v_lshl_add_u64 v[162:163], v[162:163], 0, s[0:1]
	s_mov_b32 m0, s19
	ds_read_b128 v[210:213], v167
	ds_read_b128 v[214:217], v167 offset:1024
	ds_read_b128 v[218:221], v167 offset:2048
	ds_read_b128 v[222:225], v167 offset:3072
	global_load_lds_dwordx4 v[162:163], off
	v_lshl_add_u64 v[162:163], v[176:177], 0, s[0:1]
	s_add_i32 m0, s19, 0x2000
	s_nop 0
	global_load_lds_dwordx4 v[162:163], off
	s_barrier
	s_waitcnt lgkmcnt(0)
	s_waitcnt lgkmcnt(0)
	v_mfma_f32_16x16x32_bf16 v[118:121], v[210:213], v[168:171], v[118:121]
	v_mfma_f32_16x16x32_bf16 v[114:117], v[218:221], v[168:171], v[114:117]
	v_mfma_f32_16x16x32_bf16 v[102:105], v[210:213], v[186:189], v[102:105]
	v_mfma_f32_16x16x32_bf16 v[98:101], v[218:221], v[186:189], v[98:101]
	v_mfma_f32_16x16x32_bf16 v[86:89], v[210:213], v[194:197], v[86:89]
	v_mfma_f32_16x16x32_bf16 v[82:85], v[218:221], v[194:197], v[82:85]
	v_mfma_f32_16x16x32_bf16 v[70:73], v[210:213], v[202:205], v[70:73]
	v_mfma_f32_16x16x32_bf16 v[66:69], v[218:221], v[202:205], v[66:69]
	v_mfma_f32_16x16x32_bf16 v[118:121], v[214:217], v[172:175], v[118:121]
	v_mfma_f32_16x16x32_bf16 v[114:117], v[222:225], v[172:175], v[114:117]
	v_mfma_f32_16x16x32_bf16 v[102:105], v[214:217], v[190:193], v[102:105]
	v_mfma_f32_16x16x32_bf16 v[98:101], v[222:225], v[190:193], v[98:101]
	v_mfma_f32_16x16x32_bf16 v[86:89], v[214:217], v[198:201], v[86:89]
	v_mfma_f32_16x16x32_bf16 v[82:85], v[222:225], v[198:201], v[82:85]
	v_mfma_f32_16x16x32_bf16 v[70:73], v[214:217], v[206:209], v[70:73]
	v_mfma_f32_16x16x32_bf16 v[66:69], v[222:225], v[206:209], v[66:69]
	s_mov_b32 m0, s38
	v_lshl_add_u64 v[162:163], v[226:227], 0, s[0:1]
	s_barrier
	ds_read_b128 v[168:171], v166 offset:49152
	ds_read_b128 v[172:175], v166 offset:50176
	ds_read_b128 v[186:189], v166 offset:51200
	ds_read_b128 v[190:193], v166 offset:52224
	ds_read_b128 v[194:197], v166 offset:53248
	ds_read_b128 v[198:201], v166 offset:54272
	ds_read_b128 v[202:205], v166 offset:55296
	ds_read_b128 v[206:209], v166 offset:56320
	global_load_lds_dwordx4 v[162:163], off
	v_lshl_add_u64 v[162:163], v[228:229], 0, s[0:1]
	s_mov_b32 m0, s39
	s_nop 0
	global_load_lds_dwordx4 v[162:163], off
	s_barrier
	s_waitcnt lgkmcnt(0)
	s_waitcnt lgkmcnt(0)
	v_mfma_f32_16x16x32_bf16 v[62:65], v[146:149], v[168:171], v[62:65]
	v_mfma_f32_16x16x32_bf16 v[58:61], v[154:157], v[168:171], v[58:61]
	v_mfma_f32_16x16x32_bf16 v[46:49], v[146:149], v[186:189], v[46:49]
	v_mfma_f32_16x16x32_bf16 v[42:45], v[154:157], v[186:189], v[42:45]
	v_mfma_f32_16x16x32_bf16 v[30:33], v[146:149], v[194:197], v[30:33]
	v_mfma_f32_16x16x32_bf16 v[26:29], v[154:157], v[194:197], v[26:29]
	v_mfma_f32_16x16x32_bf16 v[14:17], v[146:149], v[202:205], v[14:17]
	v_mfma_f32_16x16x32_bf16 v[10:13], v[154:157], v[202:205], v[10:13]
	v_mfma_f32_16x16x32_bf16 v[62:65], v[150:153], v[172:175], v[62:65]
	v_mfma_f32_16x16x32_bf16 v[58:61], v[158:161], v[172:175], v[58:61]
	v_mfma_f32_16x16x32_bf16 v[46:49], v[150:153], v[190:193], v[46:49]
	v_mfma_f32_16x16x32_bf16 v[42:45], v[158:161], v[190:193], v[42:45]
	v_mfma_f32_16x16x32_bf16 v[30:33], v[150:153], v[198:201], v[30:33]
	v_mfma_f32_16x16x32_bf16 v[26:29], v[158:161], v[198:201], v[26:29]
	v_mfma_f32_16x16x32_bf16 v[14:17], v[150:153], v[206:209], v[14:17]
	v_mfma_f32_16x16x32_bf16 v[10:13], v[158:161], v[206:209], v[10:13]
	s_barrier
	s_add_u32 s16, s16, 0x80080
	s_addc_u32 s17, s17, 0
	s_add_i32 s18, s18, s29
	s_mov_b32 m0, s18
	s_nop 0
	global_load_lds_dwordx4 v132, s[16:17]
	s_add_i32 m0, s18, 0x2000
	s_nop 0
	global_load_lds_dwordx4 v136, s[16:17]
	s_waitcnt vmcnt(6)
	s_barrier
	v_mfma_f32_16x16x32_bf16 v[54:57], v[210:213], v[168:171], v[54:57]
	v_mfma_f32_16x16x32_bf16 v[50:53], v[218:221], v[168:171], v[50:53]
	v_mfma_f32_16x16x32_bf16 v[38:41], v[210:213], v[186:189], v[38:41]
	v_mfma_f32_16x16x32_bf16 v[34:37], v[218:221], v[186:189], v[34:37]
	v_mfma_f32_16x16x32_bf16 v[22:25], v[210:213], v[194:197], v[22:25]
	v_mfma_f32_16x16x32_bf16 v[18:21], v[218:221], v[194:197], v[18:21]
	v_mfma_f32_16x16x32_bf16 v[6:9], v[210:213], v[202:205], v[6:9]
	v_mfma_f32_16x16x32_bf16 v[2:5], v[218:221], v[202:205], v[2:5]
	v_mfma_f32_16x16x32_bf16 v[54:57], v[214:217], v[172:175], v[54:57]
	v_mfma_f32_16x16x32_bf16 v[50:53], v[222:225], v[172:175], v[50:53]
	v_mfma_f32_16x16x32_bf16 v[38:41], v[214:217], v[190:193], v[38:41]
	v_mfma_f32_16x16x32_bf16 v[34:37], v[222:225], v[190:193], v[34:37]
	v_mfma_f32_16x16x32_bf16 v[22:25], v[214:217], v[198:201], v[22:25]
	v_mfma_f32_16x16x32_bf16 v[18:21], v[222:225], v[198:201], v[18:21]
	v_mfma_f32_16x16x32_bf16 v[6:9], v[214:217], v[206:209], v[6:9]
	v_mfma_f32_16x16x32_bf16 v[2:5], v[222:225], v[206:209], v[2:5]
	s_add_i32 s47, s47, 2
	s_add_u32 s6, s6, 0x100
	s_addc_u32 s7, s7, 0
	s_cmp_gt_u32 s47, 29
	s_barrier
	s_cbranch_scc0 .LBB0_1408
	s_ashr_i32 s3, s33, 5
	s_mul_hi_i32 s7, s3, 0x9000
	s_mul_i32 s3, s3, 0x9000
	v_lshl_or_b32 v168, s43, 8, v165
	s_add_u32 s6, s36, s3
	s_addc_u32 s7, s37, s7
	v_ashrrev_i32_e32 v169, 31, v168
	v_lshl_add_u64 v[162:163], v[168:169], 2, s[6:7]
	global_load_dwordx4 v[142:145], v[162:163], off offset:16
	global_load_dwordx4 v[146:149], v[162:163], off
	s_mov_b64 s[6:7], 0x80000
	s_and_b64 vcc, exec, s[4:5]
	s_mov_b32 s43, s2
	s_mov_b64 s[16:17], s[12:13]
	s_mov_b64 s[14:15], s[10:11]
	s_waitcnt vmcnt(0)
	v_pk_add_f32 v[150:151], v[144:145], 1.0 op_sel_hi:[1,0]
	v_pk_add_f32 v[154:155], v[142:143], 1.0 op_sel_hi:[1,0]
	global_load_dwordx4 v[158:161], v[162:163], off offset:528
	global_load_dwordx4 v[142:145], v[162:163], off offset:512
	v_lshl_add_u32 v162, s33, 8, v1
	v_ashrrev_i32_e32 v163, 31, v162
	v_pk_add_f32 v[156:157], v[146:147], 1.0 op_sel_hi:[1,0]
	v_pk_add_f32 v[152:153], v[148:149], 1.0 op_sel_hi:[1,0]
	s_mov_b32 s33, s42
	s_waitcnt vmcnt(0)
	v_pk_add_f32 v[146:147], v[144:145], 1.0 op_sel_hi:[1,0]
	v_pk_add_f32 v[144:145], v[158:159], 1.0 op_sel_hi:[1,0]
	v_lshlrev_b64 v[158:159], 12, v[162:163]
	v_pk_add_f32 v[148:149], v[142:143], 1.0 op_sel_hi:[1,0]
	v_pk_add_f32 v[142:143], v[160:161], 1.0 op_sel_hi:[1,0]
	v_lshl_add_u64 v[158:159], s[8:9], 0, v[158:159]
	v_lshlrev_b64 v[160:161], 1, v[168:169]
	v_lshl_add_u64 v[158:159], v[158:159], 0, v[160:161]
	global_load_dwordx4 v[168:171], v[158:159], off offset:2048
	s_waitcnt vmcnt(0)
	v_lshlrev_b32_e32 v172, 16, v168
	v_and_b32_e32 v173, 0xffff0000, v168
	v_lshlrev_b32_e32 v168, 16, v169
	v_and_b32_e32 v169, 0xffff0000, v169
	v_pk_fma_f32 v[128:129], v[128:129], v[152:153], v[168:169]
	v_lshlrev_b32_e32 v168, 16, v170
	v_and_b32_e32 v169, 0xffff0000, v170
	v_pk_fma_f32 v[168:169], v[122:123], v[154:155], v[168:169]
	v_lshlrev_b32_e32 v122, 16, v171
	v_and_b32_e32 v123, 0xffff0000, v171
	v_pk_fma_f32 v[126:127], v[126:127], v[156:157], v[172:173]
	v_pk_fma_f32 v[170:171], v[124:125], v[150:151], v[122:123]
	v_cvt_pk_bf16_f32 v122, v126, v127
	v_cvt_pk_bf16_f32 v123, v128, v129
	v_cvt_pk_bf16_f32 v124, v168, v169
	v_cvt_pk_bf16_f32 v125, v170, v171
	global_store_dwordx4 v[158:159], v[122:125], off offset:2048
	global_load_dwordx4 v[122:125], v[158:159], off offset:2304
	s_waitcnt vmcnt(0)
	v_lshlrev_b32_e32 v126, 16, v122
	v_and_b32_e32 v127, 0xffff0000, v122
	v_lshlrev_b32_e32 v122, 16, v123
	v_and_b32_e32 v123, 0xffff0000, v123
	v_pk_fma_f32 v[120:121], v[120:121], v[146:147], v[122:123]
	v_lshlrev_b32_e32 v122, 16, v124
	v_and_b32_e32 v123, 0xffff0000, v124
	v_pk_fma_f32 v[122:123], v[114:115], v[144:145], v[122:123]
	v_lshlrev_b32_e32 v114, 16, v125
	v_and_b32_e32 v115, 0xffff0000, v125
	v_pk_fma_f32 v[118:119], v[118:119], v[148:149], v[126:127]
	v_pk_fma_f32 v[124:125], v[116:117], v[142:143], v[114:115]
	v_cvt_pk_bf16_f32 v114, v118, v119
	v_cvt_pk_bf16_f32 v115, v120, v121
	v_cvt_pk_bf16_f32 v116, v122, v123
	v_cvt_pk_bf16_f32 v117, v124, v125
	global_store_dwordx4 v[158:159], v[114:117], off offset:2304
	s_nop 1
	v_or_b32_e32 v114, 16, v162
	v_ashrrev_i32_e32 v115, 31, v114
	v_lshlrev_b64 v[114:115], 12, v[114:115]
	v_lshl_add_u64 v[114:115], s[8:9], 0, v[114:115]
	v_lshl_add_u64 v[118:119], v[114:115], 0, v[160:161]
	global_load_dwordx4 v[114:117], v[118:119], off offset:2048
	s_waitcnt vmcnt(0)
	v_lshlrev_b32_e32 v120, 16, v114
	v_and_b32_e32 v121, 0xffff0000, v114
	v_lshlrev_b32_e32 v114, 16, v115
	v_and_b32_e32 v115, 0xffff0000, v115
	v_pk_fma_f32 v[112:113], v[112:113], v[152:153], v[114:115]
	v_lshlrev_b32_e32 v114, 16, v116
	v_and_b32_e32 v115, 0xffff0000, v116
	v_pk_fma_f32 v[114:115], v[106:107], v[154:155], v[114:115]
	v_lshlrev_b32_e32 v106, 16, v117
	v_and_b32_e32 v107, 0xffff0000, v117
	v_pk_fma_f32 v[110:111], v[110:111], v[156:157], v[120:121]
	v_pk_fma_f32 v[116:117], v[108:109], v[150:151], v[106:107]
	v_cvt_pk_bf16_f32 v106, v110, v111
	v_cvt_pk_bf16_f32 v107, v112, v113
	v_cvt_pk_bf16_f32 v108, v114, v115
	v_cvt_pk_bf16_f32 v109, v116, v117
	global_store_dwordx4 v[118:119], v[106:109], off offset:2048
	global_load_dwordx4 v[106:109], v[118:119], off offset:2304
	s_waitcnt vmcnt(0)
	v_lshlrev_b32_e32 v110, 16, v106
	v_and_b32_e32 v111, 0xffff0000, v106
	v_lshlrev_b32_e32 v106, 16, v107
	v_and_b32_e32 v107, 0xffff0000, v107
	v_pk_fma_f32 v[104:105], v[104:105], v[146:147], v[106:107]
	v_lshlrev_b32_e32 v106, 16, v108
	v_and_b32_e32 v107, 0xffff0000, v108
	v_pk_fma_f32 v[106:107], v[98:99], v[144:145], v[106:107]
	v_lshlrev_b32_e32 v98, 16, v109
	v_and_b32_e32 v99, 0xffff0000, v109
	v_pk_fma_f32 v[102:103], v[102:103], v[148:149], v[110:111]
	v_pk_fma_f32 v[108:109], v[100:101], v[142:143], v[98:99]
	v_cvt_pk_bf16_f32 v98, v102, v103
	v_cvt_pk_bf16_f32 v99, v104, v105
	v_cvt_pk_bf16_f32 v100, v106, v107
	v_cvt_pk_bf16_f32 v101, v108, v109
	global_store_dwordx4 v[118:119], v[98:101], off offset:2304
	s_nop 1
	v_or_b32_e32 v98, 32, v162
	v_ashrrev_i32_e32 v99, 31, v98
	v_lshlrev_b64 v[98:99], 12, v[98:99]
	v_lshl_add_u64 v[98:99], s[8:9], 0, v[98:99]
	v_lshl_add_u64 v[102:103], v[98:99], 0, v[160:161]
	global_load_dwordx4 v[98:101], v[102:103], off offset:2048
	s_waitcnt vmcnt(0)
	v_lshlrev_b32_e32 v104, 16, v98
	v_and_b32_e32 v105, 0xffff0000, v98
	v_lshlrev_b32_e32 v98, 16, v99
	v_and_b32_e32 v99, 0xffff0000, v99
	v_pk_fma_f32 v[96:97], v[96:97], v[152:153], v[98:99]
	v_lshlrev_b32_e32 v98, 16, v100
	v_and_b32_e32 v99, 0xffff0000, v100
	v_pk_fma_f32 v[98:99], v[90:91], v[154:155], v[98:99]
	v_lshlrev_b32_e32 v90, 16, v101
	v_and_b32_e32 v91, 0xffff0000, v101
	v_pk_fma_f32 v[94:95], v[94:95], v[156:157], v[104:105]
	v_pk_fma_f32 v[100:101], v[92:93], v[150:151], v[90:91]
	v_cvt_pk_bf16_f32 v90, v94, v95
	v_cvt_pk_bf16_f32 v91, v96, v97
	v_cvt_pk_bf16_f32 v92, v98, v99
	v_cvt_pk_bf16_f32 v93, v100, v101
	global_store_dwordx4 v[102:103], v[90:93], off offset:2048
	global_load_dwordx4 v[90:93], v[102:103], off offset:2304
	s_waitcnt vmcnt(0)
	v_lshlrev_b32_e32 v94, 16, v90
	v_and_b32_e32 v95, 0xffff0000, v90
	v_lshlrev_b32_e32 v90, 16, v91
	v_and_b32_e32 v91, 0xffff0000, v91
	v_pk_fma_f32 v[88:89], v[88:89], v[146:147], v[90:91]
	v_lshlrev_b32_e32 v90, 16, v92
	v_and_b32_e32 v91, 0xffff0000, v92
	v_pk_fma_f32 v[90:91], v[82:83], v[144:145], v[90:91]
	v_lshlrev_b32_e32 v82, 16, v93
	v_and_b32_e32 v83, 0xffff0000, v93
	v_pk_fma_f32 v[86:87], v[86:87], v[148:149], v[94:95]
	v_pk_fma_f32 v[92:93], v[84:85], v[142:143], v[82:83]
	v_cvt_pk_bf16_f32 v82, v86, v87
	v_cvt_pk_bf16_f32 v83, v88, v89
	v_cvt_pk_bf16_f32 v84, v90, v91
	v_cvt_pk_bf16_f32 v85, v92, v93
	global_store_dwordx4 v[102:103], v[82:85], off offset:2304
	s_nop 1
	v_or_b32_e32 v82, 48, v162
	v_ashrrev_i32_e32 v83, 31, v82
	v_lshlrev_b64 v[82:83], 12, v[82:83]
	v_lshl_add_u64 v[82:83], s[8:9], 0, v[82:83]
	v_lshl_add_u64 v[82:83], v[82:83], 0, v[160:161]
	global_load_dwordx4 v[84:87], v[82:83], off offset:2048
	s_waitcnt vmcnt(0)
	v_lshlrev_b32_e32 v88, 16, v84
	v_and_b32_e32 v89, 0xffff0000, v84
	v_lshlrev_b32_e32 v84, 16, v85
	v_and_b32_e32 v85, 0xffff0000, v85
	v_pk_fma_f32 v[80:81], v[80:81], v[152:153], v[84:85]
	v_lshlrev_b32_e32 v84, 16, v86
	v_and_b32_e32 v85, 0xffff0000, v86
	v_pk_fma_f32 v[84:85], v[74:75], v[154:155], v[84:85]
	v_lshlrev_b32_e32 v74, 16, v87
	v_and_b32_e32 v75, 0xffff0000, v87
	v_pk_fma_f32 v[78:79], v[78:79], v[156:157], v[88:89]
	v_pk_fma_f32 v[86:87], v[76:77], v[150:151], v[74:75]
	v_cvt_pk_bf16_f32 v74, v78, v79
	v_cvt_pk_bf16_f32 v75, v80, v81
	v_cvt_pk_bf16_f32 v76, v84, v85
	v_cvt_pk_bf16_f32 v77, v86, v87
	global_store_dwordx4 v[82:83], v[74:77], off offset:2048
	global_load_dwordx4 v[74:77], v[82:83], off offset:2304
	s_waitcnt vmcnt(0)
	v_lshlrev_b32_e32 v78, 16, v74
	v_and_b32_e32 v79, 0xffff0000, v74
	v_lshlrev_b32_e32 v74, 16, v75
	v_and_b32_e32 v75, 0xffff0000, v75
	v_pk_fma_f32 v[72:73], v[72:73], v[146:147], v[74:75]
	v_lshlrev_b32_e32 v74, 16, v76
	v_and_b32_e32 v75, 0xffff0000, v76
	v_pk_fma_f32 v[74:75], v[66:67], v[144:145], v[74:75]
	v_lshlrev_b32_e32 v66, 16, v77
	v_and_b32_e32 v67, 0xffff0000, v77
	v_pk_fma_f32 v[70:71], v[70:71], v[148:149], v[78:79]
	v_pk_fma_f32 v[76:77], v[68:69], v[142:143], v[66:67]
	v_cvt_pk_bf16_f32 v66, v70, v71
	v_cvt_pk_bf16_f32 v67, v72, v73
	v_cvt_pk_bf16_f32 v68, v74, v75
	v_cvt_pk_bf16_f32 v69, v76, v77
	v_lshl_add_u64 v[70:71], v[158:159], 0, s[6:7]
	global_store_dwordx4 v[82:83], v[66:69], off offset:2304
	global_load_dwordx4 v[66:69], v[70:71], off offset:2048
	s_mov_b64 s[6:7], 0x90000
	s_waitcnt vmcnt(0)
	v_lshlrev_b32_e32 v72, 16, v66
	v_and_b32_e32 v73, 0xffff0000, v66
	v_lshlrev_b32_e32 v66, 16, v67
	v_and_b32_e32 v67, 0xffff0000, v67
	v_pk_fma_f32 v[64:65], v[64:65], v[152:153], v[66:67]
	v_lshlrev_b32_e32 v66, 16, v68
	v_and_b32_e32 v67, 0xffff0000, v68
	v_pk_fma_f32 v[66:67], v[58:59], v[154:155], v[66:67]
	v_lshlrev_b32_e32 v58, 16, v69
	v_and_b32_e32 v59, 0xffff0000, v69
	v_pk_fma_f32 v[62:63], v[62:63], v[156:157], v[72:73]
	v_pk_fma_f32 v[68:69], v[60:61], v[150:151], v[58:59]
	v_cvt_pk_bf16_f32 v58, v62, v63
	v_cvt_pk_bf16_f32 v59, v64, v65
	v_cvt_pk_bf16_f32 v60, v66, v67
	v_cvt_pk_bf16_f32 v61, v68, v69
	global_store_dwordx4 v[70:71], v[58:61], off offset:2048
	global_load_dwordx4 v[58:61], v[70:71], off offset:2304
	s_waitcnt vmcnt(0)
	v_lshlrev_b32_e32 v62, 16, v58
	v_and_b32_e32 v63, 0xffff0000, v58
	v_lshlrev_b32_e32 v58, 16, v59
	v_and_b32_e32 v59, 0xffff0000, v59
	v_pk_fma_f32 v[56:57], v[56:57], v[146:147], v[58:59]
	v_lshlrev_b32_e32 v58, 16, v60
	v_and_b32_e32 v59, 0xffff0000, v60
	v_pk_fma_f32 v[58:59], v[50:51], v[144:145], v[58:59]
	v_lshlrev_b32_e32 v50, 16, v61
	v_and_b32_e32 v51, 0xffff0000, v61
	v_pk_fma_f32 v[54:55], v[54:55], v[148:149], v[62:63]
	v_pk_fma_f32 v[60:61], v[52:53], v[142:143], v[50:51]
	v_cvt_pk_bf16_f32 v50, v54, v55
	v_cvt_pk_bf16_f32 v51, v56, v57
	v_cvt_pk_bf16_f32 v52, v58, v59
	v_cvt_pk_bf16_f32 v53, v60, v61
	v_lshl_add_u64 v[54:55], v[158:159], 0, s[6:7]
	global_store_dwordx4 v[70:71], v[50:53], off offset:2304
	global_load_dwordx4 v[50:53], v[54:55], off offset:2048
	s_mov_b64 s[6:7], 0xa0000
	s_waitcnt vmcnt(0)
	v_lshlrev_b32_e32 v56, 16, v50
	v_and_b32_e32 v57, 0xffff0000, v50
	v_lshlrev_b32_e32 v50, 16, v51
	v_and_b32_e32 v51, 0xffff0000, v51
	v_pk_fma_f32 v[48:49], v[48:49], v[152:153], v[50:51]
	v_lshlrev_b32_e32 v50, 16, v52
	v_and_b32_e32 v51, 0xffff0000, v52
	v_pk_fma_f32 v[50:51], v[42:43], v[154:155], v[50:51]
	v_lshlrev_b32_e32 v42, 16, v53
	v_and_b32_e32 v43, 0xffff0000, v53
	v_pk_fma_f32 v[46:47], v[46:47], v[156:157], v[56:57]
	v_pk_fma_f32 v[52:53], v[44:45], v[150:151], v[42:43]
	v_cvt_pk_bf16_f32 v42, v46, v47
	v_cvt_pk_bf16_f32 v43, v48, v49
	v_cvt_pk_bf16_f32 v44, v50, v51
	v_cvt_pk_bf16_f32 v45, v52, v53
	global_store_dwordx4 v[54:55], v[42:45], off offset:2048
	global_load_dwordx4 v[42:45], v[54:55], off offset:2304
	s_waitcnt vmcnt(0)
	v_lshlrev_b32_e32 v46, 16, v42
	v_and_b32_e32 v47, 0xffff0000, v42
	v_lshlrev_b32_e32 v42, 16, v43
	v_and_b32_e32 v43, 0xffff0000, v43
	v_pk_fma_f32 v[40:41], v[40:41], v[146:147], v[42:43]
	v_lshlrev_b32_e32 v42, 16, v44
	v_and_b32_e32 v43, 0xffff0000, v44
	v_pk_fma_f32 v[42:43], v[34:35], v[144:145], v[42:43]
	v_lshlrev_b32_e32 v34, 16, v45
	v_and_b32_e32 v35, 0xffff0000, v45
	v_pk_fma_f32 v[38:39], v[38:39], v[148:149], v[46:47]
	v_pk_fma_f32 v[44:45], v[36:37], v[142:143], v[34:35]
	v_cvt_pk_bf16_f32 v34, v38, v39
	v_cvt_pk_bf16_f32 v35, v40, v41
	v_cvt_pk_bf16_f32 v36, v42, v43
	v_cvt_pk_bf16_f32 v37, v44, v45
	v_lshl_add_u64 v[38:39], v[158:159], 0, s[6:7]
	global_store_dwordx4 v[54:55], v[34:37], off offset:2304
	global_load_dwordx4 v[34:37], v[38:39], off offset:2048
	s_mov_b64 s[6:7], 0xb0000
	s_waitcnt vmcnt(0)
	v_lshlrev_b32_e32 v40, 16, v34
	v_and_b32_e32 v41, 0xffff0000, v34
	v_lshlrev_b32_e32 v34, 16, v35
	v_and_b32_e32 v35, 0xffff0000, v35
	v_pk_fma_f32 v[32:33], v[32:33], v[152:153], v[34:35]
	v_lshlrev_b32_e32 v34, 16, v36
	v_and_b32_e32 v35, 0xffff0000, v36
	v_pk_fma_f32 v[34:35], v[26:27], v[154:155], v[34:35]
	v_lshlrev_b32_e32 v26, 16, v37
	v_and_b32_e32 v27, 0xffff0000, v37
	v_pk_fma_f32 v[30:31], v[30:31], v[156:157], v[40:41]
	v_pk_fma_f32 v[36:37], v[28:29], v[150:151], v[26:27]
	v_cvt_pk_bf16_f32 v26, v30, v31
	v_cvt_pk_bf16_f32 v27, v32, v33
	v_cvt_pk_bf16_f32 v28, v34, v35
	v_cvt_pk_bf16_f32 v29, v36, v37
	global_store_dwordx4 v[38:39], v[26:29], off offset:2048
	global_load_dwordx4 v[26:29], v[38:39], off offset:2304
	s_waitcnt vmcnt(0)
	v_lshlrev_b32_e32 v30, 16, v26
	v_and_b32_e32 v31, 0xffff0000, v26
	v_lshlrev_b32_e32 v26, 16, v27
	v_and_b32_e32 v27, 0xffff0000, v27
	v_pk_fma_f32 v[24:25], v[24:25], v[146:147], v[26:27]
	v_lshlrev_b32_e32 v26, 16, v28
	v_and_b32_e32 v27, 0xffff0000, v28
	v_pk_fma_f32 v[26:27], v[18:19], v[144:145], v[26:27]
	v_lshlrev_b32_e32 v18, 16, v29
	v_and_b32_e32 v19, 0xffff0000, v29
	v_pk_fma_f32 v[22:23], v[22:23], v[148:149], v[30:31]
	v_pk_fma_f32 v[28:29], v[20:21], v[142:143], v[18:19]
	v_cvt_pk_bf16_f32 v18, v22, v23
	v_cvt_pk_bf16_f32 v19, v24, v25
	v_cvt_pk_bf16_f32 v20, v26, v27
	v_cvt_pk_bf16_f32 v21, v28, v29
	global_store_dwordx4 v[38:39], v[18:21], off offset:2304
	s_nop 1
	v_lshl_add_u64 v[18:19], v[158:159], 0, s[6:7]
	global_load_dwordx4 v[20:23], v[18:19], off offset:2048
	s_waitcnt vmcnt(0)
	v_lshlrev_b32_e32 v24, 16, v20
	v_and_b32_e32 v25, 0xffff0000, v20
	v_lshlrev_b32_e32 v20, 16, v21
	v_and_b32_e32 v21, 0xffff0000, v21
	v_pk_fma_f32 v[16:17], v[16:17], v[152:153], v[20:21]
	v_lshlrev_b32_e32 v20, 16, v22
	v_and_b32_e32 v21, 0xffff0000, v22
	v_pk_fma_f32 v[20:21], v[10:11], v[154:155], v[20:21]
	v_lshlrev_b32_e32 v10, 16, v23
	v_and_b32_e32 v11, 0xffff0000, v23
	v_pk_fma_f32 v[14:15], v[14:15], v[156:157], v[24:25]
	v_pk_fma_f32 v[22:23], v[12:13], v[150:151], v[10:11]
	v_cvt_pk_bf16_f32 v10, v14, v15
	v_cvt_pk_bf16_f32 v11, v16, v17
	v_cvt_pk_bf16_f32 v12, v20, v21
	v_cvt_pk_bf16_f32 v13, v22, v23
	global_store_dwordx4 v[18:19], v[10:13], off offset:2048
	global_load_dwordx4 v[10:13], v[18:19], off offset:2304
	s_waitcnt vmcnt(0)
	v_lshlrev_b32_e32 v14, 16, v10
	v_and_b32_e32 v15, 0xffff0000, v10
	v_lshlrev_b32_e32 v10, 16, v11
	v_and_b32_e32 v11, 0xffff0000, v11
	v_pk_fma_f32 v[8:9], v[8:9], v[146:147], v[10:11]
	v_lshlrev_b32_e32 v10, 16, v12
	v_and_b32_e32 v11, 0xffff0000, v12
	v_pk_fma_f32 v[10:11], v[2:3], v[144:145], v[10:11]
	v_lshlrev_b32_e32 v2, 16, v13
	v_and_b32_e32 v3, 0xffff0000, v13
	v_pk_fma_f32 v[6:7], v[6:7], v[148:149], v[14:15]
	v_pk_fma_f32 v[12:13], v[4:5], v[142:143], v[2:3]
	v_cvt_pk_bf16_f32 v2, v6, v7
	v_cvt_pk_bf16_f32 v3, v8, v9
	v_cvt_pk_bf16_f32 v4, v10, v11
	v_cvt_pk_bf16_f32 v5, v12, v13
	global_store_dwordx4 v[18:19], v[2:5], off offset:2304
	s_cbranch_vccz .LBB0_1399
	s_waitcnt vmcnt(0)
	s_cmpk_gt_u32 s22, 0xff
	s_cbranch_scc1 .LBB0_1412
	s_barrier
